# v2 + residual/gate/ssq epilogue load hoists in PA5,PB5,attention,PB1,PB2b (de-serialised epilogue waits)
# speedup vs baseline: 1.0100x; 1.0100x over previous
.LBB0_408:
	v_lshl_add_u32 v156, s79, 8, v133
	v_lshl_or_b32 v154, s78, 8, v159
	v_ashrrev_i32_e32 v157, 31, v156
	v_ashrrev_i32_e32 v155, 31, v154
	v_lshlrev_b64 v[162:163], 11, v[156:157]
	v_lshl_add_u64 v[162:163], v[162:163], 0, v[154:155]
	v_lshlrev_b64 v[162:163], 1, v[162:163]
	v_lshl_add_u64 v[174:175], s[54:55], 0, v[162:163]
	v_mov_b32_e32 v252, v162
	global_load_dwordx4 v[170:173], v252, s[54:55] nt
	global_load_dwordx4 v[178:181], v252, s[54:55] offset:256 nt
	v_add_u32_e32 v253, 0x10000, v252
	global_load_dwordx4 v[182:185], v253, s[54:55] nt
	global_load_dwordx4 v[186:189], v253, s[54:55] offset:256 nt
	v_add_u32_e32 v253, 0x20000, v252
	global_load_dwordx4 v[194:197], v253, s[54:55] nt
	global_load_dwordx4 v[198:201], v253, s[54:55] offset:256 nt
	v_add_u32_e32 v253, 0x30000, v252
	global_load_dwordx4 v[202:205], v253, s[54:55] nt
	global_load_dwordx4 v[206:209], v253, s[54:55] offset:256 nt
	v_add_u32_e32 v253, 0x80000, v252
	global_load_dwordx4 v[210:213], v253, s[54:55] nt
	global_load_dwordx4 v[214:217], v253, s[54:55] offset:256 nt
	v_add_u32_e32 v253, 0x90000, v252
	global_load_dwordx4 v[218:221], v253, s[54:55] nt
	global_load_dwordx4 v[222:225], v253, s[54:55] offset:256 nt
	v_add_u32_e32 v253, 0xa0000, v252
	global_load_dwordx4 v[226:229], v253, s[54:55] nt
	global_load_dwordx4 v[230:233], v253, s[54:55] offset:256 nt
	v_add_u32_e32 v253, 0xb0000, v252
	global_load_dwordx4 v[240:243], v253, s[54:55] nt
	global_load_dwordx4 v[244:247], v253, s[54:55] offset:256 nt
	v_lshl_add_u64 v[162:163], s[56:57], 0, v[162:163]
	s_waitcnt vmcnt(0)
	v_lshlrev_b32_e32 v176, 16, v170
	v_and_b32_e32 v177, 0xffff0000, v170
	v_lshlrev_b32_e32 v170, 16, v171
	v_and_b32_e32 v171, 0xffff0000, v171
	v_pk_add_f32 v[130:131], v[130:131], v[170:171]
	v_lshlrev_b32_e32 v170, 16, v172
	v_and_b32_e32 v171, 0xffff0000, v172
	v_pk_add_f32 v[128:129], v[128:129], v[176:177]
	v_lshlrev_b32_e32 v172, 16, v173
	v_and_b32_e32 v173, 0xffff0000, v173
	v_pk_add_f32 v[170:171], v[124:125], v[170:171]
	v_cvt_pk_bf16_f32 v124, v128, v129
	v_cvt_pk_bf16_f32 v125, v130, v131
	v_pk_add_f32 v[172:173], v[126:127], v[172:173]
	v_cvt_pk_bf16_f32 v126, v170, v171
	s_nop 0
	v_cvt_pk_bf16_f32 v127, v172, v173
	global_store_dwordx4 v[162:163], v[124:127], off
	s_nop 1
	v_mul_f32_e32 v124, v129, v129
	v_mul_f32_e32 v125, v131, v131
	v_fmac_f32_e32 v124, v128, v128
	v_fmac_f32_e32 v125, v130, v130
	v_add_f32_e32 v124, v124, v125
	v_mul_f32_e32 v125, v171, v171
	v_fmac_f32_e32 v125, v170, v170
	v_add_f32_e32 v124, v125, v124
	v_mul_f32_e32 v125, v173, v173
	v_fmac_f32_e32 v125, v172, v172
	v_add_f32_e32 v130, v125, v124
	v_mov_b64_e32 v[124:125], v[178:179]
	v_mov_b64_e32 v[126:127], v[180:181]
	v_lshlrev_b32_e32 v128, 16, v124
	v_and_b32_e32 v129, 0xffff0000, v124
	v_lshlrev_b32_e32 v124, 16, v125
	v_and_b32_e32 v125, 0xffff0000, v125
	v_pk_add_f32 v[122:123], v[122:123], v[124:125]
	v_lshlrev_b32_e32 v124, 16, v126
	v_and_b32_e32 v125, 0xffff0000, v126
	v_lshlrev_b32_e32 v126, 16, v127
	v_and_b32_e32 v127, 0xffff0000, v127
	v_pk_add_f32 v[120:121], v[120:121], v[128:129]
	v_pk_add_f32 v[126:127], v[118:119], v[126:127]
	v_pk_add_f32 v[124:125], v[116:117], v[124:125]
	v_cvt_pk_bf16_f32 v116, v120, v121
	v_cvt_pk_bf16_f32 v117, v122, v123
	s_nop 0
	v_cvt_pk_bf16_f32 v118, v124, v125
	v_cvt_pk_bf16_f32 v119, v126, v127
	global_store_dwordx4 v[162:163], v[116:119], off offset:256
	s_nop 1
	v_mul_f32_e32 v118, v121, v121
	v_mul_f32_e32 v119, v123, v123
	v_mul_f32_e32 v117, v125, v125
	v_fmac_f32_e32 v118, v120, v120
	v_fmac_f32_e32 v119, v122, v122
	v_mul_f32_e32 v116, v127, v127
	v_fmac_f32_e32 v117, v124, v124
	v_add_f32_e32 v118, v118, v119
	v_fmac_f32_e32 v116, v126, v126
	v_add_f32_e32 v117, v117, v118
	v_add_f32_e32 v116, v116, v117
	v_add_f32_e32 v116, v130, v116
	v_mov_b32_e32 v117, v116
	s_nop 1
	v_permlane16_swap_b32_e32 v116, v117
	v_add_f32_e32 v116, v116, v117
	v_mov_b32_e32 v117, v116
	s_nop 1
	v_permlane32_swap_b32_e32 v116, v117
	s_and_saveexec_b64 s[70:71], s[8:9]
	s_cbranch_execz .LBB0_410
	v_lshl_add_u64 v[118:119], v[156:157], 2, s[58:59]
	v_add_f32_e32 v116, v116, v117
	global_atomic_add_f32 v[118:119], v116, off
.LBB0_410:
	s_or_b64 exec, exec, s[70:71]
	v_or_b32_e32 v116, 16, v156
	v_ashrrev_i32_e32 v117, 31, v116
	v_lshlrev_b64 v[118:119], 11, v[116:117]
	v_lshl_add_u64 v[118:119], v[118:119], 0, v[154:155]
	v_lshlrev_b64 v[122:123], 1, v[118:119]
	v_lshl_add_u64 v[124:125], s[54:55], 0, v[122:123]
	v_mov_b64_e32 v[118:119], v[182:183]
	v_mov_b64_e32 v[120:121], v[184:185]
	v_lshl_add_u64 v[122:123], s[56:57], 0, v[122:123]
	v_lshlrev_b32_e32 v126, 16, v118
	v_and_b32_e32 v127, 0xffff0000, v118
	v_lshlrev_b32_e32 v118, 16, v119
	v_and_b32_e32 v119, 0xffff0000, v119
	v_lshlrev_b32_e32 v128, 16, v120
	v_and_b32_e32 v129, 0xffff0000, v120
	v_lshlrev_b32_e32 v120, 16, v121
	v_and_b32_e32 v121, 0xffff0000, v121
	v_pk_add_f32 v[114:115], v[114:115], v[118:119]
	v_pk_add_f32 v[112:113], v[112:113], v[126:127]
	v_pk_add_f32 v[118:119], v[110:111], v[120:121]
	v_pk_add_f32 v[120:121], v[108:109], v[128:129]
	v_cvt_pk_bf16_f32 v108, v112, v113
	v_cvt_pk_bf16_f32 v109, v114, v115
	v_mul_f32_e32 v113, v113, v113
	v_cvt_pk_bf16_f32 v110, v120, v121
	v_cvt_pk_bf16_f32 v111, v118, v119
	global_store_dwordx4 v[122:123], v[108:111], off
	s_nop 1
	v_mov_b64_e32 v[108:109], v[186:187]
	v_mov_b64_e32 v[110:111], v[188:189]
	v_mul_f32_e32 v115, v115, v115
	v_mul_f32_e32 v121, v121, v121
	v_fmac_f32_e32 v113, v112, v112
	v_fmac_f32_e32 v115, v114, v114
	v_mul_f32_e32 v119, v119, v119
	v_fmac_f32_e32 v121, v120, v120
	v_add_f32_e32 v112, v113, v115
	v_fmac_f32_e32 v119, v118, v118
	v_add_f32_e32 v112, v121, v112
	v_add_f32_e32 v118, v119, v112
	v_lshlrev_b32_e32 v112, 16, v108
	v_and_b32_e32 v113, 0xffff0000, v108
	v_lshlrev_b32_e32 v108, 16, v109
	v_and_b32_e32 v109, 0xffff0000, v109
	v_lshlrev_b32_e32 v114, 16, v110
	v_and_b32_e32 v115, 0xffff0000, v110
	v_lshlrev_b32_e32 v110, 16, v111
	v_and_b32_e32 v111, 0xffff0000, v111
	v_pk_add_f32 v[106:107], v[106:107], v[108:109]
	v_pk_add_f32 v[104:105], v[104:105], v[112:113]
	v_pk_add_f32 v[108:109], v[102:103], v[110:111]
	v_pk_add_f32 v[110:111], v[100:101], v[114:115]
	v_cvt_pk_bf16_f32 v100, v104, v105
	v_cvt_pk_bf16_f32 v101, v106, v107
	v_mul_f32_e32 v105, v105, v105
	v_mul_f32_e32 v107, v107, v107
	v_cvt_pk_bf16_f32 v102, v110, v111
	v_mul_f32_e32 v111, v111, v111
	v_fmac_f32_e32 v105, v104, v104
	v_fmac_f32_e32 v107, v106, v106
	v_cvt_pk_bf16_f32 v103, v108, v109
	v_mul_f32_e32 v109, v109, v109
	global_store_dwordx4 v[122:123], v[100:103], off offset:256
	v_fmac_f32_e32 v111, v110, v110
	v_fmac_f32_e32 v109, v108, v108
	v_add_f32_e32 v100, v105, v107
	v_add_f32_e32 v100, v111, v100
	v_add_f32_e32 v100, v109, v100
	v_add_f32_e32 v100, v118, v100
	v_mov_b32_e32 v101, v100
	s_nop 1
	v_permlane16_swap_b32_e32 v100, v101
	v_add_f32_e32 v100, v100, v101
	v_mov_b32_e32 v101, v100
	s_nop 1
	v_permlane32_swap_b32_e32 v100, v101
	s_and_saveexec_b64 s[70:71], s[8:9]
	s_cbranch_execz .LBB0_412
	v_lshl_add_u64 v[102:103], v[116:117], 2, s[58:59]
	v_add_f32_e32 v100, v100, v101
	global_atomic_add_f32 v[102:103], v100, off
.LBB0_412:
	s_or_b64 exec, exec, s[70:71]
	v_or_b32_e32 v100, 32, v156
	v_ashrrev_i32_e32 v101, 31, v100
	v_lshlrev_b64 v[102:103], 11, v[100:101]
	v_lshl_add_u64 v[102:103], v[102:103], 0, v[154:155]
	v_lshlrev_b64 v[106:107], 1, v[102:103]
	v_lshl_add_u64 v[108:109], s[54:55], 0, v[106:107]
	v_mov_b64_e32 v[102:103], v[194:195]
	v_mov_b64_e32 v[104:105], v[196:197]
	v_lshl_add_u64 v[106:107], s[56:57], 0, v[106:107]
	v_lshlrev_b32_e32 v110, 16, v102
	v_and_b32_e32 v111, 0xffff0000, v102
	v_lshlrev_b32_e32 v102, 16, v103
	v_and_b32_e32 v103, 0xffff0000, v103
	v_lshlrev_b32_e32 v112, 16, v104
	v_and_b32_e32 v113, 0xffff0000, v104
	v_lshlrev_b32_e32 v104, 16, v105
	v_and_b32_e32 v105, 0xffff0000, v105
	v_pk_add_f32 v[98:99], v[98:99], v[102:103]
	v_pk_add_f32 v[96:97], v[96:97], v[110:111]
	v_pk_add_f32 v[102:103], v[94:95], v[104:105]
	v_pk_add_f32 v[104:105], v[92:93], v[112:113]
	v_cvt_pk_bf16_f32 v92, v96, v97
	v_cvt_pk_bf16_f32 v93, v98, v99
	v_mul_f32_e32 v97, v97, v97
	v_cvt_pk_bf16_f32 v94, v104, v105
	v_cvt_pk_bf16_f32 v95, v102, v103
	global_store_dwordx4 v[106:107], v[92:95], off
	s_nop 1
	v_mov_b64_e32 v[92:93], v[198:199]
	v_mov_b64_e32 v[94:95], v[200:201]
	v_mul_f32_e32 v99, v99, v99
	v_mul_f32_e32 v105, v105, v105
	v_fmac_f32_e32 v97, v96, v96
	v_fmac_f32_e32 v99, v98, v98
	v_mul_f32_e32 v103, v103, v103
	v_fmac_f32_e32 v105, v104, v104
	v_add_f32_e32 v96, v97, v99
	v_fmac_f32_e32 v103, v102, v102
	v_add_f32_e32 v96, v105, v96
	v_add_f32_e32 v102, v103, v96
	v_lshlrev_b32_e32 v96, 16, v92
	v_and_b32_e32 v97, 0xffff0000, v92
	v_lshlrev_b32_e32 v92, 16, v93
	v_and_b32_e32 v93, 0xffff0000, v93
	v_lshlrev_b32_e32 v98, 16, v94
	v_and_b32_e32 v99, 0xffff0000, v94
	v_lshlrev_b32_e32 v94, 16, v95
	v_and_b32_e32 v95, 0xffff0000, v95
	v_pk_add_f32 v[90:91], v[90:91], v[92:93]
	v_pk_add_f32 v[88:89], v[88:89], v[96:97]
	v_pk_add_f32 v[92:93], v[86:87], v[94:95]
	v_pk_add_f32 v[94:95], v[84:85], v[98:99]
	v_cvt_pk_bf16_f32 v84, v88, v89
	v_cvt_pk_bf16_f32 v85, v90, v91
	v_mul_f32_e32 v89, v89, v89
	v_mul_f32_e32 v91, v91, v91
	v_cvt_pk_bf16_f32 v86, v94, v95
	v_mul_f32_e32 v95, v95, v95
	v_fmac_f32_e32 v89, v88, v88
	v_fmac_f32_e32 v91, v90, v90
	v_cvt_pk_bf16_f32 v87, v92, v93
	v_mul_f32_e32 v93, v93, v93
	global_store_dwordx4 v[106:107], v[84:87], off offset:256
	v_fmac_f32_e32 v95, v94, v94
	v_fmac_f32_e32 v93, v92, v92
	v_add_f32_e32 v84, v89, v91
	v_add_f32_e32 v84, v95, v84
	v_add_f32_e32 v84, v93, v84
	v_add_f32_e32 v84, v102, v84
	v_mov_b32_e32 v85, v84
	s_nop 1
	v_permlane16_swap_b32_e32 v84, v85
	v_add_f32_e32 v84, v84, v85
	v_mov_b32_e32 v85, v84
	s_nop 1
	v_permlane32_swap_b32_e32 v84, v85
	s_and_saveexec_b64 s[70:71], s[8:9]
	s_cbranch_execz .LBB0_414
	v_lshl_add_u64 v[86:87], v[100:101], 2, s[58:59]
	v_add_f32_e32 v84, v84, v85
	global_atomic_add_f32 v[86:87], v84, off
.LBB0_414:
	s_or_b64 exec, exec, s[70:71]
	v_or_b32_e32 v84, 48, v156
	v_ashrrev_i32_e32 v85, 31, v84
	v_lshlrev_b64 v[86:87], 11, v[84:85]
	v_lshl_add_u64 v[86:87], v[86:87], 0, v[154:155]
	v_lshlrev_b64 v[90:91], 1, v[86:87]
	v_lshl_add_u64 v[92:93], s[54:55], 0, v[90:91]
	v_mov_b64_e32 v[86:87], v[202:203]
	v_mov_b64_e32 v[88:89], v[204:205]
	v_lshl_add_u64 v[90:91], s[56:57], 0, v[90:91]
	v_lshlrev_b32_e32 v94, 16, v86
	v_and_b32_e32 v95, 0xffff0000, v86
	v_lshlrev_b32_e32 v86, 16, v87
	v_and_b32_e32 v87, 0xffff0000, v87
	v_lshlrev_b32_e32 v96, 16, v88
	v_and_b32_e32 v97, 0xffff0000, v88
	v_lshlrev_b32_e32 v88, 16, v89
	v_and_b32_e32 v89, 0xffff0000, v89
	v_pk_add_f32 v[82:83], v[82:83], v[86:87]
	v_pk_add_f32 v[80:81], v[80:81], v[94:95]
	v_pk_add_f32 v[86:87], v[78:79], v[88:89]
	v_pk_add_f32 v[88:89], v[76:77], v[96:97]
	v_cvt_pk_bf16_f32 v76, v80, v81
	v_cvt_pk_bf16_f32 v77, v82, v83
	v_mul_f32_e32 v81, v81, v81
	v_cvt_pk_bf16_f32 v78, v88, v89
	v_cvt_pk_bf16_f32 v79, v86, v87
	global_store_dwordx4 v[90:91], v[76:79], off
	s_nop 1
	v_mov_b64_e32 v[76:77], v[206:207]
	v_mov_b64_e32 v[78:79], v[208:209]
	v_mul_f32_e32 v83, v83, v83
	v_mul_f32_e32 v89, v89, v89
	v_fmac_f32_e32 v81, v80, v80
	v_fmac_f32_e32 v83, v82, v82
	v_mul_f32_e32 v87, v87, v87
	v_fmac_f32_e32 v89, v88, v88
	v_add_f32_e32 v80, v81, v83
	v_fmac_f32_e32 v87, v86, v86
	v_add_f32_e32 v80, v89, v80
	v_add_f32_e32 v86, v87, v80
	v_lshlrev_b32_e32 v80, 16, v76
	v_and_b32_e32 v81, 0xffff0000, v76
	v_lshlrev_b32_e32 v76, 16, v77
	v_and_b32_e32 v77, 0xffff0000, v77
	v_lshlrev_b32_e32 v82, 16, v78
	v_and_b32_e32 v83, 0xffff0000, v78
	v_lshlrev_b32_e32 v78, 16, v79
	v_and_b32_e32 v79, 0xffff0000, v79
	v_pk_add_f32 v[74:75], v[74:75], v[76:77]
	v_pk_add_f32 v[72:73], v[72:73], v[80:81]
	v_pk_add_f32 v[76:77], v[70:71], v[78:79]
	v_pk_add_f32 v[78:79], v[68:69], v[82:83]
	v_cvt_pk_bf16_f32 v68, v72, v73
	v_cvt_pk_bf16_f32 v69, v74, v75
	v_mul_f32_e32 v73, v73, v73
	v_mul_f32_e32 v75, v75, v75
	v_cvt_pk_bf16_f32 v70, v78, v79
	v_mul_f32_e32 v79, v79, v79
	v_fmac_f32_e32 v73, v72, v72
	v_fmac_f32_e32 v75, v74, v74
	v_cvt_pk_bf16_f32 v71, v76, v77
	v_mul_f32_e32 v77, v77, v77
	global_store_dwordx4 v[90:91], v[68:71], off offset:256
	v_fmac_f32_e32 v79, v78, v78
	v_fmac_f32_e32 v77, v76, v76
	v_add_f32_e32 v68, v73, v75
	v_add_f32_e32 v68, v79, v68
	v_add_f32_e32 v68, v77, v68
	v_add_f32_e32 v68, v86, v68
	v_mov_b32_e32 v69, v68
	s_nop 1
	v_permlane16_swap_b32_e32 v68, v69
	v_add_f32_e32 v68, v68, v69
	v_mov_b32_e32 v69, v68
	s_nop 1
	v_permlane32_swap_b32_e32 v68, v69
	s_and_saveexec_b64 s[70:71], s[8:9]
	s_cbranch_execz .LBB0_416
	v_lshl_add_u64 v[70:71], v[84:85], 2, s[58:59]
	v_add_f32_e32 v68, v68, v69
	global_atomic_add_f32 v[70:71], v68, off
.LBB0_416:
	s_or_b64 exec, exec, s[70:71]
	v_add_u32_e32 v68, 0x80, v156
	v_ashrrev_i32_e32 v69, 31, v68
	v_lshlrev_b64 v[70:71], 11, v[68:69]
	v_lshl_add_u64 v[70:71], v[70:71], 0, v[154:155]
	v_lshlrev_b64 v[74:75], 1, v[70:71]
	v_lshl_add_u64 v[76:77], s[54:55], 0, v[74:75]
	v_mov_b64_e32 v[70:71], v[210:211]
	v_mov_b64_e32 v[72:73], v[212:213]
	v_lshl_add_u64 v[74:75], s[56:57], 0, v[74:75]
	v_lshlrev_b32_e32 v78, 16, v70
	v_and_b32_e32 v79, 0xffff0000, v70
	v_lshlrev_b32_e32 v70, 16, v71
	v_and_b32_e32 v71, 0xffff0000, v71
	v_lshlrev_b32_e32 v80, 16, v72
	v_and_b32_e32 v81, 0xffff0000, v72
	v_lshlrev_b32_e32 v72, 16, v73
	v_and_b32_e32 v73, 0xffff0000, v73
	v_pk_add_f32 v[66:67], v[66:67], v[70:71]
	v_pk_add_f32 v[64:65], v[64:65], v[78:79]
	v_pk_add_f32 v[70:71], v[62:63], v[72:73]
	v_pk_add_f32 v[72:73], v[60:61], v[80:81]
	v_cvt_pk_bf16_f32 v60, v64, v65
	v_cvt_pk_bf16_f32 v61, v66, v67
	v_mul_f32_e32 v65, v65, v65
	v_cvt_pk_bf16_f32 v62, v72, v73
	v_cvt_pk_bf16_f32 v63, v70, v71
	global_store_dwordx4 v[74:75], v[60:63], off
	s_nop 1
	v_mov_b64_e32 v[60:61], v[214:215]
	v_mov_b64_e32 v[62:63], v[216:217]
	v_mul_f32_e32 v67, v67, v67
	v_mul_f32_e32 v73, v73, v73
	v_fmac_f32_e32 v65, v64, v64
	v_fmac_f32_e32 v67, v66, v66
	v_mul_f32_e32 v71, v71, v71
	v_fmac_f32_e32 v73, v72, v72
	v_add_f32_e32 v64, v65, v67
	v_fmac_f32_e32 v71, v70, v70
	v_add_f32_e32 v64, v73, v64
	v_add_f32_e32 v70, v71, v64
	v_lshlrev_b32_e32 v64, 16, v60
	v_and_b32_e32 v65, 0xffff0000, v60
	v_lshlrev_b32_e32 v60, 16, v61
	v_and_b32_e32 v61, 0xffff0000, v61
	v_lshlrev_b32_e32 v66, 16, v62
	v_and_b32_e32 v67, 0xffff0000, v62
	v_lshlrev_b32_e32 v62, 16, v63
	v_and_b32_e32 v63, 0xffff0000, v63
	v_pk_add_f32 v[58:59], v[58:59], v[60:61]
	v_pk_add_f32 v[56:57], v[56:57], v[64:65]
	v_pk_add_f32 v[60:61], v[54:55], v[62:63]
	v_pk_add_f32 v[62:63], v[52:53], v[66:67]
	v_cvt_pk_bf16_f32 v52, v56, v57
	v_cvt_pk_bf16_f32 v53, v58, v59
	v_mul_f32_e32 v57, v57, v57
	v_mul_f32_e32 v59, v59, v59
	v_cvt_pk_bf16_f32 v54, v62, v63
	v_mul_f32_e32 v63, v63, v63
	v_fmac_f32_e32 v57, v56, v56
	v_fmac_f32_e32 v59, v58, v58
	v_cvt_pk_bf16_f32 v55, v60, v61
	v_mul_f32_e32 v61, v61, v61
	global_store_dwordx4 v[74:75], v[52:55], off offset:256
	v_fmac_f32_e32 v63, v62, v62
	v_fmac_f32_e32 v61, v60, v60
	v_add_f32_e32 v52, v57, v59
	v_add_f32_e32 v52, v63, v52
	v_add_f32_e32 v52, v61, v52
	v_add_f32_e32 v52, v70, v52
	v_mov_b32_e32 v53, v52
	s_nop 1
	v_permlane16_swap_b32_e32 v52, v53
	v_add_f32_e32 v52, v52, v53
	v_mov_b32_e32 v53, v52
	s_nop 1
	v_permlane32_swap_b32_e32 v52, v53
	s_and_saveexec_b64 s[70:71], s[8:9]
	s_cbranch_execz .LBB0_418
	v_lshl_add_u64 v[54:55], v[68:69], 2, s[58:59]
	v_add_f32_e32 v52, v52, v53
	global_atomic_add_f32 v[54:55], v52, off
.LBB0_418:
	s_or_b64 exec, exec, s[70:71]
	v_add_u32_e32 v52, 0x90, v156
	v_ashrrev_i32_e32 v53, 31, v52
	v_lshlrev_b64 v[54:55], 11, v[52:53]
	v_lshl_add_u64 v[54:55], v[54:55], 0, v[154:155]
	v_lshlrev_b64 v[58:59], 1, v[54:55]
	v_lshl_add_u64 v[60:61], s[54:55], 0, v[58:59]
	v_mov_b64_e32 v[54:55], v[218:219]
	v_mov_b64_e32 v[56:57], v[220:221]
	v_lshl_add_u64 v[58:59], s[56:57], 0, v[58:59]
	v_lshlrev_b32_e32 v62, 16, v54
	v_and_b32_e32 v63, 0xffff0000, v54
	v_lshlrev_b32_e32 v54, 16, v55
	v_and_b32_e32 v55, 0xffff0000, v55
	v_lshlrev_b32_e32 v64, 16, v56
	v_and_b32_e32 v65, 0xffff0000, v56
	v_lshlrev_b32_e32 v56, 16, v57
	v_and_b32_e32 v57, 0xffff0000, v57
	v_pk_add_f32 v[50:51], v[50:51], v[54:55]
	v_pk_add_f32 v[48:49], v[48:49], v[62:63]
	v_pk_add_f32 v[54:55], v[46:47], v[56:57]
	v_pk_add_f32 v[56:57], v[44:45], v[64:65]
	v_cvt_pk_bf16_f32 v44, v48, v49
	v_cvt_pk_bf16_f32 v45, v50, v51
	v_mul_f32_e32 v49, v49, v49
	v_cvt_pk_bf16_f32 v46, v56, v57
	v_cvt_pk_bf16_f32 v47, v54, v55
	global_store_dwordx4 v[58:59], v[44:47], off
	s_nop 1
	v_mov_b64_e32 v[44:45], v[222:223]
	v_mov_b64_e32 v[46:47], v[224:225]
	v_mul_f32_e32 v51, v51, v51
	v_mul_f32_e32 v57, v57, v57
	v_fmac_f32_e32 v49, v48, v48
	v_fmac_f32_e32 v51, v50, v50
	v_mul_f32_e32 v55, v55, v55
	v_fmac_f32_e32 v57, v56, v56
	v_add_f32_e32 v48, v49, v51
	v_fmac_f32_e32 v55, v54, v54
	v_add_f32_e32 v48, v57, v48
	v_add_f32_e32 v54, v55, v48
	v_lshlrev_b32_e32 v48, 16, v44
	v_and_b32_e32 v49, 0xffff0000, v44
	v_lshlrev_b32_e32 v44, 16, v45
	v_and_b32_e32 v45, 0xffff0000, v45
	v_lshlrev_b32_e32 v50, 16, v46
	v_and_b32_e32 v51, 0xffff0000, v46
	v_lshlrev_b32_e32 v46, 16, v47
	v_and_b32_e32 v47, 0xffff0000, v47
	v_pk_add_f32 v[42:43], v[42:43], v[44:45]
	v_pk_add_f32 v[40:41], v[40:41], v[48:49]
	v_pk_add_f32 v[44:45], v[38:39], v[46:47]
	v_pk_add_f32 v[46:47], v[36:37], v[50:51]
	v_cvt_pk_bf16_f32 v36, v40, v41
	v_cvt_pk_bf16_f32 v37, v42, v43
	v_mul_f32_e32 v41, v41, v41
	v_mul_f32_e32 v43, v43, v43
	v_cvt_pk_bf16_f32 v38, v46, v47
	v_mul_f32_e32 v47, v47, v47
	v_fmac_f32_e32 v41, v40, v40
	v_fmac_f32_e32 v43, v42, v42
	v_cvt_pk_bf16_f32 v39, v44, v45
	v_mul_f32_e32 v45, v45, v45
	global_store_dwordx4 v[58:59], v[36:39], off offset:256
	v_fmac_f32_e32 v47, v46, v46
	v_fmac_f32_e32 v45, v44, v44
	v_add_f32_e32 v36, v41, v43
	v_add_f32_e32 v36, v47, v36
	v_add_f32_e32 v36, v45, v36
	v_add_f32_e32 v36, v54, v36
	v_mov_b32_e32 v37, v36
	s_nop 1
	v_permlane16_swap_b32_e32 v36, v37
	v_add_f32_e32 v36, v36, v37
	v_mov_b32_e32 v37, v36
	s_nop 1
	v_permlane32_swap_b32_e32 v36, v37
	s_and_saveexec_b64 s[70:71], s[8:9]
	s_cbranch_execz .LBB0_420
	v_lshl_add_u64 v[38:39], v[52:53], 2, s[58:59]
	v_add_f32_e32 v36, v36, v37
	global_atomic_add_f32 v[38:39], v36, off
.LBB0_420:
	s_or_b64 exec, exec, s[70:71]
	v_add_u32_e32 v36, 0xa0, v156
	v_ashrrev_i32_e32 v37, 31, v36
	v_lshlrev_b64 v[38:39], 11, v[36:37]
	v_lshl_add_u64 v[38:39], v[38:39], 0, v[154:155]
	v_lshlrev_b64 v[42:43], 1, v[38:39]
	v_lshl_add_u64 v[44:45], s[54:55], 0, v[42:43]
	v_mov_b64_e32 v[38:39], v[226:227]
	v_mov_b64_e32 v[40:41], v[228:229]
	v_lshl_add_u64 v[42:43], s[56:57], 0, v[42:43]
	v_lshlrev_b32_e32 v46, 16, v38
	v_and_b32_e32 v47, 0xffff0000, v38
	v_lshlrev_b32_e32 v38, 16, v39
	v_and_b32_e32 v39, 0xffff0000, v39
	v_lshlrev_b32_e32 v48, 16, v40
	v_and_b32_e32 v49, 0xffff0000, v40
	v_lshlrev_b32_e32 v40, 16, v41
	v_and_b32_e32 v41, 0xffff0000, v41
	v_pk_add_f32 v[34:35], v[34:35], v[38:39]
	v_pk_add_f32 v[32:33], v[32:33], v[46:47]
	v_pk_add_f32 v[38:39], v[30:31], v[40:41]
	v_pk_add_f32 v[40:41], v[28:29], v[48:49]
	v_cvt_pk_bf16_f32 v28, v32, v33
	v_cvt_pk_bf16_f32 v29, v34, v35
	v_mul_f32_e32 v33, v33, v33
	v_cvt_pk_bf16_f32 v30, v40, v41
	v_cvt_pk_bf16_f32 v31, v38, v39
	global_store_dwordx4 v[42:43], v[28:31], off
	s_nop 1
	v_mov_b64_e32 v[28:29], v[230:231]
	v_mov_b64_e32 v[30:31], v[232:233]
	v_mul_f32_e32 v35, v35, v35
	v_mul_f32_e32 v41, v41, v41
	v_fmac_f32_e32 v33, v32, v32
	v_fmac_f32_e32 v35, v34, v34
	v_mul_f32_e32 v39, v39, v39
	v_fmac_f32_e32 v41, v40, v40
	v_add_f32_e32 v32, v33, v35
	v_fmac_f32_e32 v39, v38, v38
	v_add_f32_e32 v32, v41, v32
	v_add_f32_e32 v38, v39, v32
	v_lshlrev_b32_e32 v32, 16, v28
	v_and_b32_e32 v33, 0xffff0000, v28
	v_lshlrev_b32_e32 v28, 16, v29
	v_and_b32_e32 v29, 0xffff0000, v29
	v_lshlrev_b32_e32 v34, 16, v30
	v_and_b32_e32 v35, 0xffff0000, v30
	v_lshlrev_b32_e32 v30, 16, v31
	v_and_b32_e32 v31, 0xffff0000, v31
	v_pk_add_f32 v[26:27], v[26:27], v[28:29]
	v_pk_add_f32 v[24:25], v[24:25], v[32:33]
	v_pk_add_f32 v[28:29], v[22:23], v[30:31]
	v_pk_add_f32 v[30:31], v[20:21], v[34:35]
	v_cvt_pk_bf16_f32 v20, v24, v25
	v_cvt_pk_bf16_f32 v21, v26, v27
	v_mul_f32_e32 v25, v25, v25
	v_mul_f32_e32 v27, v27, v27
	v_cvt_pk_bf16_f32 v22, v30, v31
	v_mul_f32_e32 v31, v31, v31
	v_fmac_f32_e32 v25, v24, v24
	v_fmac_f32_e32 v27, v26, v26
	v_cvt_pk_bf16_f32 v23, v28, v29
	v_mul_f32_e32 v29, v29, v29
	global_store_dwordx4 v[42:43], v[20:23], off offset:256
	v_fmac_f32_e32 v31, v30, v30
	v_fmac_f32_e32 v29, v28, v28
	v_add_f32_e32 v20, v25, v27
	v_add_f32_e32 v20, v31, v20
	v_add_f32_e32 v20, v29, v20
	v_add_f32_e32 v20, v38, v20
	v_mov_b32_e32 v21, v20
	s_nop 1
	v_permlane16_swap_b32_e32 v20, v21
	v_add_f32_e32 v20, v20, v21
	v_mov_b32_e32 v21, v20
	s_nop 1
	v_permlane32_swap_b32_e32 v20, v21
	s_and_saveexec_b64 s[70:71], s[8:9]
	s_cbranch_execz .LBB0_422
	v_lshl_add_u64 v[22:23], v[36:37], 2, s[58:59]
	v_add_f32_e32 v20, v20, v21
	global_atomic_add_f32 v[22:23], v20, off
.LBB0_422:
	s_or_b64 exec, exec, s[70:71]
	v_add_u32_e32 v20, 0xb0, v156
	v_ashrrev_i32_e32 v21, 31, v20
	v_lshlrev_b64 v[22:23], 11, v[20:21]
	v_lshl_add_u64 v[22:23], v[22:23], 0, v[154:155]
	v_lshlrev_b64 v[26:27], 1, v[22:23]
	v_lshl_add_u64 v[28:29], s[54:55], 0, v[26:27]
	v_mov_b64_e32 v[22:23], v[240:241]
	v_mov_b64_e32 v[24:25], v[242:243]
	v_lshl_add_u64 v[26:27], s[56:57], 0, v[26:27]
	v_lshlrev_b32_e32 v30, 16, v22
	v_and_b32_e32 v31, 0xffff0000, v22
	v_lshlrev_b32_e32 v22, 16, v23
	v_and_b32_e32 v23, 0xffff0000, v23
	v_lshlrev_b32_e32 v32, 16, v24
	v_and_b32_e32 v33, 0xffff0000, v24
	v_lshlrev_b32_e32 v24, 16, v25
	v_and_b32_e32 v25, 0xffff0000, v25
	v_pk_add_f32 v[18:19], v[18:19], v[22:23]
	v_pk_add_f32 v[16:17], v[16:17], v[30:31]
	v_pk_add_f32 v[22:23], v[14:15], v[24:25]
	v_pk_add_f32 v[24:25], v[12:13], v[32:33]
	v_cvt_pk_bf16_f32 v12, v16, v17
	v_cvt_pk_bf16_f32 v13, v18, v19
	v_mul_f32_e32 v17, v17, v17
	v_cvt_pk_bf16_f32 v14, v24, v25
	v_cvt_pk_bf16_f32 v15, v22, v23
	global_store_dwordx4 v[26:27], v[12:15], off
	s_nop 1
	v_mov_b64_e32 v[12:13], v[244:245]
	v_mov_b64_e32 v[14:15], v[246:247]
	v_mul_f32_e32 v19, v19, v19
	v_mul_f32_e32 v25, v25, v25
	v_fmac_f32_e32 v17, v16, v16
	v_fmac_f32_e32 v19, v18, v18
	v_mul_f32_e32 v23, v23, v23
	v_fmac_f32_e32 v25, v24, v24
	v_add_f32_e32 v16, v17, v19
	v_fmac_f32_e32 v23, v22, v22
	v_add_f32_e32 v16, v25, v16
	v_add_f32_e32 v22, v23, v16
	v_lshlrev_b32_e32 v16, 16, v12
	v_and_b32_e32 v17, 0xffff0000, v12
	v_lshlrev_b32_e32 v12, 16, v13
	v_and_b32_e32 v13, 0xffff0000, v13
	v_lshlrev_b32_e32 v18, 16, v14
	v_and_b32_e32 v19, 0xffff0000, v14
	v_lshlrev_b32_e32 v14, 16, v15
	v_and_b32_e32 v15, 0xffff0000, v15
	v_pk_add_f32 v[10:11], v[10:11], v[12:13]
	v_pk_add_f32 v[8:9], v[8:9], v[16:17]
	v_pk_add_f32 v[12:13], v[6:7], v[14:15]
	v_pk_add_f32 v[14:15], v[4:5], v[18:19]
	v_cvt_pk_bf16_f32 v4, v8, v9
	v_cvt_pk_bf16_f32 v5, v10, v11
	v_mul_f32_e32 v9, v9, v9
	v_mul_f32_e32 v11, v11, v11
	v_cvt_pk_bf16_f32 v6, v14, v15
	v_mul_f32_e32 v15, v15, v15
	v_fmac_f32_e32 v9, v8, v8
	v_fmac_f32_e32 v11, v10, v10
	v_cvt_pk_bf16_f32 v7, v12, v13
	v_mul_f32_e32 v13, v13, v13
	global_store_dwordx4 v[26:27], v[4:7], off offset:256
	v_fmac_f32_e32 v15, v14, v14
	v_fmac_f32_e32 v13, v12, v12
	v_add_f32_e32 v4, v9, v11
	v_add_f32_e32 v4, v15, v4
	v_add_f32_e32 v4, v13, v4
	v_add_f32_e32 v4, v22, v4
	v_mov_b32_e32 v5, v4
	s_nop 1
	v_permlane16_swap_b32_e32 v4, v5
	v_add_f32_e32 v4, v4, v5
	v_mov_b32_e32 v5, v4
	s_nop 1
	v_permlane32_swap_b32_e32 v4, v5
	s_and_saveexec_b64 s[70:71], s[8:9]
	s_cbranch_execz .LBB0_424
	v_lshl_add_u64 v[6:7], v[20:21], 2, s[58:59]
	v_add_f32_e32 v4, v4, v5
	global_atomic_add_f32 v[6:7], v4, off

.LBB0_504:
	v_lshl_add_u32 v144, s82, 8, v154
	v_ashrrev_i32_e32 v145, 31, v144
	v_lshl_add_u64 v[146:147], v[144:145], 2, s[24:25]
	global_load_dword v240, v[146:147], off
	global_load_dword v241, v[146:147], off offset:64
	global_load_dword v242, v[146:147], off offset:128
	global_load_dword v243, v[146:147], off offset:192
	global_load_dword v244, v[146:147], off offset:512
	global_load_dword v245, v[146:147], off offset:576
	global_load_dword v246, v[146:147], off offset:640
	global_load_dword v247, v[146:147], off offset:704
	v_lshl_add_u32 v176, s2, 8, v157
	s_waitcnt vmcnt(0)
	v_fmamk_f32 v146, v240, 0x3a000000, v197
	v_cmp_gt_f32_e32 vcc, s36, v146
	v_mul_f32_e32 v147, 0x4f800000, v146
	s_nop 0
	v_cndmask_b32_e32 v146, v146, v147, vcc
	v_sqrt_f32_e32 v147, v146
	s_nop 0
	v_add_u32_e32 v148, -1, v147
	v_fma_f32 v149, -v148, v147, v146
	v_cmp_ge_f32_e64 s[10:11], 0, v149
	v_add_u32_e32 v149, 1, v147
	s_nop 0
	v_cndmask_b32_e64 v148, v147, v148, s[10:11]
	v_fma_f32 v147, -v149, v147, v146
	v_cmp_lt_f32_e64 s[10:11], 0, v147
	s_nop 1
	v_cndmask_b32_e64 v147, v148, v149, s[10:11]
	v_mul_f32_e32 v148, 0x37800000, v147
	v_cndmask_b32_e32 v147, v147, v148, vcc
	v_cmp_class_f32_e32 vcc, v146, v198
	s_nop 1
	v_cndmask_b32_e32 v146, v147, v146, vcc
	v_div_scale_f32 v147, s[2:3], v146, v146, 1.0
	v_rcp_f32_e32 v148, v147
	s_nop 0
	v_fma_f32 v149, -v147, v148, 1.0
	v_fmac_f32_e32 v148, v149, v148
	v_div_scale_f32 v149, vcc, 1.0, v146, 1.0
	v_mul_f32_e32 v150, v149, v148
	v_fma_f32 v151, -v147, v150, v149
	v_fmac_f32_e32 v150, v151, v148
	v_fma_f32 v147, -v147, v150, v149
	v_div_fmas_f32 v147, v147, v148, v150
	v_div_fixup_f32 v146, v147, v146, 1.0
	v_pk_mul_f32 v[124:125], v[124:125], v[146:147] op_sel_hi:[1,0]
	v_lshlrev_b64 v[148:149], 12, v[144:145]
	v_mul_f32_e32 v145, 0xbfb8aa3b, v124
	v_exp_f32_e32 v145, v145
	v_pk_mul_f32 v[126:127], v[126:127], v[146:147] op_sel_hi:[1,0]
	v_pk_mul_f32 v[120:121], v[120:121], v[146:147] op_sel_hi:[1,0]
	v_pk_mul_f32 v[122:123], v[122:123], v[146:147] op_sel_hi:[1,0]
	v_add_f32_e32 v145, 1.0, v145
	v_rcp_f32_e32 v145, v145
	s_nop 0
	v_mul_f32_e32 v124, v124, v145
	v_mul_f32_e32 v145, 0xbfb8aa3b, v125
	v_exp_f32_e32 v145, v145
	s_nop 0
	v_add_f32_e32 v145, 1.0, v145
	v_rcp_f32_e32 v145, v145
	s_nop 0
	v_mul_f32_e32 v125, v125, v145
	v_mul_f32_e32 v145, 0xbfb8aa3b, v126
	v_exp_f32_e32 v145, v145
	s_nop 0
	v_add_f32_e32 v145, 1.0, v145
	v_rcp_f32_e32 v145, v145
	s_nop 0
	v_mul_f32_e32 v126, v126, v145
	v_mul_f32_e32 v145, 0xbfb8aa3b, v127
	v_exp_f32_e32 v145, v145
	s_nop 0
	v_add_f32_e32 v145, 1.0, v145
	v_rcp_f32_e32 v145, v145
	s_nop 0
	v_mul_f32_e32 v127, v127, v145
	v_mul_f32_e32 v145, 0xbfb8aa3b, v120
	v_exp_f32_e32 v145, v145
	s_nop 0
	v_add_f32_e32 v145, 1.0, v145
	v_rcp_f32_e32 v145, v145
	s_nop 0
	v_mul_f32_e32 v145, v120, v145
	v_mul_f32_e32 v120, 0xbfb8aa3b, v121
	v_exp_f32_e32 v120, v120
	s_nop 0
	v_add_f32_e32 v120, 1.0, v120
	v_rcp_f32_e32 v120, v120
	s_nop 0
	v_mul_f32_e32 v147, v121, v120
	v_mul_f32_e32 v120, 0xbfb8aa3b, v122
	v_exp_f32_e32 v120, v120
	v_pk_mul_f32 v[116:117], v[116:117], v[146:147] op_sel_hi:[1,0]
	v_pk_mul_f32 v[118:119], v[118:119], v[146:147] op_sel_hi:[1,0]
	v_pk_mul_f32 v[112:113], v[112:113], v[146:147] op_sel_hi:[1,0]
	v_add_f32_e32 v120, 1.0, v120
	v_rcp_f32_e32 v120, v120
	v_pk_mul_f32 v[114:115], v[114:115], v[146:147] op_sel_hi:[1,0]
	v_mul_f32_e32 v150, v122, v120
	v_mul_f32_e32 v120, 0xbfb8aa3b, v123
	v_exp_f32_e32 v120, v120
	s_nop 0
	v_add_f32_e32 v120, 1.0, v120
	v_rcp_f32_e32 v120, v120
	s_nop 0
	v_mul_f32_e32 v123, v123, v120
	v_cvt_pk_bf16_f32 v120, v124, v125
	v_cvt_pk_bf16_f32 v121, v126, v127
	v_lshl_add_u64 v[126:127], s[22:23], 0, v[148:149]
	v_lshlrev_b64 v[124:125], 1, v[176:177]
	v_lshl_add_u64 v[126:127], v[126:127], 0, v[124:125]
	v_cvt_pk_bf16_f32 v122, v145, v147
	v_cvt_pk_bf16_f32 v123, v150, v123
	global_store_dwordx4 v[126:127], v[120:123], off
	s_nop 1
	v_mul_f32_e32 v120, 0xbfb8aa3b, v116
	v_exp_f32_e32 v120, v120
	s_nop 0
	v_add_f32_e32 v120, 1.0, v120
	v_rcp_f32_e32 v120, v120
	s_nop 0
	v_mul_f32_e32 v116, v116, v120
	v_mul_f32_e32 v120, 0xbfb8aa3b, v117
	v_exp_f32_e32 v120, v120
	s_nop 0
	v_add_f32_e32 v120, 1.0, v120
	v_rcp_f32_e32 v120, v120
	s_nop 0
	v_mul_f32_e32 v117, v117, v120
	v_mul_f32_e32 v120, 0xbfb8aa3b, v118
	v_exp_f32_e32 v120, v120
	s_nop 0
	v_add_f32_e32 v120, 1.0, v120
	v_rcp_f32_e32 v120, v120
	s_nop 0
	v_mul_f32_e32 v118, v118, v120
	v_mul_f32_e32 v120, 0xbfb8aa3b, v119
	v_exp_f32_e32 v120, v120
	s_nop 0
	v_add_f32_e32 v120, 1.0, v120
	v_rcp_f32_e32 v120, v120
	s_nop 0
	v_mul_f32_e32 v119, v119, v120
	v_mul_f32_e32 v120, 0xbfb8aa3b, v112
	v_exp_f32_e32 v120, v120
	s_nop 0
	v_add_f32_e32 v120, 1.0, v120
	v_rcp_f32_e32 v120, v120
	s_nop 0
	v_mul_f32_e32 v120, v112, v120
	v_mul_f32_e32 v112, 0xbfb8aa3b, v113
	v_exp_f32_e32 v112, v112
	s_nop 0
	v_add_f32_e32 v112, 1.0, v112
	v_rcp_f32_e32 v112, v112
	s_nop 0
	v_mul_f32_e32 v121, v113, v112
	v_mul_f32_e32 v112, 0xbfb8aa3b, v114
	v_exp_f32_e32 v112, v112
	s_nop 0
	v_add_f32_e32 v112, 1.0, v112
	v_rcp_f32_e32 v112, v112
	s_nop 0
	v_mul_f32_e32 v122, v114, v112
	v_mul_f32_e32 v112, 0xbfb8aa3b, v115
	v_exp_f32_e32 v112, v112
	s_nop 0
	v_add_f32_e32 v112, 1.0, v112
	v_rcp_f32_e32 v112, v112
	s_nop 0
	v_mul_f32_e32 v115, v115, v112
	v_cvt_pk_bf16_f32 v112, v116, v117
	v_cvt_pk_bf16_f32 v113, v118, v119
	v_cvt_pk_bf16_f32 v114, v120, v121
	v_cvt_pk_bf16_f32 v115, v122, v115
	global_store_dwordx4 v[126:127], v[112:115], off offset:256
	s_nop 1
	v_or_b32_e32 v114, 16, v144
	v_ashrrev_i32_e32 v115, 31, v114
	v_lshl_add_u64 v[112:113], v[114:115], 2, s[24:25]
	v_lshlrev_b64 v[114:115], 12, v[114:115]
	v_fmamk_f32 v112, v241, 0x3a000000, v197
	v_cmp_gt_f32_e32 vcc, s36, v112
	v_mul_f32_e32 v113, 0x4f800000, v112
	s_nop 0
	v_cndmask_b32_e32 v112, v112, v113, vcc
	v_sqrt_f32_e32 v113, v112
	s_nop 0
	v_add_u32_e32 v116, -1, v113
	v_fma_f32 v117, -v116, v113, v112
	v_cmp_ge_f32_e64 s[10:11], 0, v117
	v_add_u32_e32 v117, 1, v113
	s_nop 0
	v_cndmask_b32_e64 v116, v113, v116, s[10:11]
	v_fma_f32 v113, -v117, v113, v112
	v_cmp_lt_f32_e64 s[10:11], 0, v113
	s_nop 1
	v_cndmask_b32_e64 v113, v116, v117, s[10:11]
	v_mul_f32_e32 v116, 0x37800000, v113
	v_cndmask_b32_e32 v113, v113, v116, vcc
	v_cmp_class_f32_e32 vcc, v112, v198
	s_nop 1
	v_cndmask_b32_e32 v112, v113, v112, vcc
	v_div_scale_f32 v113, s[2:3], v112, v112, 1.0
	v_rcp_f32_e32 v116, v113
	s_nop 0
	v_fma_f32 v117, -v113, v116, 1.0
	v_fmac_f32_e32 v116, v117, v116
	v_div_scale_f32 v117, vcc, 1.0, v112, 1.0
	v_mul_f32_e32 v118, v117, v116
	v_fma_f32 v119, -v113, v118, v117
	v_fmac_f32_e32 v118, v119, v116
	v_fma_f32 v113, -v113, v118, v117
	v_div_fmas_f32 v113, v113, v116, v118
	v_div_fixup_f32 v112, v113, v112, 1.0
	v_pk_mul_f32 v[108:109], v[108:109], v[112:113] op_sel_hi:[1,0]
	v_pk_mul_f32 v[110:111], v[110:111], v[112:113] op_sel_hi:[1,0]
	v_mul_f32_e32 v113, 0xbfb8aa3b, v108
	v_exp_f32_e32 v113, v113
	s_nop 0
	v_add_f32_e32 v113, 1.0, v113
	v_rcp_f32_e32 v113, v113
	s_nop 0
	v_mul_f32_e32 v108, v108, v113
	v_mul_f32_e32 v113, 0xbfb8aa3b, v109
	v_exp_f32_e32 v113, v113
	s_nop 0
	v_add_f32_e32 v113, 1.0, v113
	v_rcp_f32_e32 v113, v113
	s_nop 0
	v_mul_f32_e32 v109, v109, v113
	v_mul_f32_e32 v113, 0xbfb8aa3b, v110
	v_exp_f32_e32 v113, v113
	s_nop 0
	v_add_f32_e32 v113, 1.0, v113
	v_rcp_f32_e32 v113, v113
	s_nop 0
	v_mul_f32_e32 v110, v110, v113
	v_mul_f32_e32 v113, 0xbfb8aa3b, v111
	v_exp_f32_e32 v113, v113
	s_nop 0
	v_add_f32_e32 v113, 1.0, v113
	v_rcp_f32_e32 v113, v113
	s_nop 0
	v_pk_mul_f32 v[104:105], v[104:105], v[112:113] op_sel_hi:[1,0]
	v_mul_f32_e32 v111, v111, v113
	v_pk_mul_f32 v[106:107], v[106:107], v[112:113] op_sel_hi:[1,0]
	v_mul_f32_e32 v113, 0xbfb8aa3b, v104
	v_exp_f32_e32 v113, v113
	s_nop 0
	v_add_f32_e32 v113, 1.0, v113
	v_rcp_f32_e32 v113, v113
	s_nop 0
	v_mul_f32_e32 v113, v104, v113
	v_mul_f32_e32 v104, 0xbfb8aa3b, v105
	v_exp_f32_e32 v104, v104
	v_pk_mul_f32 v[100:101], v[100:101], v[112:113] op_sel_hi:[1,0]
	v_pk_mul_f32 v[102:103], v[102:103], v[112:113] op_sel_hi:[1,0]
	v_pk_mul_f32 v[96:97], v[96:97], v[112:113] op_sel_hi:[1,0]
	v_add_f32_e32 v104, 1.0, v104
	v_rcp_f32_e32 v104, v104
	v_pk_mul_f32 v[98:99], v[98:99], v[112:113] op_sel_hi:[1,0]
	v_mul_f32_e32 v116, v105, v104
	v_mul_f32_e32 v104, 0xbfb8aa3b, v106
	v_exp_f32_e32 v104, v104
	s_nop 0
	v_add_f32_e32 v104, 1.0, v104
	v_rcp_f32_e32 v104, v104
	s_nop 0
	v_mul_f32_e32 v117, v106, v104
	v_mul_f32_e32 v104, 0xbfb8aa3b, v107
	v_exp_f32_e32 v104, v104
	s_nop 0
	v_add_f32_e32 v104, 1.0, v104
	v_rcp_f32_e32 v104, v104
	s_nop 0
	v_mul_f32_e32 v107, v107, v104
	v_cvt_pk_bf16_f32 v104, v108, v109
	v_lshl_add_u64 v[108:109], s[22:23], 0, v[114:115]
	v_lshl_add_u64 v[108:109], v[108:109], 0, v[124:125]
	v_cvt_pk_bf16_f32 v105, v110, v111
	v_cvt_pk_bf16_f32 v106, v113, v116
	v_cvt_pk_bf16_f32 v107, v117, v107
	global_store_dwordx4 v[108:109], v[104:107], off
	s_nop 1
	v_mul_f32_e32 v104, 0xbfb8aa3b, v100
	v_exp_f32_e32 v104, v104
	s_nop 0
	v_add_f32_e32 v104, 1.0, v104
	v_rcp_f32_e32 v104, v104
	s_nop 0
	v_mul_f32_e32 v100, v100, v104
	v_mul_f32_e32 v104, 0xbfb8aa3b, v101
	v_exp_f32_e32 v104, v104
	s_nop 0
	v_add_f32_e32 v104, 1.0, v104
	v_rcp_f32_e32 v104, v104
	s_nop 0
	v_mul_f32_e32 v101, v101, v104
	v_mul_f32_e32 v104, 0xbfb8aa3b, v102
	v_exp_f32_e32 v104, v104
	s_nop 0
	v_add_f32_e32 v104, 1.0, v104
	v_rcp_f32_e32 v104, v104
	s_nop 0
	v_mul_f32_e32 v102, v102, v104
	v_mul_f32_e32 v104, 0xbfb8aa3b, v103
	v_exp_f32_e32 v104, v104
	s_nop 0
	v_add_f32_e32 v104, 1.0, v104
	v_rcp_f32_e32 v104, v104
	s_nop 0
	v_mul_f32_e32 v103, v103, v104
	v_mul_f32_e32 v104, 0xbfb8aa3b, v96
	v_exp_f32_e32 v104, v104
	s_nop 0
	v_add_f32_e32 v104, 1.0, v104
	v_rcp_f32_e32 v104, v104
	s_nop 0
	v_mul_f32_e32 v104, v96, v104
	v_mul_f32_e32 v96, 0xbfb8aa3b, v97
	v_exp_f32_e32 v96, v96
	s_nop 0
	v_add_f32_e32 v96, 1.0, v96
	v_rcp_f32_e32 v96, v96
	s_nop 0
	v_mul_f32_e32 v105, v97, v96
	v_mul_f32_e32 v96, 0xbfb8aa3b, v98
	v_exp_f32_e32 v96, v96
	s_nop 0
	v_add_f32_e32 v96, 1.0, v96
	v_rcp_f32_e32 v96, v96
	s_nop 0
	v_mul_f32_e32 v106, v98, v96
	v_mul_f32_e32 v96, 0xbfb8aa3b, v99
	v_exp_f32_e32 v96, v96
	s_nop 0
	v_add_f32_e32 v96, 1.0, v96
	v_rcp_f32_e32 v96, v96
	s_nop 0
	v_mul_f32_e32 v99, v99, v96
	v_cvt_pk_bf16_f32 v96, v100, v101
	v_cvt_pk_bf16_f32 v97, v102, v103
	v_cvt_pk_bf16_f32 v98, v104, v105
	v_cvt_pk_bf16_f32 v99, v106, v99
	global_store_dwordx4 v[108:109], v[96:99], off offset:256
	s_nop 1
	v_or_b32_e32 v98, 32, v144
	v_ashrrev_i32_e32 v99, 31, v98
	v_lshl_add_u64 v[96:97], v[98:99], 2, s[24:25]
	v_lshlrev_b64 v[98:99], 12, v[98:99]
	v_fmamk_f32 v96, v242, 0x3a000000, v197
	v_cmp_gt_f32_e32 vcc, s36, v96
	v_mul_f32_e32 v97, 0x4f800000, v96
	s_nop 0
	v_cndmask_b32_e32 v96, v96, v97, vcc
	v_sqrt_f32_e32 v97, v96
	s_nop 0
	v_add_u32_e32 v100, -1, v97
	v_fma_f32 v101, -v100, v97, v96
	v_cmp_ge_f32_e64 s[10:11], 0, v101
	v_add_u32_e32 v101, 1, v97
	s_nop 0
	v_cndmask_b32_e64 v100, v97, v100, s[10:11]
	v_fma_f32 v97, -v101, v97, v96
	v_cmp_lt_f32_e64 s[10:11], 0, v97
	s_nop 1
	v_cndmask_b32_e64 v97, v100, v101, s[10:11]
	v_mul_f32_e32 v100, 0x37800000, v97
	v_cndmask_b32_e32 v97, v97, v100, vcc
	v_cmp_class_f32_e32 vcc, v96, v198
	s_nop 1
	v_cndmask_b32_e32 v96, v97, v96, vcc
	v_div_scale_f32 v97, s[2:3], v96, v96, 1.0
	v_rcp_f32_e32 v100, v97
	s_nop 0
	v_fma_f32 v101, -v97, v100, 1.0
	v_fmac_f32_e32 v100, v101, v100
	v_div_scale_f32 v101, vcc, 1.0, v96, 1.0
	v_mul_f32_e32 v102, v101, v100
	v_fma_f32 v103, -v97, v102, v101
	v_fmac_f32_e32 v102, v103, v100
	v_fma_f32 v97, -v97, v102, v101
	v_div_fmas_f32 v97, v97, v100, v102
	v_div_fixup_f32 v96, v97, v96, 1.0
	v_pk_mul_f32 v[92:93], v[92:93], v[96:97] op_sel_hi:[1,0]
	v_pk_mul_f32 v[94:95], v[94:95], v[96:97] op_sel_hi:[1,0]
	v_mul_f32_e32 v97, 0xbfb8aa3b, v92
	v_exp_f32_e32 v97, v97
	s_nop 0
	v_add_f32_e32 v97, 1.0, v97
	v_rcp_f32_e32 v97, v97
	s_nop 0
	v_mul_f32_e32 v92, v92, v97
	v_mul_f32_e32 v97, 0xbfb8aa3b, v93
	v_exp_f32_e32 v97, v97
	s_nop 0
	v_add_f32_e32 v97, 1.0, v97
	v_rcp_f32_e32 v97, v97
	s_nop 0
	v_mul_f32_e32 v93, v93, v97
	v_mul_f32_e32 v97, 0xbfb8aa3b, v94
	v_exp_f32_e32 v97, v97
	s_nop 0
	v_add_f32_e32 v97, 1.0, v97
	v_rcp_f32_e32 v97, v97
	s_nop 0
	v_mul_f32_e32 v94, v94, v97
	v_mul_f32_e32 v97, 0xbfb8aa3b, v95
	v_exp_f32_e32 v97, v97
	s_nop 0
	v_add_f32_e32 v97, 1.0, v97
	v_rcp_f32_e32 v97, v97
	s_nop 0
	v_pk_mul_f32 v[88:89], v[88:89], v[96:97] op_sel_hi:[1,0]
	v_mul_f32_e32 v95, v95, v97
	v_pk_mul_f32 v[90:91], v[90:91], v[96:97] op_sel_hi:[1,0]
	v_mul_f32_e32 v97, 0xbfb8aa3b, v88
	v_exp_f32_e32 v97, v97
	s_nop 0
	v_add_f32_e32 v97, 1.0, v97
	v_rcp_f32_e32 v97, v97
	s_nop 0
	v_mul_f32_e32 v97, v88, v97
	v_mul_f32_e32 v88, 0xbfb8aa3b, v89
	v_exp_f32_e32 v88, v88
	v_pk_mul_f32 v[84:85], v[84:85], v[96:97] op_sel_hi:[1,0]
	v_pk_mul_f32 v[86:87], v[86:87], v[96:97] op_sel_hi:[1,0]
	v_pk_mul_f32 v[80:81], v[80:81], v[96:97] op_sel_hi:[1,0]
	v_add_f32_e32 v88, 1.0, v88
	v_rcp_f32_e32 v88, v88
	v_pk_mul_f32 v[82:83], v[82:83], v[96:97] op_sel_hi:[1,0]
	v_mul_f32_e32 v100, v89, v88
	v_mul_f32_e32 v88, 0xbfb8aa3b, v90
	v_exp_f32_e32 v88, v88
	s_nop 0
	v_add_f32_e32 v88, 1.0, v88
	v_rcp_f32_e32 v88, v88
	s_nop 0
	v_mul_f32_e32 v101, v90, v88
	v_mul_f32_e32 v88, 0xbfb8aa3b, v91
	v_exp_f32_e32 v88, v88
	s_nop 0
	v_add_f32_e32 v88, 1.0, v88
	v_rcp_f32_e32 v88, v88
	s_nop 0
	v_mul_f32_e32 v91, v91, v88
	v_cvt_pk_bf16_f32 v88, v92, v93
	v_lshl_add_u64 v[92:93], s[22:23], 0, v[98:99]
	v_lshl_add_u64 v[92:93], v[92:93], 0, v[124:125]
	v_cvt_pk_bf16_f32 v89, v94, v95
	v_cvt_pk_bf16_f32 v90, v97, v100
	v_cvt_pk_bf16_f32 v91, v101, v91
	global_store_dwordx4 v[92:93], v[88:91], off
	s_nop 1
	v_mul_f32_e32 v88, 0xbfb8aa3b, v84
	v_exp_f32_e32 v88, v88
	s_nop 0
	v_add_f32_e32 v88, 1.0, v88
	v_rcp_f32_e32 v88, v88
	s_nop 0
	v_mul_f32_e32 v84, v84, v88
	v_mul_f32_e32 v88, 0xbfb8aa3b, v85
	v_exp_f32_e32 v88, v88
	s_nop 0
	v_add_f32_e32 v88, 1.0, v88
	v_rcp_f32_e32 v88, v88
	s_nop 0
	v_mul_f32_e32 v85, v85, v88
	v_mul_f32_e32 v88, 0xbfb8aa3b, v86
	v_exp_f32_e32 v88, v88
	s_nop 0
	v_add_f32_e32 v88, 1.0, v88
	v_rcp_f32_e32 v88, v88
	s_nop 0
	v_mul_f32_e32 v86, v86, v88
	v_mul_f32_e32 v88, 0xbfb8aa3b, v87
	v_exp_f32_e32 v88, v88
	s_nop 0
	v_add_f32_e32 v88, 1.0, v88
	v_rcp_f32_e32 v88, v88
	s_nop 0
	v_mul_f32_e32 v87, v87, v88
	v_mul_f32_e32 v88, 0xbfb8aa3b, v80
	v_exp_f32_e32 v88, v88
	s_nop 0
	v_add_f32_e32 v88, 1.0, v88
	v_rcp_f32_e32 v88, v88
	s_nop 0
	v_mul_f32_e32 v88, v80, v88
	v_mul_f32_e32 v80, 0xbfb8aa3b, v81
	v_exp_f32_e32 v80, v80
	s_nop 0
	v_add_f32_e32 v80, 1.0, v80
	v_rcp_f32_e32 v80, v80
	s_nop 0
	v_mul_f32_e32 v89, v81, v80
	v_mul_f32_e32 v80, 0xbfb8aa3b, v82
	v_exp_f32_e32 v80, v80
	s_nop 0
	v_add_f32_e32 v80, 1.0, v80
	v_rcp_f32_e32 v80, v80
	s_nop 0
	v_mul_f32_e32 v90, v82, v80
	v_mul_f32_e32 v80, 0xbfb8aa3b, v83
	v_exp_f32_e32 v80, v80
	s_nop 0
	v_add_f32_e32 v80, 1.0, v80
	v_rcp_f32_e32 v80, v80
	s_nop 0
	v_mul_f32_e32 v83, v83, v80
	v_cvt_pk_bf16_f32 v80, v84, v85
	v_cvt_pk_bf16_f32 v81, v86, v87
	v_cvt_pk_bf16_f32 v82, v88, v89
	v_cvt_pk_bf16_f32 v83, v90, v83
	global_store_dwordx4 v[92:93], v[80:83], off offset:256
	s_nop 1
	v_or_b32_e32 v82, 48, v144
	v_ashrrev_i32_e32 v83, 31, v82
	v_lshl_add_u64 v[80:81], v[82:83], 2, s[24:25]
	v_lshlrev_b64 v[82:83], 12, v[82:83]
	v_fmamk_f32 v80, v243, 0x3a000000, v197
	v_cmp_gt_f32_e32 vcc, s36, v80
	v_mul_f32_e32 v81, 0x4f800000, v80
	s_nop 0
	v_cndmask_b32_e32 v80, v80, v81, vcc
	v_sqrt_f32_e32 v81, v80
	s_nop 0
	v_add_u32_e32 v84, -1, v81
	v_fma_f32 v85, -v84, v81, v80
	v_cmp_ge_f32_e64 s[10:11], 0, v85
	v_add_u32_e32 v85, 1, v81
	s_nop 0
	v_cndmask_b32_e64 v84, v81, v84, s[10:11]
	v_fma_f32 v81, -v85, v81, v80
	v_cmp_lt_f32_e64 s[10:11], 0, v81
	s_nop 1
	v_cndmask_b32_e64 v81, v84, v85, s[10:11]
	v_mul_f32_e32 v84, 0x37800000, v81
	v_cndmask_b32_e32 v81, v81, v84, vcc
	v_cmp_class_f32_e32 vcc, v80, v198
	s_nop 1
	v_cndmask_b32_e32 v80, v81, v80, vcc
	v_div_scale_f32 v81, s[2:3], v80, v80, 1.0
	v_rcp_f32_e32 v84, v81
	s_nop 0
	v_fma_f32 v85, -v81, v84, 1.0
	v_fmac_f32_e32 v84, v85, v84
	v_div_scale_f32 v85, vcc, 1.0, v80, 1.0
	v_mul_f32_e32 v86, v85, v84
	v_fma_f32 v87, -v81, v86, v85
	v_fmac_f32_e32 v86, v87, v84
	v_fma_f32 v81, -v81, v86, v85
	v_div_fmas_f32 v81, v81, v84, v86
	v_div_fixup_f32 v80, v81, v80, 1.0
	v_pk_mul_f32 v[76:77], v[76:77], v[80:81] op_sel_hi:[1,0]
	v_pk_mul_f32 v[78:79], v[78:79], v[80:81] op_sel_hi:[1,0]
	v_mul_f32_e32 v81, 0xbfb8aa3b, v76
	v_exp_f32_e32 v81, v81
	s_nop 0
	v_add_f32_e32 v81, 1.0, v81
	v_rcp_f32_e32 v81, v81
	s_nop 0
	v_mul_f32_e32 v76, v76, v81
	v_mul_f32_e32 v81, 0xbfb8aa3b, v77
	v_exp_f32_e32 v81, v81
	s_nop 0
	v_add_f32_e32 v81, 1.0, v81
	v_rcp_f32_e32 v81, v81
	s_nop 0
	v_mul_f32_e32 v77, v77, v81
	v_mul_f32_e32 v81, 0xbfb8aa3b, v78
	v_exp_f32_e32 v81, v81
	s_nop 0
	v_add_f32_e32 v81, 1.0, v81
	v_rcp_f32_e32 v81, v81
	s_nop 0
	v_mul_f32_e32 v78, v78, v81
	v_mul_f32_e32 v81, 0xbfb8aa3b, v79
	v_exp_f32_e32 v81, v81
	s_nop 0
	v_add_f32_e32 v81, 1.0, v81
	v_rcp_f32_e32 v81, v81
	s_nop 0
	v_pk_mul_f32 v[72:73], v[72:73], v[80:81] op_sel_hi:[1,0]
	v_mul_f32_e32 v79, v79, v81
	v_pk_mul_f32 v[74:75], v[74:75], v[80:81] op_sel_hi:[1,0]
	v_mul_f32_e32 v81, 0xbfb8aa3b, v72
	v_exp_f32_e32 v81, v81
	s_nop 0
	v_add_f32_e32 v81, 1.0, v81
	v_rcp_f32_e32 v81, v81
	s_nop 0
	v_mul_f32_e32 v81, v72, v81
	v_mul_f32_e32 v72, 0xbfb8aa3b, v73
	v_exp_f32_e32 v72, v72
	v_pk_mul_f32 v[68:69], v[68:69], v[80:81] op_sel_hi:[1,0]
	v_pk_mul_f32 v[70:71], v[70:71], v[80:81] op_sel_hi:[1,0]
	v_pk_mul_f32 v[64:65], v[64:65], v[80:81] op_sel_hi:[1,0]
	v_add_f32_e32 v72, 1.0, v72
	v_rcp_f32_e32 v72, v72
	v_pk_mul_f32 v[66:67], v[66:67], v[80:81] op_sel_hi:[1,0]
	v_mul_f32_e32 v84, v73, v72
	v_mul_f32_e32 v72, 0xbfb8aa3b, v74
	v_exp_f32_e32 v72, v72
	s_nop 0
	v_add_f32_e32 v72, 1.0, v72
	v_rcp_f32_e32 v72, v72
	s_nop 0
	v_mul_f32_e32 v85, v74, v72
	v_mul_f32_e32 v72, 0xbfb8aa3b, v75
	v_exp_f32_e32 v72, v72
	s_nop 0
	v_add_f32_e32 v72, 1.0, v72
	v_rcp_f32_e32 v72, v72
	s_nop 0
	v_mul_f32_e32 v75, v75, v72
	v_cvt_pk_bf16_f32 v72, v76, v77
	v_lshl_add_u64 v[76:77], s[22:23], 0, v[82:83]
	v_lshl_add_u64 v[76:77], v[76:77], 0, v[124:125]
	v_cvt_pk_bf16_f32 v73, v78, v79
	v_cvt_pk_bf16_f32 v74, v81, v84
	v_cvt_pk_bf16_f32 v75, v85, v75
	global_store_dwordx4 v[76:77], v[72:75], off
	s_nop 1
	v_mul_f32_e32 v72, 0xbfb8aa3b, v68
	v_exp_f32_e32 v72, v72
	s_nop 0
	v_add_f32_e32 v72, 1.0, v72
	v_rcp_f32_e32 v72, v72
	s_nop 0
	v_mul_f32_e32 v68, v68, v72
	v_mul_f32_e32 v72, 0xbfb8aa3b, v69
	v_exp_f32_e32 v72, v72
	s_nop 0
	v_add_f32_e32 v72, 1.0, v72
	v_rcp_f32_e32 v72, v72
	s_nop 0
	v_mul_f32_e32 v69, v69, v72
	v_mul_f32_e32 v72, 0xbfb8aa3b, v70
	v_exp_f32_e32 v72, v72
	s_nop 0
	v_add_f32_e32 v72, 1.0, v72
	v_rcp_f32_e32 v72, v72
	s_nop 0
	v_mul_f32_e32 v70, v70, v72
	v_mul_f32_e32 v72, 0xbfb8aa3b, v71
	v_exp_f32_e32 v72, v72
	s_nop 0
	v_add_f32_e32 v72, 1.0, v72
	v_rcp_f32_e32 v72, v72
	s_nop 0
	v_mul_f32_e32 v71, v71, v72
	v_mul_f32_e32 v72, 0xbfb8aa3b, v64
	v_exp_f32_e32 v72, v72
	s_nop 0
	v_add_f32_e32 v72, 1.0, v72
	v_rcp_f32_e32 v72, v72
	s_nop 0
	v_mul_f32_e32 v72, v64, v72
	v_mul_f32_e32 v64, 0xbfb8aa3b, v65
	v_exp_f32_e32 v64, v64
	s_nop 0
	v_add_f32_e32 v64, 1.0, v64
	v_rcp_f32_e32 v64, v64
	s_nop 0
	v_mul_f32_e32 v73, v65, v64
	v_mul_f32_e32 v64, 0xbfb8aa3b, v66
	v_exp_f32_e32 v64, v64
	s_nop 0
	v_add_f32_e32 v64, 1.0, v64
	v_rcp_f32_e32 v64, v64
	s_nop 0
	v_mul_f32_e32 v74, v66, v64
	v_mul_f32_e32 v64, 0xbfb8aa3b, v67
	v_exp_f32_e32 v64, v64
	s_nop 0
	v_add_f32_e32 v64, 1.0, v64
	v_rcp_f32_e32 v64, v64
	s_nop 0
	v_mul_f32_e32 v67, v67, v64
	v_cvt_pk_bf16_f32 v64, v68, v69
	v_cvt_pk_bf16_f32 v65, v70, v71
	v_cvt_pk_bf16_f32 v66, v72, v73
	v_cvt_pk_bf16_f32 v67, v74, v67
	global_store_dwordx4 v[76:77], v[64:67], off offset:256
	s_nop 1
	v_add_u32_e32 v66, 0x80, v144
	v_ashrrev_i32_e32 v67, 31, v66
	v_lshl_add_u64 v[64:65], v[66:67], 2, s[24:25]
	v_lshlrev_b64 v[66:67], 12, v[66:67]
	v_fmamk_f32 v64, v244, 0x3a000000, v197
	v_cmp_gt_f32_e32 vcc, s36, v64
	v_mul_f32_e32 v65, 0x4f800000, v64
	s_nop 0
	v_cndmask_b32_e32 v64, v64, v65, vcc
	v_sqrt_f32_e32 v65, v64
	s_nop 0
	v_add_u32_e32 v68, -1, v65
	v_fma_f32 v69, -v68, v65, v64
	v_cmp_ge_f32_e64 s[10:11], 0, v69
	v_add_u32_e32 v69, 1, v65
	s_nop 0
	v_cndmask_b32_e64 v68, v65, v68, s[10:11]
	v_fma_f32 v65, -v69, v65, v64
	v_cmp_lt_f32_e64 s[10:11], 0, v65
	s_nop 1
	v_cndmask_b32_e64 v65, v68, v69, s[10:11]
	v_mul_f32_e32 v68, 0x37800000, v65
	v_cndmask_b32_e32 v65, v65, v68, vcc
	v_cmp_class_f32_e32 vcc, v64, v198
	s_nop 1
	v_cndmask_b32_e32 v64, v65, v64, vcc
	v_div_scale_f32 v65, s[2:3], v64, v64, 1.0
	v_rcp_f32_e32 v68, v65
	s_nop 0
	v_fma_f32 v69, -v65, v68, 1.0
	v_fmac_f32_e32 v68, v69, v68
	v_div_scale_f32 v69, vcc, 1.0, v64, 1.0
	v_mul_f32_e32 v70, v69, v68
	v_fma_f32 v71, -v65, v70, v69
	v_fmac_f32_e32 v70, v71, v68
	v_fma_f32 v65, -v65, v70, v69
	v_div_fmas_f32 v65, v65, v68, v70
	v_div_fixup_f32 v64, v65, v64, 1.0
	v_pk_mul_f32 v[60:61], v[60:61], v[64:65] op_sel_hi:[1,0]
	v_pk_mul_f32 v[62:63], v[62:63], v[64:65] op_sel_hi:[1,0]
	v_mul_f32_e32 v65, 0xbfb8aa3b, v60
	v_exp_f32_e32 v65, v65
	s_nop 0
	v_add_f32_e32 v65, 1.0, v65
	v_rcp_f32_e32 v65, v65
	s_nop 0
	v_mul_f32_e32 v60, v60, v65
	v_mul_f32_e32 v65, 0xbfb8aa3b, v61
	v_exp_f32_e32 v65, v65
	s_nop 0
	v_add_f32_e32 v65, 1.0, v65
	v_rcp_f32_e32 v65, v65
	s_nop 0
	v_mul_f32_e32 v61, v61, v65
	v_mul_f32_e32 v65, 0xbfb8aa3b, v62
	v_exp_f32_e32 v65, v65
	s_nop 0
	v_add_f32_e32 v65, 1.0, v65
	v_rcp_f32_e32 v65, v65
	s_nop 0
	v_mul_f32_e32 v62, v62, v65
	v_mul_f32_e32 v65, 0xbfb8aa3b, v63
	v_exp_f32_e32 v65, v65
	s_nop 0
	v_add_f32_e32 v65, 1.0, v65
	v_rcp_f32_e32 v65, v65
	s_nop 0
	v_pk_mul_f32 v[56:57], v[56:57], v[64:65] op_sel_hi:[1,0]
	v_mul_f32_e32 v63, v63, v65
	v_pk_mul_f32 v[58:59], v[58:59], v[64:65] op_sel_hi:[1,0]
	v_mul_f32_e32 v65, 0xbfb8aa3b, v56
	v_exp_f32_e32 v65, v65
	s_nop 0
	v_add_f32_e32 v65, 1.0, v65
	v_rcp_f32_e32 v65, v65
	s_nop 0
	v_mul_f32_e32 v65, v56, v65
	v_mul_f32_e32 v56, 0xbfb8aa3b, v57
	v_exp_f32_e32 v56, v56
	v_pk_mul_f32 v[52:53], v[52:53], v[64:65] op_sel_hi:[1,0]
	v_pk_mul_f32 v[54:55], v[54:55], v[64:65] op_sel_hi:[1,0]
	v_pk_mul_f32 v[48:49], v[48:49], v[64:65] op_sel_hi:[1,0]
	v_add_f32_e32 v56, 1.0, v56
	v_rcp_f32_e32 v56, v56
	v_pk_mul_f32 v[50:51], v[50:51], v[64:65] op_sel_hi:[1,0]
	v_mul_f32_e32 v68, v57, v56
	v_mul_f32_e32 v56, 0xbfb8aa3b, v58
	v_exp_f32_e32 v56, v56
	s_nop 0
	v_add_f32_e32 v56, 1.0, v56
	v_rcp_f32_e32 v56, v56
	s_nop 0
	v_mul_f32_e32 v69, v58, v56
	v_mul_f32_e32 v56, 0xbfb8aa3b, v59
	v_exp_f32_e32 v56, v56
	s_nop 0
	v_add_f32_e32 v56, 1.0, v56
	v_rcp_f32_e32 v56, v56
	s_nop 0
	v_mul_f32_e32 v59, v59, v56
	v_cvt_pk_bf16_f32 v56, v60, v61
	v_lshl_add_u64 v[60:61], s[22:23], 0, v[66:67]
	v_lshl_add_u64 v[60:61], v[60:61], 0, v[124:125]
	v_cvt_pk_bf16_f32 v57, v62, v63
	v_cvt_pk_bf16_f32 v58, v65, v68
	v_cvt_pk_bf16_f32 v59, v69, v59
	global_store_dwordx4 v[60:61], v[56:59], off
	s_nop 1
	v_mul_f32_e32 v56, 0xbfb8aa3b, v52
	v_exp_f32_e32 v56, v56
	s_nop 0
	v_add_f32_e32 v56, 1.0, v56
	v_rcp_f32_e32 v56, v56
	s_nop 0
	v_mul_f32_e32 v52, v52, v56
	v_mul_f32_e32 v56, 0xbfb8aa3b, v53
	v_exp_f32_e32 v56, v56
	s_nop 0
	v_add_f32_e32 v56, 1.0, v56
	v_rcp_f32_e32 v56, v56
	s_nop 0
	v_mul_f32_e32 v53, v53, v56
	v_mul_f32_e32 v56, 0xbfb8aa3b, v54
	v_exp_f32_e32 v56, v56
	s_nop 0
	v_add_f32_e32 v56, 1.0, v56
	v_rcp_f32_e32 v56, v56
	s_nop 0
	v_mul_f32_e32 v54, v54, v56
	v_mul_f32_e32 v56, 0xbfb8aa3b, v55
	v_exp_f32_e32 v56, v56
	s_nop 0
	v_add_f32_e32 v56, 1.0, v56
	v_rcp_f32_e32 v56, v56
	s_nop 0
	v_mul_f32_e32 v55, v55, v56
	v_mul_f32_e32 v56, 0xbfb8aa3b, v48
	v_exp_f32_e32 v56, v56
	s_nop 0
	v_add_f32_e32 v56, 1.0, v56
	v_rcp_f32_e32 v56, v56
	s_nop 0
	v_mul_f32_e32 v56, v48, v56
	v_mul_f32_e32 v48, 0xbfb8aa3b, v49
	v_exp_f32_e32 v48, v48
	s_nop 0
	v_add_f32_e32 v48, 1.0, v48
	v_rcp_f32_e32 v48, v48
	s_nop 0
	v_mul_f32_e32 v57, v49, v48
	v_mul_f32_e32 v48, 0xbfb8aa3b, v50
	v_exp_f32_e32 v48, v48
	s_nop 0
	v_add_f32_e32 v48, 1.0, v48
	v_rcp_f32_e32 v48, v48
	s_nop 0
	v_mul_f32_e32 v58, v50, v48
	v_mul_f32_e32 v48, 0xbfb8aa3b, v51
	v_exp_f32_e32 v48, v48
	s_nop 0
	v_add_f32_e32 v48, 1.0, v48
	v_rcp_f32_e32 v48, v48
	s_nop 0
	v_mul_f32_e32 v51, v51, v48
	v_cvt_pk_bf16_f32 v48, v52, v53
	v_cvt_pk_bf16_f32 v49, v54, v55
	v_cvt_pk_bf16_f32 v50, v56, v57
	v_cvt_pk_bf16_f32 v51, v58, v51
	global_store_dwordx4 v[60:61], v[48:51], off offset:256
	s_nop 1
	v_add_u32_e32 v50, 0x90, v144
	v_ashrrev_i32_e32 v51, 31, v50
	v_lshl_add_u64 v[48:49], v[50:51], 2, s[24:25]
	v_lshlrev_b64 v[50:51], 12, v[50:51]
	v_fmamk_f32 v48, v245, 0x3a000000, v197
	v_cmp_gt_f32_e32 vcc, s36, v48
	v_mul_f32_e32 v49, 0x4f800000, v48
	s_nop 0
	v_cndmask_b32_e32 v48, v48, v49, vcc
	v_sqrt_f32_e32 v49, v48
	s_nop 0
	v_add_u32_e32 v52, -1, v49
	v_fma_f32 v53, -v52, v49, v48
	v_cmp_ge_f32_e64 s[10:11], 0, v53
	v_add_u32_e32 v53, 1, v49
	s_nop 0
	v_cndmask_b32_e64 v52, v49, v52, s[10:11]
	v_fma_f32 v49, -v53, v49, v48
	v_cmp_lt_f32_e64 s[10:11], 0, v49
	s_nop 1
	v_cndmask_b32_e64 v49, v52, v53, s[10:11]
	v_mul_f32_e32 v52, 0x37800000, v49
	v_cndmask_b32_e32 v49, v49, v52, vcc
	v_cmp_class_f32_e32 vcc, v48, v198
	s_nop 1
	v_cndmask_b32_e32 v48, v49, v48, vcc
	v_div_scale_f32 v49, s[2:3], v48, v48, 1.0
	v_rcp_f32_e32 v52, v49
	s_nop 0
	v_fma_f32 v53, -v49, v52, 1.0
	v_fmac_f32_e32 v52, v53, v52
	v_div_scale_f32 v53, vcc, 1.0, v48, 1.0
	v_mul_f32_e32 v54, v53, v52
	v_fma_f32 v55, -v49, v54, v53
	v_fmac_f32_e32 v54, v55, v52
	v_fma_f32 v49, -v49, v54, v53
	v_div_fmas_f32 v49, v49, v52, v54
	v_div_fixup_f32 v48, v49, v48, 1.0
	v_pk_mul_f32 v[44:45], v[44:45], v[48:49] op_sel_hi:[1,0]
	v_pk_mul_f32 v[46:47], v[46:47], v[48:49] op_sel_hi:[1,0]
	v_mul_f32_e32 v49, 0xbfb8aa3b, v44
	v_exp_f32_e32 v49, v49
	s_nop 0
	v_add_f32_e32 v49, 1.0, v49
	v_rcp_f32_e32 v49, v49
	s_nop 0
	v_mul_f32_e32 v44, v44, v49
	v_mul_f32_e32 v49, 0xbfb8aa3b, v45
	v_exp_f32_e32 v49, v49
	s_nop 0
	v_add_f32_e32 v49, 1.0, v49
	v_rcp_f32_e32 v49, v49
	s_nop 0
	v_mul_f32_e32 v45, v45, v49
	v_mul_f32_e32 v49, 0xbfb8aa3b, v46
	v_exp_f32_e32 v49, v49
	s_nop 0
	v_add_f32_e32 v49, 1.0, v49
	v_rcp_f32_e32 v49, v49
	s_nop 0
	v_mul_f32_e32 v46, v46, v49
	v_mul_f32_e32 v49, 0xbfb8aa3b, v47
	v_exp_f32_e32 v49, v49
	s_nop 0
	v_add_f32_e32 v49, 1.0, v49
	v_rcp_f32_e32 v49, v49
	s_nop 0
	v_pk_mul_f32 v[40:41], v[40:41], v[48:49] op_sel_hi:[1,0]
	v_mul_f32_e32 v47, v47, v49
	v_pk_mul_f32 v[42:43], v[42:43], v[48:49] op_sel_hi:[1,0]
	v_mul_f32_e32 v49, 0xbfb8aa3b, v40
	v_exp_f32_e32 v49, v49
	s_nop 0
	v_add_f32_e32 v49, 1.0, v49
	v_rcp_f32_e32 v49, v49
	s_nop 0
	v_mul_f32_e32 v49, v40, v49
	v_mul_f32_e32 v40, 0xbfb8aa3b, v41
	v_exp_f32_e32 v40, v40
	v_pk_mul_f32 v[36:37], v[36:37], v[48:49] op_sel_hi:[1,0]
	v_pk_mul_f32 v[38:39], v[38:39], v[48:49] op_sel_hi:[1,0]
	v_pk_mul_f32 v[32:33], v[32:33], v[48:49] op_sel_hi:[1,0]
	v_add_f32_e32 v40, 1.0, v40
	v_rcp_f32_e32 v40, v40
	v_pk_mul_f32 v[34:35], v[34:35], v[48:49] op_sel_hi:[1,0]
	v_mul_f32_e32 v52, v41, v40
	v_mul_f32_e32 v40, 0xbfb8aa3b, v42
	v_exp_f32_e32 v40, v40
	s_nop 0
	v_add_f32_e32 v40, 1.0, v40
	v_rcp_f32_e32 v40, v40
	s_nop 0
	v_mul_f32_e32 v53, v42, v40
	v_mul_f32_e32 v40, 0xbfb8aa3b, v43
	v_exp_f32_e32 v40, v40
	s_nop 0
	v_add_f32_e32 v40, 1.0, v40
	v_rcp_f32_e32 v40, v40
	s_nop 0
	v_mul_f32_e32 v43, v43, v40
	v_cvt_pk_bf16_f32 v40, v44, v45
	v_lshl_add_u64 v[44:45], s[22:23], 0, v[50:51]
	v_lshl_add_u64 v[44:45], v[44:45], 0, v[124:125]
	v_cvt_pk_bf16_f32 v41, v46, v47
	v_cvt_pk_bf16_f32 v42, v49, v52
	v_cvt_pk_bf16_f32 v43, v53, v43
	global_store_dwordx4 v[44:45], v[40:43], off
	s_nop 1
	v_mul_f32_e32 v40, 0xbfb8aa3b, v36
	v_exp_f32_e32 v40, v40
	s_nop 0
	v_add_f32_e32 v40, 1.0, v40
	v_rcp_f32_e32 v40, v40
	s_nop 0
	v_mul_f32_e32 v36, v36, v40
	v_mul_f32_e32 v40, 0xbfb8aa3b, v37
	v_exp_f32_e32 v40, v40
	s_nop 0
	v_add_f32_e32 v40, 1.0, v40
	v_rcp_f32_e32 v40, v40
	s_nop 0
	v_mul_f32_e32 v37, v37, v40
	v_mul_f32_e32 v40, 0xbfb8aa3b, v38
	v_exp_f32_e32 v40, v40
	s_nop 0
	v_add_f32_e32 v40, 1.0, v40
	v_rcp_f32_e32 v40, v40
	s_nop 0
	v_mul_f32_e32 v38, v38, v40
	v_mul_f32_e32 v40, 0xbfb8aa3b, v39
	v_exp_f32_e32 v40, v40
	s_nop 0
	v_add_f32_e32 v40, 1.0, v40
	v_rcp_f32_e32 v40, v40
	s_nop 0
	v_mul_f32_e32 v39, v39, v40
	v_mul_f32_e32 v40, 0xbfb8aa3b, v32
	v_exp_f32_e32 v40, v40
	s_nop 0
	v_add_f32_e32 v40, 1.0, v40
	v_rcp_f32_e32 v40, v40
	s_nop 0
	v_mul_f32_e32 v40, v32, v40
	v_mul_f32_e32 v32, 0xbfb8aa3b, v33
	v_exp_f32_e32 v32, v32
	s_nop 0
	v_add_f32_e32 v32, 1.0, v32
	v_rcp_f32_e32 v32, v32
	s_nop 0
	v_mul_f32_e32 v41, v33, v32
	v_mul_f32_e32 v32, 0xbfb8aa3b, v34
	v_exp_f32_e32 v32, v32
	s_nop 0
	v_add_f32_e32 v32, 1.0, v32
	v_rcp_f32_e32 v32, v32
	s_nop 0
	v_mul_f32_e32 v42, v34, v32
	v_mul_f32_e32 v32, 0xbfb8aa3b, v35
	v_exp_f32_e32 v32, v32
	s_nop 0
	v_add_f32_e32 v32, 1.0, v32
	v_rcp_f32_e32 v32, v32
	s_nop 0
	v_mul_f32_e32 v35, v35, v32
	v_cvt_pk_bf16_f32 v32, v36, v37
	v_cvt_pk_bf16_f32 v33, v38, v39
	v_cvt_pk_bf16_f32 v34, v40, v41
	v_cvt_pk_bf16_f32 v35, v42, v35
	global_store_dwordx4 v[44:45], v[32:35], off offset:256
	s_nop 1
	v_add_u32_e32 v34, 0xa0, v144
	v_ashrrev_i32_e32 v35, 31, v34
	v_lshl_add_u64 v[32:33], v[34:35], 2, s[24:25]
	v_lshlrev_b64 v[34:35], 12, v[34:35]
	v_fmamk_f32 v32, v246, 0x3a000000, v197
	v_cmp_gt_f32_e32 vcc, s36, v32
	v_mul_f32_e32 v33, 0x4f800000, v32
	s_nop 0
	v_cndmask_b32_e32 v32, v32, v33, vcc
	v_sqrt_f32_e32 v33, v32
	s_nop 0
	v_add_u32_e32 v36, -1, v33
	v_fma_f32 v37, -v36, v33, v32
	v_cmp_ge_f32_e64 s[10:11], 0, v37
	v_add_u32_e32 v37, 1, v33
	s_nop 0
	v_cndmask_b32_e64 v36, v33, v36, s[10:11]
	v_fma_f32 v33, -v37, v33, v32
	v_cmp_lt_f32_e64 s[10:11], 0, v33
	s_nop 1
	v_cndmask_b32_e64 v33, v36, v37, s[10:11]
	v_mul_f32_e32 v36, 0x37800000, v33
	v_cndmask_b32_e32 v33, v33, v36, vcc
	v_cmp_class_f32_e32 vcc, v32, v198
	s_nop 1
	v_cndmask_b32_e32 v32, v33, v32, vcc
	v_div_scale_f32 v33, s[2:3], v32, v32, 1.0
	v_rcp_f32_e32 v36, v33
	s_nop 0
	v_fma_f32 v37, -v33, v36, 1.0
	v_fmac_f32_e32 v36, v37, v36
	v_div_scale_f32 v37, vcc, 1.0, v32, 1.0
	v_mul_f32_e32 v38, v37, v36
	v_fma_f32 v39, -v33, v38, v37
	v_fmac_f32_e32 v38, v39, v36
	v_fma_f32 v33, -v33, v38, v37
	v_div_fmas_f32 v33, v33, v36, v38
	v_div_fixup_f32 v32, v33, v32, 1.0
	v_pk_mul_f32 v[28:29], v[28:29], v[32:33] op_sel_hi:[1,0]
	v_pk_mul_f32 v[30:31], v[30:31], v[32:33] op_sel_hi:[1,0]
	v_mul_f32_e32 v33, 0xbfb8aa3b, v28
	v_exp_f32_e32 v33, v33
	s_nop 0
	v_add_f32_e32 v33, 1.0, v33
	v_rcp_f32_e32 v33, v33
	s_nop 0
	v_mul_f32_e32 v28, v28, v33
	v_mul_f32_e32 v33, 0xbfb8aa3b, v29
	v_exp_f32_e32 v33, v33
	s_nop 0
	v_add_f32_e32 v33, 1.0, v33
	v_rcp_f32_e32 v33, v33
	s_nop 0
	v_mul_f32_e32 v29, v29, v33
	v_mul_f32_e32 v33, 0xbfb8aa3b, v30
	v_exp_f32_e32 v33, v33
	s_nop 0
	v_add_f32_e32 v33, 1.0, v33
	v_rcp_f32_e32 v33, v33
	s_nop 0
	v_mul_f32_e32 v30, v30, v33
	v_mul_f32_e32 v33, 0xbfb8aa3b, v31
	v_exp_f32_e32 v33, v33
	s_nop 0
	v_add_f32_e32 v33, 1.0, v33
	v_rcp_f32_e32 v33, v33
	s_nop 0
	v_pk_mul_f32 v[24:25], v[24:25], v[32:33] op_sel_hi:[1,0]
	v_mul_f32_e32 v31, v31, v33
	v_pk_mul_f32 v[26:27], v[26:27], v[32:33] op_sel_hi:[1,0]
	v_mul_f32_e32 v33, 0xbfb8aa3b, v24
	v_exp_f32_e32 v33, v33
	s_nop 0
	v_add_f32_e32 v33, 1.0, v33
	v_rcp_f32_e32 v33, v33
	s_nop 0
	v_mul_f32_e32 v33, v24, v33
	v_mul_f32_e32 v24, 0xbfb8aa3b, v25
	v_exp_f32_e32 v24, v24
	v_pk_mul_f32 v[20:21], v[20:21], v[32:33] op_sel_hi:[1,0]
	v_pk_mul_f32 v[22:23], v[22:23], v[32:33] op_sel_hi:[1,0]
	v_pk_mul_f32 v[16:17], v[16:17], v[32:33] op_sel_hi:[1,0]
	v_add_f32_e32 v24, 1.0, v24
	v_rcp_f32_e32 v24, v24
	v_pk_mul_f32 v[18:19], v[18:19], v[32:33] op_sel_hi:[1,0]
	v_mul_f32_e32 v36, v25, v24
	v_mul_f32_e32 v24, 0xbfb8aa3b, v26
	v_exp_f32_e32 v24, v24
	s_nop 0
	v_add_f32_e32 v24, 1.0, v24
	v_rcp_f32_e32 v24, v24
	s_nop 0
	v_mul_f32_e32 v37, v26, v24
	v_mul_f32_e32 v24, 0xbfb8aa3b, v27
	v_exp_f32_e32 v24, v24
	s_nop 0
	v_add_f32_e32 v24, 1.0, v24
	v_rcp_f32_e32 v24, v24
	s_nop 0
	v_mul_f32_e32 v27, v27, v24
	v_cvt_pk_bf16_f32 v24, v28, v29
	v_lshl_add_u64 v[28:29], s[22:23], 0, v[34:35]
	v_lshl_add_u64 v[28:29], v[28:29], 0, v[124:125]
	v_cvt_pk_bf16_f32 v25, v30, v31
	v_cvt_pk_bf16_f32 v26, v33, v36
	v_cvt_pk_bf16_f32 v27, v37, v27
	global_store_dwordx4 v[28:29], v[24:27], off
	s_nop 1
	v_mul_f32_e32 v24, 0xbfb8aa3b, v20
	v_exp_f32_e32 v24, v24
	s_nop 0
	v_add_f32_e32 v24, 1.0, v24
	v_rcp_f32_e32 v24, v24
	s_nop 0
	v_mul_f32_e32 v20, v20, v24
	v_mul_f32_e32 v24, 0xbfb8aa3b, v21
	v_exp_f32_e32 v24, v24
	s_nop 0
	v_add_f32_e32 v24, 1.0, v24
	v_rcp_f32_e32 v24, v24
	s_nop 0
	v_mul_f32_e32 v21, v21, v24
	v_mul_f32_e32 v24, 0xbfb8aa3b, v22
	v_exp_f32_e32 v24, v24
	s_nop 0
	v_add_f32_e32 v24, 1.0, v24
	v_rcp_f32_e32 v24, v24
	s_nop 0
	v_mul_f32_e32 v22, v22, v24
	v_mul_f32_e32 v24, 0xbfb8aa3b, v23
	v_exp_f32_e32 v24, v24
	s_nop 0
	v_add_f32_e32 v24, 1.0, v24
	v_rcp_f32_e32 v24, v24
	s_nop 0
	v_mul_f32_e32 v23, v23, v24
	v_mul_f32_e32 v24, 0xbfb8aa3b, v16
	v_exp_f32_e32 v24, v24
	s_nop 0
	v_add_f32_e32 v24, 1.0, v24
	v_rcp_f32_e32 v24, v24
	s_nop 0
	v_mul_f32_e32 v24, v16, v24
	v_mul_f32_e32 v16, 0xbfb8aa3b, v17
	v_exp_f32_e32 v16, v16
	s_nop 0
	v_add_f32_e32 v16, 1.0, v16
	v_rcp_f32_e32 v16, v16
	s_nop 0
	v_mul_f32_e32 v25, v17, v16
	v_mul_f32_e32 v16, 0xbfb8aa3b, v18
	v_exp_f32_e32 v16, v16
	s_nop 0
	v_add_f32_e32 v16, 1.0, v16
	v_rcp_f32_e32 v16, v16
	s_nop 0
	v_mul_f32_e32 v26, v18, v16
	v_mul_f32_e32 v16, 0xbfb8aa3b, v19
	v_exp_f32_e32 v16, v16
	s_nop 0
	v_add_f32_e32 v16, 1.0, v16
	v_rcp_f32_e32 v16, v16
	s_nop 0
	v_mul_f32_e32 v19, v19, v16
	v_cvt_pk_bf16_f32 v16, v20, v21
	v_cvt_pk_bf16_f32 v17, v22, v23
	v_cvt_pk_bf16_f32 v18, v24, v25
	v_cvt_pk_bf16_f32 v19, v26, v19
	global_store_dwordx4 v[28:29], v[16:19], off offset:256
	s_nop 1
	v_add_u32_e32 v18, 0xb0, v144
	v_ashrrev_i32_e32 v19, 31, v18
	v_lshl_add_u64 v[16:17], v[18:19], 2, s[24:25]
	v_lshlrev_b64 v[18:19], 12, v[18:19]
	v_fmamk_f32 v16, v247, 0x3a000000, v197
	v_cmp_gt_f32_e32 vcc, s36, v16
	v_mul_f32_e32 v17, 0x4f800000, v16
	s_nop 0
	v_cndmask_b32_e32 v16, v16, v17, vcc
	v_sqrt_f32_e32 v17, v16
	s_nop 0
	v_add_u32_e32 v20, -1, v17
	v_fma_f32 v21, -v20, v17, v16
	v_cmp_ge_f32_e64 s[10:11], 0, v21
	v_add_u32_e32 v21, 1, v17
	s_nop 0
	v_cndmask_b32_e64 v20, v17, v20, s[10:11]
	v_fma_f32 v17, -v21, v17, v16
	v_cmp_lt_f32_e64 s[10:11], 0, v17
	s_nop 1
	v_cndmask_b32_e64 v17, v20, v21, s[10:11]
	v_mul_f32_e32 v20, 0x37800000, v17
	v_cndmask_b32_e32 v17, v17, v20, vcc
	v_cmp_class_f32_e32 vcc, v16, v198
	s_nop 1
	v_cndmask_b32_e32 v16, v17, v16, vcc
	v_div_scale_f32 v17, s[2:3], v16, v16, 1.0
	v_rcp_f32_e32 v20, v17
	s_nop 0
	v_fma_f32 v21, -v17, v20, 1.0
	v_fmac_f32_e32 v20, v21, v20
	v_div_scale_f32 v21, vcc, 1.0, v16, 1.0
	v_mul_f32_e32 v22, v21, v20
	v_fma_f32 v23, -v17, v22, v21
	v_fmac_f32_e32 v22, v23, v20
	v_fma_f32 v17, -v17, v22, v21
	v_div_fmas_f32 v17, v17, v20, v22
	v_div_fixup_f32 v16, v17, v16, 1.0
	v_pk_mul_f32 v[12:13], v[12:13], v[16:17] op_sel_hi:[1,0]
	v_pk_mul_f32 v[14:15], v[14:15], v[16:17] op_sel_hi:[1,0]
	v_mul_f32_e32 v17, 0xbfb8aa3b, v12
	v_exp_f32_e32 v17, v17
	s_nop 0
	v_add_f32_e32 v17, 1.0, v17
	v_rcp_f32_e32 v17, v17
	s_nop 0
	v_mul_f32_e32 v12, v12, v17
	v_mul_f32_e32 v17, 0xbfb8aa3b, v13
	v_exp_f32_e32 v17, v17
	s_nop 0
	v_add_f32_e32 v17, 1.0, v17
	v_rcp_f32_e32 v17, v17
	s_nop 0
	v_mul_f32_e32 v13, v13, v17
	v_mul_f32_e32 v17, 0xbfb8aa3b, v14
	v_exp_f32_e32 v17, v17
	s_nop 0
	v_add_f32_e32 v17, 1.0, v17
	v_rcp_f32_e32 v17, v17
	s_nop 0
	v_mul_f32_e32 v14, v14, v17
	v_mul_f32_e32 v17, 0xbfb8aa3b, v15
	v_exp_f32_e32 v17, v17
	s_nop 0
	v_add_f32_e32 v17, 1.0, v17
	v_rcp_f32_e32 v17, v17
	s_nop 0
	v_pk_mul_f32 v[8:9], v[8:9], v[16:17] op_sel_hi:[1,0]
	v_mul_f32_e32 v15, v15, v17
	v_pk_mul_f32 v[10:11], v[10:11], v[16:17] op_sel_hi:[1,0]
	v_mul_f32_e32 v17, 0xbfb8aa3b, v8
	v_exp_f32_e32 v17, v17
	s_nop 0
	v_add_f32_e32 v17, 1.0, v17
	v_rcp_f32_e32 v17, v17
	s_nop 0
	v_mul_f32_e32 v17, v8, v17
	v_mul_f32_e32 v8, 0xbfb8aa3b, v9
	v_exp_f32_e32 v8, v8
	v_pk_mul_f32 v[4:5], v[4:5], v[16:17] op_sel_hi:[1,0]
	v_pk_mul_f32 v[6:7], v[6:7], v[16:17] op_sel_hi:[1,0]
	v_pk_mul_f32 v[0:1], v[0:1], v[16:17] op_sel_hi:[1,0]
	v_add_f32_e32 v8, 1.0, v8
	v_rcp_f32_e32 v8, v8
	v_pk_mul_f32 v[2:3], v[2:3], v[16:17] op_sel_hi:[1,0]
	v_mul_f32_e32 v20, v9, v8
	v_mul_f32_e32 v8, 0xbfb8aa3b, v10
	v_exp_f32_e32 v8, v8
	s_nop 0
	v_add_f32_e32 v8, 1.0, v8
	v_rcp_f32_e32 v8, v8
	s_nop 0
	v_mul_f32_e32 v21, v10, v8
	v_mul_f32_e32 v8, 0xbfb8aa3b, v11
	v_exp_f32_e32 v8, v8
	s_nop 0
	v_add_f32_e32 v8, 1.0, v8
	v_rcp_f32_e32 v8, v8
	s_nop 0
	v_mul_f32_e32 v11, v11, v8
	v_cvt_pk_bf16_f32 v8, v12, v13
	v_lshl_add_u64 v[12:13], s[22:23], 0, v[18:19]
	v_lshl_add_u64 v[12:13], v[12:13], 0, v[124:125]
	v_cvt_pk_bf16_f32 v9, v14, v15
	v_cvt_pk_bf16_f32 v10, v17, v20
	v_cvt_pk_bf16_f32 v11, v21, v11
	global_store_dwordx4 v[12:13], v[8:11], off
	s_nop 1
	v_mul_f32_e32 v8, 0xbfb8aa3b, v4
	v_exp_f32_e32 v8, v8
	s_nop 0
	v_add_f32_e32 v8, 1.0, v8
	v_rcp_f32_e32 v8, v8
	s_nop 0
	v_mul_f32_e32 v4, v4, v8
	v_mul_f32_e32 v8, 0xbfb8aa3b, v5
	v_exp_f32_e32 v8, v8
	s_nop 0
	v_add_f32_e32 v8, 1.0, v8
	v_rcp_f32_e32 v8, v8
	s_nop 0
	v_mul_f32_e32 v5, v5, v8
	v_mul_f32_e32 v8, 0xbfb8aa3b, v6
	v_exp_f32_e32 v8, v8
	s_nop 0
	v_add_f32_e32 v8, 1.0, v8
	v_rcp_f32_e32 v8, v8
	s_nop 0
	v_mul_f32_e32 v6, v6, v8
	v_mul_f32_e32 v8, 0xbfb8aa3b, v7
	v_exp_f32_e32 v8, v8
	s_nop 0
	v_add_f32_e32 v8, 1.0, v8
	v_rcp_f32_e32 v8, v8
	s_nop 0
	v_mul_f32_e32 v7, v7, v8
	v_mul_f32_e32 v8, 0xbfb8aa3b, v0
	v_exp_f32_e32 v8, v8
	s_nop 0
	v_add_f32_e32 v8, 1.0, v8
	v_rcp_f32_e32 v8, v8
	s_nop 0
	v_mul_f32_e32 v8, v0, v8
	v_mul_f32_e32 v0, 0xbfb8aa3b, v1
	v_exp_f32_e32 v0, v0
	s_nop 0
	v_add_f32_e32 v0, 1.0, v0
	v_rcp_f32_e32 v0, v0
	s_nop 0
	v_mul_f32_e32 v9, v1, v0
	v_mul_f32_e32 v0, 0xbfb8aa3b, v2
	v_exp_f32_e32 v0, v0
	s_nop 0
	v_add_f32_e32 v0, 1.0, v0
	v_rcp_f32_e32 v0, v0
	s_nop 0
	v_mul_f32_e32 v10, v2, v0
	v_mul_f32_e32 v0, 0xbfb8aa3b, v3
	v_exp_f32_e32 v0, v0
	s_nop 0
	v_add_f32_e32 v0, 1.0, v0
	v_rcp_f32_e32 v0, v0
	s_nop 0
	v_mul_f32_e32 v3, v3, v0
	v_cvt_pk_bf16_f32 v0, v4, v5
	v_cvt_pk_bf16_f32 v1, v6, v7
	v_cvt_pk_bf16_f32 v2, v8, v9
	v_cvt_pk_bf16_f32 v3, v10, v3
	global_store_dwordx4 v[12:13], v[0:3], off offset:256
	s_andn2_b64 vcc, exec, s[8:9]
	s_mov_b64 s[8:9], -1
	s_cbranch_vccnz .LBB0_496
	s_branch .LBB0_545

.LBB0_506:
	s_cmp_lg_u32 s2, 2
	s_cbranch_scc0 .LBB0_524
	v_lshl_add_u32 v146, s82, 8, v154
	v_ashrrev_i32_e32 v147, 31, v146
	v_lshl_add_u64 v[148:149], v[146:147], 2, s[24:25]
	global_load_dword v240, v[148:149], off
	global_load_dword v241, v[148:149], off offset:64
	global_load_dword v242, v[148:149], off offset:128
	global_load_dword v243, v[148:149], off offset:192
	global_load_dword v244, v[148:149], off offset:512
	global_load_dword v245, v[148:149], off offset:576
	global_load_dword v246, v[148:149], off offset:640
	global_load_dword v247, v[148:149], off offset:704
	s_lshl_b32 s3, s2, 8
	s_add_i32 s4, s3, 0xfffffd00
	s_cmp_gt_i32 s2, 2
	s_mov_b32 s10, 0xd200000
	s_cselect_b32 s10, s10, 0xc200000
	s_cselect_b32 s3, s4, s3
	s_cselect_b32 s33, 0, 0
	s_cselect_b32 s34, s94, 0x400000
	s_add_u32 s10, s18, s10
	v_or_b32_e32 v144, s3, v156
	s_addc_u32 s11, s19, 0
	v_ashrrev_i32_e32 v145, 31, v144
	v_lshl_add_u64 v[144:145], v[144:145], 1, s[10:11]
	s_add_u32 s44, s18, s34
	s_addc_u32 s45, s19, s33
	s_waitcnt vmcnt(0)
	v_fmamk_f32 v148, v240, 0x3a000000, v197
	v_cmp_gt_f32_e32 vcc, s36, v148
	v_mul_f32_e32 v149, 0x4f800000, v148
	s_nop 0
	v_cndmask_b32_e32 v148, v148, v149, vcc
	v_sqrt_f32_e32 v149, v148
	s_nop 0
	v_add_u32_e32 v150, -1, v149
	v_fma_f32 v151, -v150, v149, v148
	v_cmp_ge_f32_e64 s[10:11], 0, v151
	v_add_u32_e32 v151, 1, v149
	s_nop 0
	v_cndmask_b32_e64 v150, v149, v150, s[10:11]
	v_fma_f32 v149, -v151, v149, v148
	v_cmp_lt_f32_e64 s[10:11], 0, v149
	s_nop 1
	v_cndmask_b32_e64 v149, v150, v151, s[10:11]
	v_mul_f32_e32 v150, 0x37800000, v149
	v_cndmask_b32_e32 v149, v149, v150, vcc
	v_cmp_class_f32_e32 vcc, v148, v198
	s_nop 1
	v_cndmask_b32_e32 v148, v149, v148, vcc
	v_div_scale_f32 v149, s[10:11], v148, v148, 1.0
	v_rcp_f32_e32 v150, v149
	s_nop 0
	v_fma_f32 v151, -v149, v150, 1.0
	v_fmac_f32_e32 v150, v151, v150
	v_div_scale_f32 v151, vcc, 1.0, v148, 1.0
	v_mul_f32_e32 v152, v151, v150
	v_fma_f32 v153, -v149, v152, v151
	v_fmac_f32_e32 v152, v153, v150
	v_fma_f32 v149, -v149, v152, v151
	v_div_fmas_f32 v149, v149, v150, v152
	v_div_fixup_f32 v148, v149, v148, 1.0
	v_pk_mul_f32 v[152:153], v[126:127], v[148:149] op_sel_hi:[1,0]
	v_pk_mul_f32 v[160:161], v[124:125], v[148:149] op_sel_hi:[1,0]
	v_pk_mul_f32 v[164:165], v[122:123], v[148:149] op_sel_hi:[1,0]
	v_pk_mul_f32 v[162:163], v[120:121], v[148:149] op_sel_hi:[1,0]
	v_mul_f32_e32 v149, v161, v161
	v_mul_f32_e32 v159, v153, v153
	v_fmac_f32_e32 v149, v160, v160
	v_fmac_f32_e32 v159, v152, v152
	v_add_f32_e32 v149, v149, v159
	v_mul_f32_e32 v159, v163, v163
	v_lshlrev_b64 v[150:151], 10, v[146:147]
	v_fmac_f32_e32 v159, v162, v162
	v_lshl_add_u64 v[150:151], v[144:145], 0, v[150:151]
	v_add_f32_e32 v149, v159, v149
	v_cvt_pk_bf16_f32 v160, v160, v161
	v_cvt_pk_bf16_f32 v161, v152, v153
	v_mul_f32_e32 v159, v165, v165
	v_cvt_pk_bf16_f32 v162, v162, v163
	v_cvt_pk_bf16_f32 v163, v164, v165
	global_store_dwordx4 v[150:151], v[160:163], off
	v_pk_mul_f32 v[152:153], v[118:119], v[148:149] op_sel_hi:[1,0]
	v_fmac_f32_e32 v159, v164, v164
	v_pk_mul_f32 v[160:161], v[116:117], v[148:149] op_sel_hi:[1,0]
	v_mul_f32_e32 v163, v153, v153
	v_mul_f32_e32 v162, v161, v161
	v_add_f32_e32 v159, v159, v149
	v_pk_mul_f32 v[164:165], v[114:115], v[148:149] op_sel_hi:[1,0]
	v_pk_mul_f32 v[148:149], v[112:113], v[148:149] op_sel_hi:[1,0]
	v_fmac_f32_e32 v162, v160, v160
	v_fmac_f32_e32 v163, v152, v152
	v_add_f32_e32 v162, v162, v163
	v_mul_f32_e32 v163, v149, v149
	v_fmac_f32_e32 v163, v148, v148
	v_add_f32_e32 v162, v163, v162
	v_mul_f32_e32 v163, v165, v165
	v_fmac_f32_e32 v163, v164, v164
	v_add_f32_e32 v162, v163, v162
	v_add_f32_e32 v159, v159, v162
	v_cvt_pk_bf16_f32 v160, v160, v161
	v_cvt_pk_bf16_f32 v161, v152, v153
	v_cvt_pk_bf16_f32 v162, v148, v149
	v_mov_b32_e32 v148, v159
	s_nop 1
	v_permlane16_swap_b32_e32 v159, v148
	v_cvt_pk_bf16_f32 v163, v164, v165
	global_store_dwordx4 v[150:151], v[160:163], off offset:256
	v_add_f32_e32 v150, v159, v148
	v_mov_b32_e32 v151, v150
	s_nop 1
	v_permlane32_swap_b32_e32 v150, v151
	v_lshl_add_u64 v[148:149], v[146:147], 2, s[44:45]
	s_and_saveexec_b64 s[10:11], s[6:7]
	s_cbranch_execz .LBB0_509
	v_add_f32_e32 v147, v150, v151
	global_atomic_add_f32 v[148:149], v147, off
.LBB0_509:
	s_or_b64 exec, exec, s[10:11]
	v_or_b32_e32 v152, 16, v146
	v_ashrrev_i32_e32 v153, 31, v152
	v_lshl_add_u64 v[150:151], v[152:153], 2, s[24:25]
	v_lshlrev_b64 v[152:153], 10, v[152:153]
	v_lshl_add_u64 v[152:153], v[144:145], 0, v[152:153]
	v_fmamk_f32 v147, v241, 0x3a000000, v197
	v_cmp_gt_f32_e32 vcc, s36, v147
	v_mul_f32_e32 v150, 0x4f800000, v147
	s_nop 0
	v_cndmask_b32_e32 v147, v147, v150, vcc
	v_sqrt_f32_e32 v150, v147
	s_nop 0
	v_add_u32_e32 v151, -1, v150
	v_fma_f32 v159, -v151, v150, v147
	v_cmp_ge_f32_e64 s[10:11], 0, v159
	v_add_u32_e32 v159, 1, v150
	s_nop 0
	v_cndmask_b32_e64 v151, v150, v151, s[10:11]
	v_fma_f32 v150, -v159, v150, v147
	v_cmp_lt_f32_e64 s[10:11], 0, v150
	s_nop 1
	v_cndmask_b32_e64 v150, v151, v159, s[10:11]
	v_mul_f32_e32 v151, 0x37800000, v150
	v_cndmask_b32_e32 v150, v150, v151, vcc
	v_cmp_class_f32_e32 vcc, v147, v198
	s_nop 1
	v_cndmask_b32_e32 v147, v150, v147, vcc
	v_div_scale_f32 v150, s[10:11], v147, v147, 1.0
	v_rcp_f32_e32 v151, v150
	s_nop 0
	v_fma_f32 v159, -v150, v151, 1.0
	v_fmac_f32_e32 v151, v159, v151
	v_div_scale_f32 v159, vcc, 1.0, v147, 1.0
	v_mul_f32_e32 v160, v159, v151
	v_fma_f32 v161, -v150, v160, v159
	v_fmac_f32_e32 v160, v161, v151
	v_fma_f32 v150, -v150, v160, v159
	v_div_fmas_f32 v150, v150, v151, v160
	v_div_fixup_f32 v150, v150, v147, 1.0
	v_pk_mul_f32 v[162:163], v[110:111], v[150:151] op_sel_hi:[1,0]
	v_pk_mul_f32 v[160:161], v[108:109], v[150:151] op_sel_hi:[1,0]
	v_pk_mul_f32 v[164:165], v[106:107], v[150:151] op_sel_hi:[1,0]
	v_pk_mul_f32 v[166:167], v[104:105], v[150:151] op_sel_hi:[1,0]
	v_mul_f32_e32 v147, v161, v161
	v_mul_f32_e32 v151, v163, v163
	v_fmac_f32_e32 v147, v160, v160
	v_fmac_f32_e32 v151, v162, v162
	v_add_f32_e32 v147, v147, v151
	v_mul_f32_e32 v151, v167, v167
	v_fmac_f32_e32 v151, v166, v166
	v_add_f32_e32 v147, v151, v147
	v_mul_f32_e32 v151, v165, v165
	v_fmac_f32_e32 v151, v164, v164
	v_cvt_pk_bf16_f32 v160, v160, v161
	v_cvt_pk_bf16_f32 v161, v162, v163
	v_cvt_pk_bf16_f32 v162, v166, v167
	v_cvt_pk_bf16_f32 v163, v164, v165
	global_store_dwordx4 v[152:153], v[160:163], off
	v_add_f32_e32 v147, v151, v147
	v_pk_mul_f32 v[164:165], v[98:99], v[150:151] op_sel_hi:[1,0]
	v_pk_mul_f32 v[162:163], v[102:103], v[150:151] op_sel_hi:[1,0]
	v_pk_mul_f32 v[160:161], v[100:101], v[150:151] op_sel_hi:[1,0]
	v_mul_f32_e32 v166, v163, v163
	v_mul_f32_e32 v159, v161, v161
	v_pk_mul_f32 v[150:151], v[96:97], v[150:151] op_sel_hi:[1,0]
	v_fmac_f32_e32 v159, v160, v160
	v_fmac_f32_e32 v166, v162, v162
	v_add_f32_e32 v159, v159, v166
	v_mul_f32_e32 v166, v151, v151
	v_fmac_f32_e32 v166, v150, v150
	v_add_f32_e32 v159, v166, v159
	v_mul_f32_e32 v166, v165, v165
	v_fmac_f32_e32 v166, v164, v164
	v_add_f32_e32 v159, v166, v159
	v_add_f32_e32 v147, v147, v159
	v_cvt_pk_bf16_f32 v160, v160, v161
	v_cvt_pk_bf16_f32 v161, v162, v163
	v_cvt_pk_bf16_f32 v162, v150, v151
	v_mov_b32_e32 v150, v147
	s_nop 1
	v_permlane16_swap_b32_e32 v147, v150
	v_add_f32_e32 v147, v147, v150
	v_mov_b32_e32 v150, v147
	s_nop 1
	v_permlane32_swap_b32_e32 v147, v150
	v_cvt_pk_bf16_f32 v163, v164, v165
	global_store_dwordx4 v[152:153], v[160:163], off offset:256
	s_and_saveexec_b64 s[10:11], s[6:7]
	s_cbranch_execz .LBB0_511
	v_add_f32_e32 v147, v147, v150
	global_atomic_add_f32 v[148:149], v147, off offset:64
.LBB0_511:
	s_or_b64 exec, exec, s[10:11]
	v_or_b32_e32 v152, 32, v146
	v_ashrrev_i32_e32 v153, 31, v152
	v_lshl_add_u64 v[150:151], v[152:153], 2, s[24:25]
	v_lshlrev_b64 v[152:153], 10, v[152:153]
	v_lshl_add_u64 v[152:153], v[144:145], 0, v[152:153]
	v_fmamk_f32 v147, v242, 0x3a000000, v197
	v_cmp_gt_f32_e32 vcc, s36, v147
	v_mul_f32_e32 v150, 0x4f800000, v147
	s_nop 0
	v_cndmask_b32_e32 v147, v147, v150, vcc
	v_sqrt_f32_e32 v150, v147
	s_nop 0
	v_add_u32_e32 v151, -1, v150
	v_fma_f32 v159, -v151, v150, v147
	v_cmp_ge_f32_e64 s[10:11], 0, v159
	v_add_u32_e32 v159, 1, v150
	s_nop 0
	v_cndmask_b32_e64 v151, v150, v151, s[10:11]
	v_fma_f32 v150, -v159, v150, v147
	v_cmp_lt_f32_e64 s[10:11], 0, v150
	s_nop 1
	v_cndmask_b32_e64 v150, v151, v159, s[10:11]
	v_mul_f32_e32 v151, 0x37800000, v150
	v_cndmask_b32_e32 v150, v150, v151, vcc
	v_cmp_class_f32_e32 vcc, v147, v198
	s_nop 1
	v_cndmask_b32_e32 v147, v150, v147, vcc
	v_div_scale_f32 v150, s[10:11], v147, v147, 1.0
	v_rcp_f32_e32 v151, v150
	s_nop 0
	v_fma_f32 v159, -v150, v151, 1.0
	v_fmac_f32_e32 v151, v159, v151
	v_div_scale_f32 v159, vcc, 1.0, v147, 1.0
	v_mul_f32_e32 v160, v159, v151
	v_fma_f32 v161, -v150, v160, v159
	v_fmac_f32_e32 v160, v161, v151
	v_fma_f32 v150, -v150, v160, v159
	v_div_fmas_f32 v150, v150, v151, v160
	v_div_fixup_f32 v150, v150, v147, 1.0
	v_pk_mul_f32 v[162:163], v[94:95], v[150:151] op_sel_hi:[1,0]
	v_pk_mul_f32 v[160:161], v[92:93], v[150:151] op_sel_hi:[1,0]
	v_pk_mul_f32 v[164:165], v[90:91], v[150:151] op_sel_hi:[1,0]
	v_pk_mul_f32 v[166:167], v[88:89], v[150:151] op_sel_hi:[1,0]
	v_mul_f32_e32 v147, v161, v161
	v_mul_f32_e32 v151, v163, v163
	v_fmac_f32_e32 v147, v160, v160
	v_fmac_f32_e32 v151, v162, v162
	v_add_f32_e32 v147, v147, v151
	v_mul_f32_e32 v151, v167, v167
	v_fmac_f32_e32 v151, v166, v166
	v_add_f32_e32 v147, v151, v147
	v_mul_f32_e32 v151, v165, v165
	v_fmac_f32_e32 v151, v164, v164
	v_cvt_pk_bf16_f32 v160, v160, v161
	v_cvt_pk_bf16_f32 v161, v162, v163
	v_cvt_pk_bf16_f32 v162, v166, v167
	v_cvt_pk_bf16_f32 v163, v164, v165
	global_store_dwordx4 v[152:153], v[160:163], off
	v_add_f32_e32 v147, v151, v147
	v_pk_mul_f32 v[164:165], v[82:83], v[150:151] op_sel_hi:[1,0]
	v_pk_mul_f32 v[162:163], v[86:87], v[150:151] op_sel_hi:[1,0]
	v_pk_mul_f32 v[160:161], v[84:85], v[150:151] op_sel_hi:[1,0]
	v_mul_f32_e32 v166, v163, v163
	v_mul_f32_e32 v159, v161, v161
	v_pk_mul_f32 v[150:151], v[80:81], v[150:151] op_sel_hi:[1,0]
	v_fmac_f32_e32 v159, v160, v160
	v_fmac_f32_e32 v166, v162, v162
	v_add_f32_e32 v159, v159, v166
	v_mul_f32_e32 v166, v151, v151
	v_fmac_f32_e32 v166, v150, v150
	v_add_f32_e32 v159, v166, v159
	v_mul_f32_e32 v166, v165, v165
	v_fmac_f32_e32 v166, v164, v164
	v_add_f32_e32 v159, v166, v159
	v_add_f32_e32 v147, v147, v159
	v_cvt_pk_bf16_f32 v160, v160, v161
	v_cvt_pk_bf16_f32 v161, v162, v163
	v_cvt_pk_bf16_f32 v162, v150, v151
	v_mov_b32_e32 v150, v147
	s_nop 1
	v_permlane16_swap_b32_e32 v147, v150
	v_add_f32_e32 v147, v147, v150
	v_mov_b32_e32 v150, v147
	s_nop 1
	v_permlane32_swap_b32_e32 v147, v150
	v_cvt_pk_bf16_f32 v163, v164, v165
	global_store_dwordx4 v[152:153], v[160:163], off offset:256
	s_and_saveexec_b64 s[10:11], s[6:7]
	s_cbranch_execz .LBB0_513
	v_add_f32_e32 v147, v147, v150
	global_atomic_add_f32 v[148:149], v147, off offset:128
.LBB0_513:
	s_or_b64 exec, exec, s[10:11]
	v_or_b32_e32 v152, 48, v146
	v_ashrrev_i32_e32 v153, 31, v152
	v_lshl_add_u64 v[150:151], v[152:153], 2, s[24:25]
	v_lshlrev_b64 v[152:153], 10, v[152:153]
	v_lshl_add_u64 v[152:153], v[144:145], 0, v[152:153]
	v_fmamk_f32 v147, v243, 0x3a000000, v197
	v_cmp_gt_f32_e32 vcc, s36, v147
	v_mul_f32_e32 v150, 0x4f800000, v147
	s_nop 0
	v_cndmask_b32_e32 v147, v147, v150, vcc
	v_sqrt_f32_e32 v150, v147
	s_nop 0
	v_add_u32_e32 v151, -1, v150
	v_fma_f32 v159, -v151, v150, v147
	v_cmp_ge_f32_e64 s[10:11], 0, v159
	v_add_u32_e32 v159, 1, v150
	s_nop 0
	v_cndmask_b32_e64 v151, v150, v151, s[10:11]
	v_fma_f32 v150, -v159, v150, v147
	v_cmp_lt_f32_e64 s[10:11], 0, v150
	s_nop 1
	v_cndmask_b32_e64 v150, v151, v159, s[10:11]
	v_mul_f32_e32 v151, 0x37800000, v150
	v_cndmask_b32_e32 v150, v150, v151, vcc
	v_cmp_class_f32_e32 vcc, v147, v198
	s_nop 1
	v_cndmask_b32_e32 v147, v150, v147, vcc
	v_div_scale_f32 v150, s[10:11], v147, v147, 1.0
	v_rcp_f32_e32 v151, v150
	s_nop 0
	v_fma_f32 v159, -v150, v151, 1.0
	v_fmac_f32_e32 v151, v159, v151
	v_div_scale_f32 v159, vcc, 1.0, v147, 1.0
	v_mul_f32_e32 v160, v159, v151
	v_fma_f32 v161, -v150, v160, v159
	v_fmac_f32_e32 v160, v161, v151
	v_fma_f32 v150, -v150, v160, v159
	v_div_fmas_f32 v150, v150, v151, v160
	v_div_fixup_f32 v150, v150, v147, 1.0
	v_pk_mul_f32 v[162:163], v[78:79], v[150:151] op_sel_hi:[1,0]
	v_pk_mul_f32 v[160:161], v[76:77], v[150:151] op_sel_hi:[1,0]
	v_pk_mul_f32 v[164:165], v[74:75], v[150:151] op_sel_hi:[1,0]
	v_pk_mul_f32 v[166:167], v[72:73], v[150:151] op_sel_hi:[1,0]
	v_mul_f32_e32 v147, v161, v161
	v_mul_f32_e32 v151, v163, v163
	v_fmac_f32_e32 v147, v160, v160
	v_fmac_f32_e32 v151, v162, v162
	v_add_f32_e32 v147, v147, v151
	v_mul_f32_e32 v151, v167, v167
	v_fmac_f32_e32 v151, v166, v166
	v_add_f32_e32 v147, v151, v147
	v_mul_f32_e32 v151, v165, v165
	v_fmac_f32_e32 v151, v164, v164
	v_cvt_pk_bf16_f32 v160, v160, v161
	v_cvt_pk_bf16_f32 v161, v162, v163
	v_cvt_pk_bf16_f32 v162, v166, v167
	v_cvt_pk_bf16_f32 v163, v164, v165
	global_store_dwordx4 v[152:153], v[160:163], off
	v_add_f32_e32 v147, v151, v147
	v_pk_mul_f32 v[164:165], v[66:67], v[150:151] op_sel_hi:[1,0]
	v_pk_mul_f32 v[162:163], v[70:71], v[150:151] op_sel_hi:[1,0]
	v_pk_mul_f32 v[160:161], v[68:69], v[150:151] op_sel_hi:[1,0]
	v_mul_f32_e32 v166, v163, v163
	v_mul_f32_e32 v159, v161, v161
	v_pk_mul_f32 v[150:151], v[64:65], v[150:151] op_sel_hi:[1,0]
	v_fmac_f32_e32 v159, v160, v160
	v_fmac_f32_e32 v166, v162, v162
	v_add_f32_e32 v159, v159, v166
	v_mul_f32_e32 v166, v151, v151
	v_fmac_f32_e32 v166, v150, v150
	v_add_f32_e32 v159, v166, v159
	v_mul_f32_e32 v166, v165, v165
	v_fmac_f32_e32 v166, v164, v164
	v_add_f32_e32 v159, v166, v159
	v_add_f32_e32 v147, v147, v159
	v_cvt_pk_bf16_f32 v160, v160, v161
	v_cvt_pk_bf16_f32 v161, v162, v163
	v_cvt_pk_bf16_f32 v162, v150, v151
	v_mov_b32_e32 v150, v147
	s_nop 1
	v_permlane16_swap_b32_e32 v147, v150
	v_add_f32_e32 v147, v147, v150
	v_mov_b32_e32 v150, v147
	s_nop 1
	v_permlane32_swap_b32_e32 v147, v150
	v_cvt_pk_bf16_f32 v163, v164, v165
	global_store_dwordx4 v[152:153], v[160:163], off offset:256
	s_and_saveexec_b64 s[10:11], s[6:7]
	s_cbranch_execz .LBB0_515
	v_add_f32_e32 v147, v147, v150
	global_atomic_add_f32 v[148:149], v147, off offset:192
.LBB0_515:
	s_or_b64 exec, exec, s[10:11]
	v_add_u32_e32 v152, 0x80, v146
	v_ashrrev_i32_e32 v153, 31, v152
	v_lshl_add_u64 v[150:151], v[152:153], 2, s[24:25]
	v_lshlrev_b64 v[152:153], 10, v[152:153]
	v_lshl_add_u64 v[152:153], v[144:145], 0, v[152:153]
	v_fmamk_f32 v147, v244, 0x3a000000, v197
	v_cmp_gt_f32_e32 vcc, s36, v147
	v_mul_f32_e32 v150, 0x4f800000, v147
	s_nop 0
	v_cndmask_b32_e32 v147, v147, v150, vcc
	v_sqrt_f32_e32 v150, v147
	s_nop 0
	v_add_u32_e32 v151, -1, v150
	v_fma_f32 v159, -v151, v150, v147
	v_cmp_ge_f32_e64 s[10:11], 0, v159
	v_add_u32_e32 v159, 1, v150
	s_nop 0
	v_cndmask_b32_e64 v151, v150, v151, s[10:11]
	v_fma_f32 v150, -v159, v150, v147
	v_cmp_lt_f32_e64 s[10:11], 0, v150
	s_nop 1
	v_cndmask_b32_e64 v150, v151, v159, s[10:11]
	v_mul_f32_e32 v151, 0x37800000, v150
	v_cndmask_b32_e32 v150, v150, v151, vcc
	v_cmp_class_f32_e32 vcc, v147, v198
	s_nop 1
	v_cndmask_b32_e32 v147, v150, v147, vcc
	v_div_scale_f32 v150, s[10:11], v147, v147, 1.0
	v_rcp_f32_e32 v151, v150
	s_nop 0
	v_fma_f32 v159, -v150, v151, 1.0
	v_fmac_f32_e32 v151, v159, v151
	v_div_scale_f32 v159, vcc, 1.0, v147, 1.0
	v_mul_f32_e32 v160, v159, v151
	v_fma_f32 v161, -v150, v160, v159
	v_fmac_f32_e32 v160, v161, v151
	v_fma_f32 v150, -v150, v160, v159
	v_div_fmas_f32 v150, v150, v151, v160
	v_div_fixup_f32 v150, v150, v147, 1.0
	v_pk_mul_f32 v[162:163], v[62:63], v[150:151] op_sel_hi:[1,0]
	v_pk_mul_f32 v[160:161], v[60:61], v[150:151] op_sel_hi:[1,0]
	v_pk_mul_f32 v[164:165], v[58:59], v[150:151] op_sel_hi:[1,0]
	v_pk_mul_f32 v[166:167], v[56:57], v[150:151] op_sel_hi:[1,0]
	v_mul_f32_e32 v147, v161, v161
	v_mul_f32_e32 v151, v163, v163
	v_fmac_f32_e32 v147, v160, v160
	v_fmac_f32_e32 v151, v162, v162
	v_add_f32_e32 v147, v147, v151
	v_mul_f32_e32 v151, v167, v167
	v_fmac_f32_e32 v151, v166, v166
	v_add_f32_e32 v147, v151, v147
	v_mul_f32_e32 v151, v165, v165
	v_fmac_f32_e32 v151, v164, v164
	v_cvt_pk_bf16_f32 v160, v160, v161
	v_cvt_pk_bf16_f32 v161, v162, v163
	v_cvt_pk_bf16_f32 v162, v166, v167
	v_cvt_pk_bf16_f32 v163, v164, v165
	global_store_dwordx4 v[152:153], v[160:163], off
	v_add_f32_e32 v147, v151, v147
	v_pk_mul_f32 v[164:165], v[50:51], v[150:151] op_sel_hi:[1,0]
	v_pk_mul_f32 v[162:163], v[54:55], v[150:151] op_sel_hi:[1,0]
	v_pk_mul_f32 v[160:161], v[52:53], v[150:151] op_sel_hi:[1,0]
	v_mul_f32_e32 v166, v163, v163
	v_mul_f32_e32 v159, v161, v161
	v_pk_mul_f32 v[150:151], v[48:49], v[150:151] op_sel_hi:[1,0]
	v_fmac_f32_e32 v159, v160, v160
	v_fmac_f32_e32 v166, v162, v162
	v_add_f32_e32 v159, v159, v166
	v_mul_f32_e32 v166, v151, v151
	v_fmac_f32_e32 v166, v150, v150
	v_add_f32_e32 v159, v166, v159
	v_mul_f32_e32 v166, v165, v165
	v_fmac_f32_e32 v166, v164, v164
	v_add_f32_e32 v159, v166, v159
	v_add_f32_e32 v147, v147, v159
	v_cvt_pk_bf16_f32 v160, v160, v161
	v_cvt_pk_bf16_f32 v161, v162, v163
	v_cvt_pk_bf16_f32 v162, v150, v151
	v_mov_b32_e32 v150, v147
	s_nop 1
	v_permlane16_swap_b32_e32 v147, v150
	v_add_f32_e32 v147, v147, v150
	v_mov_b32_e32 v150, v147
	s_nop 1
	v_permlane32_swap_b32_e32 v147, v150
	v_cvt_pk_bf16_f32 v163, v164, v165
	global_store_dwordx4 v[152:153], v[160:163], off offset:256
	s_and_saveexec_b64 s[10:11], s[6:7]
	s_cbranch_execz .LBB0_517
	v_add_f32_e32 v147, v147, v150
	global_atomic_add_f32 v[148:149], v147, off offset:512
.LBB0_517:
	s_or_b64 exec, exec, s[10:11]
	v_add_u32_e32 v152, 0x90, v146
	v_ashrrev_i32_e32 v153, 31, v152
	v_lshl_add_u64 v[150:151], v[152:153], 2, s[24:25]
	v_lshlrev_b64 v[152:153], 10, v[152:153]
	v_lshl_add_u64 v[152:153], v[144:145], 0, v[152:153]
	v_fmamk_f32 v147, v245, 0x3a000000, v197
	v_cmp_gt_f32_e32 vcc, s36, v147
	v_mul_f32_e32 v150, 0x4f800000, v147
	s_nop 0
	v_cndmask_b32_e32 v147, v147, v150, vcc
	v_sqrt_f32_e32 v150, v147
	s_nop 0
	v_add_u32_e32 v151, -1, v150
	v_fma_f32 v159, -v151, v150, v147
	v_cmp_ge_f32_e64 s[10:11], 0, v159
	v_add_u32_e32 v159, 1, v150
	s_nop 0
	v_cndmask_b32_e64 v151, v150, v151, s[10:11]
	v_fma_f32 v150, -v159, v150, v147
	v_cmp_lt_f32_e64 s[10:11], 0, v150
	s_nop 1
	v_cndmask_b32_e64 v150, v151, v159, s[10:11]
	v_mul_f32_e32 v151, 0x37800000, v150
	v_cndmask_b32_e32 v150, v150, v151, vcc
	v_cmp_class_f32_e32 vcc, v147, v198
	s_nop 1
	v_cndmask_b32_e32 v147, v150, v147, vcc
	v_div_scale_f32 v150, s[10:11], v147, v147, 1.0
	v_rcp_f32_e32 v151, v150
	s_nop 0
	v_fma_f32 v159, -v150, v151, 1.0
	v_fmac_f32_e32 v151, v159, v151
	v_div_scale_f32 v159, vcc, 1.0, v147, 1.0
	v_mul_f32_e32 v160, v159, v151
	v_fma_f32 v161, -v150, v160, v159
	v_fmac_f32_e32 v160, v161, v151
	v_fma_f32 v150, -v150, v160, v159
	v_div_fmas_f32 v150, v150, v151, v160
	v_div_fixup_f32 v150, v150, v147, 1.0
	v_pk_mul_f32 v[162:163], v[46:47], v[150:151] op_sel_hi:[1,0]
	v_pk_mul_f32 v[160:161], v[44:45], v[150:151] op_sel_hi:[1,0]
	v_pk_mul_f32 v[164:165], v[42:43], v[150:151] op_sel_hi:[1,0]
	v_pk_mul_f32 v[166:167], v[40:41], v[150:151] op_sel_hi:[1,0]
	v_mul_f32_e32 v147, v161, v161
	v_mul_f32_e32 v151, v163, v163
	v_fmac_f32_e32 v147, v160, v160
	v_fmac_f32_e32 v151, v162, v162
	v_add_f32_e32 v147, v147, v151
	v_mul_f32_e32 v151, v167, v167
	v_fmac_f32_e32 v151, v166, v166
	v_add_f32_e32 v147, v151, v147
	v_mul_f32_e32 v151, v165, v165
	v_fmac_f32_e32 v151, v164, v164
	v_cvt_pk_bf16_f32 v160, v160, v161
	v_cvt_pk_bf16_f32 v161, v162, v163
	v_cvt_pk_bf16_f32 v162, v166, v167
	v_cvt_pk_bf16_f32 v163, v164, v165
	global_store_dwordx4 v[152:153], v[160:163], off
	v_add_f32_e32 v147, v151, v147
	v_pk_mul_f32 v[164:165], v[34:35], v[150:151] op_sel_hi:[1,0]
	v_pk_mul_f32 v[162:163], v[38:39], v[150:151] op_sel_hi:[1,0]
	v_pk_mul_f32 v[160:161], v[36:37], v[150:151] op_sel_hi:[1,0]
	v_mul_f32_e32 v166, v163, v163
	v_mul_f32_e32 v159, v161, v161
	v_pk_mul_f32 v[150:151], v[32:33], v[150:151] op_sel_hi:[1,0]
	v_fmac_f32_e32 v159, v160, v160
	v_fmac_f32_e32 v166, v162, v162
	v_add_f32_e32 v159, v159, v166
	v_mul_f32_e32 v166, v151, v151
	v_fmac_f32_e32 v166, v150, v150
	v_add_f32_e32 v159, v166, v159
	v_mul_f32_e32 v166, v165, v165
	v_fmac_f32_e32 v166, v164, v164
	v_add_f32_e32 v159, v166, v159
	v_add_f32_e32 v147, v147, v159
	v_cvt_pk_bf16_f32 v160, v160, v161
	v_cvt_pk_bf16_f32 v161, v162, v163
	v_cvt_pk_bf16_f32 v162, v150, v151
	v_mov_b32_e32 v150, v147
	s_nop 1
	v_permlane16_swap_b32_e32 v147, v150
	v_add_f32_e32 v147, v147, v150
	v_mov_b32_e32 v150, v147
	s_nop 1
	v_permlane32_swap_b32_e32 v147, v150
	v_cvt_pk_bf16_f32 v163, v164, v165
	global_store_dwordx4 v[152:153], v[160:163], off offset:256
	s_and_saveexec_b64 s[10:11], s[6:7]
	s_cbranch_execz .LBB0_519
	v_add_f32_e32 v147, v147, v150
	global_atomic_add_f32 v[148:149], v147, off offset:576
.LBB0_519:
	s_or_b64 exec, exec, s[10:11]
	v_add_u32_e32 v152, 0xa0, v146
	v_ashrrev_i32_e32 v153, 31, v152
	v_lshl_add_u64 v[150:151], v[152:153], 2, s[24:25]
	v_lshlrev_b64 v[152:153], 10, v[152:153]
	v_lshl_add_u64 v[152:153], v[144:145], 0, v[152:153]
	v_fmamk_f32 v147, v246, 0x3a000000, v197
	v_cmp_gt_f32_e32 vcc, s36, v147
	v_mul_f32_e32 v150, 0x4f800000, v147
	s_nop 0
	v_cndmask_b32_e32 v147, v147, v150, vcc
	v_sqrt_f32_e32 v150, v147
	s_nop 0
	v_add_u32_e32 v151, -1, v150
	v_fma_f32 v159, -v151, v150, v147
	v_cmp_ge_f32_e64 s[10:11], 0, v159
	v_add_u32_e32 v159, 1, v150
	s_nop 0
	v_cndmask_b32_e64 v151, v150, v151, s[10:11]
	v_fma_f32 v150, -v159, v150, v147
	v_cmp_lt_f32_e64 s[10:11], 0, v150
	s_nop 1
	v_cndmask_b32_e64 v150, v151, v159, s[10:11]
	v_mul_f32_e32 v151, 0x37800000, v150
	v_cndmask_b32_e32 v150, v150, v151, vcc
	v_cmp_class_f32_e32 vcc, v147, v198
	s_nop 1
	v_cndmask_b32_e32 v147, v150, v147, vcc
	v_div_scale_f32 v150, s[10:11], v147, v147, 1.0
	v_rcp_f32_e32 v151, v150
	s_nop 0
	v_fma_f32 v159, -v150, v151, 1.0
	v_fmac_f32_e32 v151, v159, v151
	v_div_scale_f32 v159, vcc, 1.0, v147, 1.0
	v_mul_f32_e32 v160, v159, v151
	v_fma_f32 v161, -v150, v160, v159
	v_fmac_f32_e32 v160, v161, v151
	v_fma_f32 v150, -v150, v160, v159
	v_div_fmas_f32 v150, v150, v151, v160
	v_div_fixup_f32 v150, v150, v147, 1.0
	v_pk_mul_f32 v[162:163], v[30:31], v[150:151] op_sel_hi:[1,0]
	v_pk_mul_f32 v[160:161], v[28:29], v[150:151] op_sel_hi:[1,0]
	v_pk_mul_f32 v[164:165], v[26:27], v[150:151] op_sel_hi:[1,0]
	v_pk_mul_f32 v[166:167], v[24:25], v[150:151] op_sel_hi:[1,0]
	v_mul_f32_e32 v147, v161, v161
	v_mul_f32_e32 v151, v163, v163
	v_fmac_f32_e32 v147, v160, v160
	v_fmac_f32_e32 v151, v162, v162
	v_add_f32_e32 v147, v147, v151
	v_mul_f32_e32 v151, v167, v167
	v_fmac_f32_e32 v151, v166, v166
	v_add_f32_e32 v147, v151, v147
	v_mul_f32_e32 v151, v165, v165
	v_fmac_f32_e32 v151, v164, v164
	v_cvt_pk_bf16_f32 v160, v160, v161
	v_cvt_pk_bf16_f32 v161, v162, v163
	v_cvt_pk_bf16_f32 v162, v166, v167
	v_cvt_pk_bf16_f32 v163, v164, v165
	global_store_dwordx4 v[152:153], v[160:163], off
	v_add_f32_e32 v147, v151, v147
	v_pk_mul_f32 v[164:165], v[18:19], v[150:151] op_sel_hi:[1,0]
	v_pk_mul_f32 v[162:163], v[22:23], v[150:151] op_sel_hi:[1,0]
	v_pk_mul_f32 v[160:161], v[20:21], v[150:151] op_sel_hi:[1,0]
	v_mul_f32_e32 v166, v163, v163
	v_mul_f32_e32 v159, v161, v161
	v_pk_mul_f32 v[150:151], v[16:17], v[150:151] op_sel_hi:[1,0]
	v_fmac_f32_e32 v159, v160, v160
	v_fmac_f32_e32 v166, v162, v162
	v_add_f32_e32 v159, v159, v166
	v_mul_f32_e32 v166, v151, v151
	v_fmac_f32_e32 v166, v150, v150
	v_add_f32_e32 v159, v166, v159
	v_mul_f32_e32 v166, v165, v165
	v_fmac_f32_e32 v166, v164, v164
	v_add_f32_e32 v159, v166, v159
	v_add_f32_e32 v147, v147, v159
	v_cvt_pk_bf16_f32 v160, v160, v161
	v_cvt_pk_bf16_f32 v161, v162, v163
	v_cvt_pk_bf16_f32 v162, v150, v151
	v_mov_b32_e32 v150, v147
	s_nop 1
	v_permlane16_swap_b32_e32 v147, v150
	v_add_f32_e32 v147, v147, v150
	v_mov_b32_e32 v150, v147
	s_nop 1
	v_permlane32_swap_b32_e32 v147, v150
	v_cvt_pk_bf16_f32 v163, v164, v165
	global_store_dwordx4 v[152:153], v[160:163], off offset:256
	s_and_saveexec_b64 s[10:11], s[6:7]
	s_cbranch_execz .LBB0_521
	v_add_f32_e32 v147, v147, v150
	global_atomic_add_f32 v[148:149], v147, off offset:640
.LBB0_521:
	s_or_b64 exec, exec, s[10:11]
	v_add_u32_e32 v150, 0xb0, v146
	v_ashrrev_i32_e32 v151, 31, v150
	v_lshl_add_u64 v[146:147], v[150:151], 2, s[24:25]
	v_lshlrev_b64 v[150:151], 10, v[150:151]
	v_lshl_add_u64 v[144:145], v[144:145], 0, v[150:151]
	v_fmamk_f32 v146, v247, 0x3a000000, v197
	v_cmp_gt_f32_e32 vcc, s36, v146
	v_mul_f32_e32 v147, 0x4f800000, v146
	s_nop 0
	v_cndmask_b32_e32 v146, v146, v147, vcc
	v_sqrt_f32_e32 v147, v146
	s_nop 0
	v_add_u32_e32 v152, -1, v147
	v_fma_f32 v153, -v152, v147, v146
	v_cmp_ge_f32_e64 s[10:11], 0, v153
	v_add_u32_e32 v153, 1, v147
	s_nop 0
	v_cndmask_b32_e64 v152, v147, v152, s[10:11]
	v_fma_f32 v147, -v153, v147, v146
	v_cmp_lt_f32_e64 s[10:11], 0, v147
	s_nop 1
	v_cndmask_b32_e64 v147, v152, v153, s[10:11]
	v_mul_f32_e32 v152, 0x37800000, v147
	v_cndmask_b32_e32 v147, v147, v152, vcc
	v_cmp_class_f32_e32 vcc, v146, v198
	s_nop 1
	v_cndmask_b32_e32 v146, v147, v146, vcc
	v_div_scale_f32 v147, s[10:11], v146, v146, 1.0
	v_rcp_f32_e32 v152, v147
	s_nop 0
	v_fma_f32 v153, -v147, v152, 1.0
	v_fmac_f32_e32 v152, v153, v152
	v_div_scale_f32 v153, vcc, 1.0, v146, 1.0
	v_mul_f32_e32 v159, v153, v152
	v_fma_f32 v160, -v147, v159, v153
	v_fmac_f32_e32 v159, v160, v152
	v_fma_f32 v147, -v147, v159, v153
	v_div_fmas_f32 v147, v147, v152, v159
	v_div_fixup_f32 v146, v147, v146, 1.0
	v_pk_mul_f32 v[152:153], v[14:15], v[146:147] op_sel_hi:[1,0]
	v_pk_mul_f32 v[150:151], v[12:13], v[146:147] op_sel_hi:[1,0]
	v_pk_mul_f32 v[160:161], v[10:11], v[146:147] op_sel_hi:[1,0]
	v_pk_mul_f32 v[162:163], v[8:9], v[146:147] op_sel_hi:[1,0]
	v_mul_f32_e32 v147, v151, v151
	v_mul_f32_e32 v159, v153, v153
	v_fmac_f32_e32 v147, v150, v150
	v_fmac_f32_e32 v159, v152, v152
	v_add_f32_e32 v147, v147, v159
	v_mul_f32_e32 v159, v163, v163
	v_fmac_f32_e32 v159, v162, v162
	v_add_f32_e32 v147, v159, v147
	v_cvt_pk_bf16_f32 v150, v150, v151
	v_cvt_pk_bf16_f32 v151, v152, v153
	v_cvt_pk_bf16_f32 v152, v162, v163
	v_cvt_pk_bf16_f32 v153, v160, v161
	v_mul_f32_e32 v159, v161, v161
	global_store_dwordx4 v[144:145], v[150:153], off
	v_fmac_f32_e32 v159, v160, v160
	v_add_f32_e32 v159, v159, v147
	v_pk_mul_f32 v[152:153], v[6:7], v[146:147] op_sel_hi:[1,0]
	v_pk_mul_f32 v[150:151], v[4:5], v[146:147] op_sel_hi:[1,0]
	v_mul_f32_e32 v163, v153, v153
	v_mul_f32_e32 v162, v151, v151
	v_pk_mul_f32 v[160:161], v[2:3], v[146:147] op_sel_hi:[1,0]
	v_pk_mul_f32 v[146:147], v[0:1], v[146:147] op_sel_hi:[1,0]
	v_fmac_f32_e32 v162, v150, v150
	v_fmac_f32_e32 v163, v152, v152
	v_add_f32_e32 v162, v162, v163
	v_mul_f32_e32 v163, v147, v147
	v_fmac_f32_e32 v163, v146, v146
	v_add_f32_e32 v162, v163, v162
	v_mul_f32_e32 v163, v161, v161
	v_fmac_f32_e32 v163, v160, v160
	v_add_f32_e32 v162, v163, v162
	v_add_f32_e32 v159, v159, v162
	v_cvt_pk_bf16_f32 v150, v150, v151
	v_cvt_pk_bf16_f32 v151, v152, v153
	v_cvt_pk_bf16_f32 v152, v146, v147
	v_cvt_pk_bf16_f32 v153, v160, v161
	global_store_dwordx4 v[144:145], v[150:153], off offset:256
	v_mov_b32_e32 v144, v159
	s_nop 1
	v_permlane16_swap_b32_e32 v159, v144
	v_add_f32_e32 v144, v159, v144
	v_mov_b32_e32 v145, v144
	s_nop 1
	v_permlane32_swap_b32_e32 v144, v145
	s_and_saveexec_b64 s[10:11], s[6:7]
	s_cbranch_execz .LBB0_523
	v_add_f32_e32 v144, v144, v145
	global_atomic_add_f32 v[148:149], v144, off offset:704

.LBB0_524:
	s_and_b64 vcc, exec, s[10:11]
	s_cbranch_vccz .LBB0_543
	s_andn2_b64 vcc, exec, s[30:31]
	s_cbranch_vccnz .LBB0_543
	v_lshl_add_u32 v144, s82, 8, v154
	v_ashrrev_i32_e32 v145, 31, v144
	v_lshl_add_u64 v[146:147], v[144:145], 2, s[24:25]
	global_load_dword v240, v[146:147], off
	global_load_dword v241, v[146:147], off offset:64
	global_load_dword v242, v[146:147], off offset:128
	global_load_dword v243, v[146:147], off offset:192
	global_load_dword v244, v[146:147], off offset:512
	global_load_dword v245, v[146:147], off offset:576
	global_load_dword v246, v[146:147], off offset:640
	global_load_dword v247, v[146:147], off offset:704
	s_waitcnt vmcnt(0)
	v_fmamk_f32 v146, v240, 0x3a000000, v197
	v_mul_f32_e32 v147, 0x4f800000, v146
	v_cmp_gt_f32_e32 vcc, s36, v146
	s_nop 1
	v_cndmask_b32_e32 v148, v146, v147, vcc
	v_sqrt_f32_e32 v149, v148
	v_lshlrev_b64 v[146:147], 8, v[144:145]
	v_lshl_add_u64 v[160:161], v[136:137], 0, v[146:147]
	v_add_u32_e32 v150, -1, v149
	v_add_u32_e32 v151, 1, v149
	v_fma_f32 v152, -v150, v149, v148
	v_fma_f32 v153, -v151, v149, v148
	v_cmp_ge_f32_e64 s[10:11], 0, v152
	s_nop 1
	v_cndmask_b32_e64 v149, v149, v150, s[10:11]
	v_cmp_lt_f32_e64 s[10:11], 0, v153
	s_nop 1
	v_cndmask_b32_e64 v149, v149, v151, s[10:11]
	v_mul_f32_e32 v150, 0x37800000, v149
	v_cndmask_b32_e32 v149, v149, v150, vcc
	v_cmp_class_f32_e32 vcc, v148, v198
	s_nop 1
	v_cndmask_b32_e32 v148, v149, v148, vcc
	v_div_scale_f32 v149, s[10:11], v148, v148, 1.0
	v_rcp_f32_e32 v150, v149
	v_div_scale_f32 v146, vcc, 1.0, v148, 1.0
	v_fma_f32 v147, -v149, v150, 1.0
	v_fmac_f32_e32 v150, v147, v150
	v_mul_f32_e32 v147, v146, v150
	v_fma_f32 v151, -v149, v147, v146
	v_fmac_f32_e32 v147, v151, v150
	v_fma_f32 v146, -v149, v147, v146
	v_div_fmas_f32 v146, v146, v150, v147
	v_div_fixup_f32 v150, v146, v148, 1.0
	v_pk_mul_f32 v[148:149], v[126:127], v[150:151] op_sel_hi:[1,0]
	v_pk_mul_f32 v[146:147], v[124:125], v[150:151] op_sel_hi:[1,0]
	v_pk_mul_f32 v[152:153], v[122:123], v[150:151] op_sel_hi:[1,0]
	v_pk_mul_f32 v[150:151], v[120:121], v[150:151] op_sel_hi:[1,0]
	global_store_dwordx4 v[160:161], v[146:149], off
	global_store_dwordx4 v[160:161], v[150:153], off offset:16
	s_nop 0
	v_mul_f32_e32 v147, v147, v147
	v_mul_f32_e32 v149, v149, v149
	v_mul_f32_e32 v151, v151, v151
	v_fmac_f32_e32 v147, v146, v146
	v_fmac_f32_e32 v149, v148, v148
	v_mul_f32_e32 v153, v153, v153
	v_fmac_f32_e32 v151, v150, v150
	v_add_f32_e32 v146, v147, v149
	v_fmac_f32_e32 v153, v152, v152
	v_add_f32_e32 v146, v151, v146
	v_add_f32_e32 v146, v153, v146
	v_mov_b32_e32 v147, v146
	s_nop 1
	v_permlane16_swap_b32_e32 v146, v147
	v_add_f32_e32 v146, v146, v147
	v_mov_b32_e32 v147, v146
	s_nop 1
	v_permlane32_swap_b32_e32 v146, v147
	s_and_saveexec_b64 s[10:11], s[6:7]
	s_cbranch_execz .LBB0_528
	v_lshl_add_u64 v[148:149], v[144:145], 2, s[26:27]
	v_add_f32_e32 v145, v146, v147
	global_atomic_add_f32 v[148:149], v145, off
.LBB0_528:
	s_or_b64 exec, exec, s[10:11]
	v_or_b32_e32 v146, 16, v144
	v_ashrrev_i32_e32 v147, 31, v146
	v_lshl_add_u64 v[148:149], v[146:147], 2, s[24:25]
	v_fmamk_f32 v145, v241, 0x3a000000, v197
	v_mul_f32_e32 v148, 0x4f800000, v145
	v_cmp_gt_f32_e32 vcc, s36, v145
	s_nop 1
	v_cndmask_b32_e32 v145, v145, v148, vcc
	v_sqrt_f32_e32 v150, v145
	v_lshlrev_b64 v[148:149], 8, v[146:147]
	v_add_u32_e32 v151, -1, v150
	v_add_u32_e32 v152, 1, v150
	v_fma_f32 v153, -v151, v150, v145
	v_fma_f32 v159, -v152, v150, v145
	v_cmp_ge_f32_e64 s[10:11], 0, v153
	s_nop 1
	v_cndmask_b32_e64 v150, v150, v151, s[10:11]
	v_cmp_lt_f32_e64 s[10:11], 0, v159
	s_nop 1
	v_cndmask_b32_e64 v150, v150, v152, s[10:11]
	v_mul_f32_e32 v151, 0x37800000, v150
	v_cndmask_b32_e32 v150, v150, v151, vcc
	v_cmp_class_f32_e32 vcc, v145, v198
	v_lshl_add_u64 v[152:153], v[136:137], 0, v[148:149]
	s_nop 0
	v_cndmask_b32_e32 v145, v150, v145, vcc
	v_div_scale_f32 v150, s[10:11], v145, v145, 1.0
	v_rcp_f32_e32 v151, v150
	v_div_scale_f32 v148, vcc, 1.0, v145, 1.0
	v_fma_f32 v149, -v150, v151, 1.0
	v_fmac_f32_e32 v151, v149, v151
	v_mul_f32_e32 v149, v148, v151
	v_fma_f32 v159, -v150, v149, v148
	v_fmac_f32_e32 v149, v159, v151
	v_fma_f32 v148, -v150, v149, v148
	v_div_fmas_f32 v148, v148, v151, v149
	v_div_fixup_f32 v160, v148, v145, 1.0
	v_pk_mul_f32 v[150:151], v[110:111], v[160:161] op_sel_hi:[1,0]
	v_pk_mul_f32 v[148:149], v[108:109], v[160:161] op_sel_hi:[1,0]
	v_pk_mul_f32 v[162:163], v[106:107], v[160:161] op_sel_hi:[1,0]
	v_pk_mul_f32 v[160:161], v[104:105], v[160:161] op_sel_hi:[1,0]
	global_store_dwordx4 v[152:153], v[148:151], off
	global_store_dwordx4 v[152:153], v[160:163], off offset:16
	v_mul_f32_e32 v145, v149, v149
	v_mul_f32_e32 v149, v151, v151
	v_mul_f32_e32 v151, v161, v161
	v_fmac_f32_e32 v145, v148, v148
	v_fmac_f32_e32 v149, v150, v150
	v_mul_f32_e32 v152, v163, v163
	v_fmac_f32_e32 v151, v160, v160
	v_add_f32_e32 v145, v145, v149
	v_fmac_f32_e32 v152, v162, v162
	v_add_f32_e32 v145, v151, v145
	v_add_f32_e32 v145, v152, v145
	v_mov_b32_e32 v148, v145
	s_nop 1
	v_permlane16_swap_b32_e32 v145, v148
	v_add_f32_e32 v145, v145, v148
	v_mov_b32_e32 v148, v145
	s_nop 1
	v_permlane32_swap_b32_e32 v145, v148
	s_and_saveexec_b64 s[10:11], s[6:7]
	s_cbranch_execz .LBB0_530
	v_lshl_add_u64 v[146:147], v[146:147], 2, s[26:27]
	v_add_f32_e32 v145, v145, v148
	global_atomic_add_f32 v[146:147], v145, off
.LBB0_530:
	s_or_b64 exec, exec, s[10:11]
	v_or_b32_e32 v146, 32, v144
	v_ashrrev_i32_e32 v147, 31, v146
	v_lshl_add_u64 v[148:149], v[146:147], 2, s[24:25]
	v_fmamk_f32 v145, v242, 0x3a000000, v197
	v_mul_f32_e32 v148, 0x4f800000, v145
	v_cmp_gt_f32_e32 vcc, s36, v145
	s_nop 1
	v_cndmask_b32_e32 v145, v145, v148, vcc
	v_sqrt_f32_e32 v150, v145
	v_lshlrev_b64 v[148:149], 8, v[146:147]
	v_add_u32_e32 v151, -1, v150
	v_add_u32_e32 v152, 1, v150
	v_fma_f32 v153, -v151, v150, v145
	v_fma_f32 v159, -v152, v150, v145
	v_cmp_ge_f32_e64 s[10:11], 0, v153
	s_nop 1
	v_cndmask_b32_e64 v150, v150, v151, s[10:11]
	v_cmp_lt_f32_e64 s[10:11], 0, v159
	s_nop 1
	v_cndmask_b32_e64 v150, v150, v152, s[10:11]
	v_mul_f32_e32 v151, 0x37800000, v150
	v_cndmask_b32_e32 v150, v150, v151, vcc
	v_cmp_class_f32_e32 vcc, v145, v198
	v_lshl_add_u64 v[152:153], v[136:137], 0, v[148:149]
	s_nop 0
	v_cndmask_b32_e32 v145, v150, v145, vcc
	v_div_scale_f32 v150, s[10:11], v145, v145, 1.0
	v_rcp_f32_e32 v151, v150
	v_div_scale_f32 v148, vcc, 1.0, v145, 1.0
	v_fma_f32 v149, -v150, v151, 1.0
	v_fmac_f32_e32 v151, v149, v151
	v_mul_f32_e32 v149, v148, v151
	v_fma_f32 v159, -v150, v149, v148
	v_fmac_f32_e32 v149, v159, v151
	v_fma_f32 v148, -v150, v149, v148
	v_div_fmas_f32 v148, v148, v151, v149
	v_div_fixup_f32 v160, v148, v145, 1.0
	v_pk_mul_f32 v[150:151], v[94:95], v[160:161] op_sel_hi:[1,0]
	v_pk_mul_f32 v[148:149], v[92:93], v[160:161] op_sel_hi:[1,0]
	v_pk_mul_f32 v[162:163], v[90:91], v[160:161] op_sel_hi:[1,0]
	v_pk_mul_f32 v[160:161], v[88:89], v[160:161] op_sel_hi:[1,0]
	global_store_dwordx4 v[152:153], v[148:151], off
	global_store_dwordx4 v[152:153], v[160:163], off offset:16
	v_mul_f32_e32 v145, v149, v149
	v_mul_f32_e32 v149, v151, v151
	v_mul_f32_e32 v151, v161, v161
	v_fmac_f32_e32 v145, v148, v148
	v_fmac_f32_e32 v149, v150, v150
	v_mul_f32_e32 v152, v163, v163
	v_fmac_f32_e32 v151, v160, v160
	v_add_f32_e32 v145, v145, v149
	v_fmac_f32_e32 v152, v162, v162
	v_add_f32_e32 v145, v151, v145
	v_add_f32_e32 v145, v152, v145
	v_mov_b32_e32 v148, v145
	s_nop 1
	v_permlane16_swap_b32_e32 v145, v148
	v_add_f32_e32 v145, v145, v148
	v_mov_b32_e32 v148, v145
	s_nop 1
	v_permlane32_swap_b32_e32 v145, v148
	s_and_saveexec_b64 s[10:11], s[6:7]
	s_cbranch_execz .LBB0_532
	v_lshl_add_u64 v[146:147], v[146:147], 2, s[26:27]
	v_add_f32_e32 v145, v145, v148
	global_atomic_add_f32 v[146:147], v145, off
.LBB0_532:
	s_or_b64 exec, exec, s[10:11]
	v_or_b32_e32 v146, 48, v144
	v_ashrrev_i32_e32 v147, 31, v146
	v_lshl_add_u64 v[148:149], v[146:147], 2, s[24:25]
	v_fmamk_f32 v145, v243, 0x3a000000, v197
	v_mul_f32_e32 v148, 0x4f800000, v145
	v_cmp_gt_f32_e32 vcc, s36, v145
	s_nop 1
	v_cndmask_b32_e32 v145, v145, v148, vcc
	v_sqrt_f32_e32 v150, v145
	v_lshlrev_b64 v[148:149], 8, v[146:147]
	v_add_u32_e32 v151, -1, v150
	v_add_u32_e32 v152, 1, v150
	v_fma_f32 v153, -v151, v150, v145
	v_fma_f32 v159, -v152, v150, v145
	v_cmp_ge_f32_e64 s[10:11], 0, v153
	s_nop 1
	v_cndmask_b32_e64 v150, v150, v151, s[10:11]
	v_cmp_lt_f32_e64 s[10:11], 0, v159
	s_nop 1
	v_cndmask_b32_e64 v150, v150, v152, s[10:11]
	v_mul_f32_e32 v151, 0x37800000, v150
	v_cndmask_b32_e32 v150, v150, v151, vcc
	v_cmp_class_f32_e32 vcc, v145, v198
	v_lshl_add_u64 v[152:153], v[136:137], 0, v[148:149]
	s_nop 0
	v_cndmask_b32_e32 v145, v150, v145, vcc
	v_div_scale_f32 v150, s[10:11], v145, v145, 1.0
	v_rcp_f32_e32 v151, v150
	v_div_scale_f32 v148, vcc, 1.0, v145, 1.0
	v_fma_f32 v149, -v150, v151, 1.0
	v_fmac_f32_e32 v151, v149, v151
	v_mul_f32_e32 v149, v148, v151
	v_fma_f32 v159, -v150, v149, v148
	v_fmac_f32_e32 v149, v159, v151
	v_fma_f32 v148, -v150, v149, v148
	v_div_fmas_f32 v148, v148, v151, v149
	v_div_fixup_f32 v160, v148, v145, 1.0
	v_pk_mul_f32 v[150:151], v[78:79], v[160:161] op_sel_hi:[1,0]
	v_pk_mul_f32 v[148:149], v[76:77], v[160:161] op_sel_hi:[1,0]
	v_pk_mul_f32 v[162:163], v[74:75], v[160:161] op_sel_hi:[1,0]
	v_pk_mul_f32 v[160:161], v[72:73], v[160:161] op_sel_hi:[1,0]
	global_store_dwordx4 v[152:153], v[148:151], off
	global_store_dwordx4 v[152:153], v[160:163], off offset:16
	v_mul_f32_e32 v145, v149, v149
	v_mul_f32_e32 v149, v151, v151
	v_mul_f32_e32 v151, v161, v161
	v_fmac_f32_e32 v145, v148, v148
	v_fmac_f32_e32 v149, v150, v150
	v_mul_f32_e32 v152, v163, v163
	v_fmac_f32_e32 v151, v160, v160
	v_add_f32_e32 v145, v145, v149
	v_fmac_f32_e32 v152, v162, v162
	v_add_f32_e32 v145, v151, v145
	v_add_f32_e32 v145, v152, v145
	v_mov_b32_e32 v148, v145
	s_nop 1
	v_permlane16_swap_b32_e32 v145, v148
	v_add_f32_e32 v145, v145, v148
	v_mov_b32_e32 v148, v145
	s_nop 1
	v_permlane32_swap_b32_e32 v145, v148
	s_and_saveexec_b64 s[10:11], s[6:7]
	s_cbranch_execz .LBB0_534
	v_lshl_add_u64 v[146:147], v[146:147], 2, s[26:27]
	v_add_f32_e32 v145, v145, v148
	global_atomic_add_f32 v[146:147], v145, off
.LBB0_534:
	s_or_b64 exec, exec, s[10:11]
	v_add_u32_e32 v146, 0x80, v144
	v_ashrrev_i32_e32 v147, 31, v146
	v_lshl_add_u64 v[148:149], v[146:147], 2, s[24:25]
	v_fmamk_f32 v145, v244, 0x3a000000, v197
	v_mul_f32_e32 v148, 0x4f800000, v145
	v_cmp_gt_f32_e32 vcc, s36, v145
	s_nop 1
	v_cndmask_b32_e32 v145, v145, v148, vcc
	v_sqrt_f32_e32 v150, v145
	v_lshlrev_b64 v[148:149], 8, v[146:147]
	v_add_u32_e32 v151, -1, v150
	v_add_u32_e32 v152, 1, v150
	v_fma_f32 v153, -v151, v150, v145
	v_fma_f32 v159, -v152, v150, v145
	v_cmp_ge_f32_e64 s[10:11], 0, v153
	s_nop 1
	v_cndmask_b32_e64 v150, v150, v151, s[10:11]
	v_cmp_lt_f32_e64 s[10:11], 0, v159
	s_nop 1
	v_cndmask_b32_e64 v150, v150, v152, s[10:11]
	v_mul_f32_e32 v151, 0x37800000, v150
	v_cndmask_b32_e32 v150, v150, v151, vcc
	v_cmp_class_f32_e32 vcc, v145, v198
	v_lshl_add_u64 v[152:153], v[136:137], 0, v[148:149]
	s_nop 0
	v_cndmask_b32_e32 v145, v150, v145, vcc
	v_div_scale_f32 v150, s[10:11], v145, v145, 1.0
	v_rcp_f32_e32 v151, v150
	v_div_scale_f32 v148, vcc, 1.0, v145, 1.0
	v_fma_f32 v149, -v150, v151, 1.0
	v_fmac_f32_e32 v151, v149, v151
	v_mul_f32_e32 v149, v148, v151
	v_fma_f32 v159, -v150, v149, v148
	v_fmac_f32_e32 v149, v159, v151
	v_fma_f32 v148, -v150, v149, v148
	v_div_fmas_f32 v148, v148, v151, v149
	v_div_fixup_f32 v160, v148, v145, 1.0
	v_pk_mul_f32 v[150:151], v[62:63], v[160:161] op_sel_hi:[1,0]
	v_pk_mul_f32 v[148:149], v[60:61], v[160:161] op_sel_hi:[1,0]
	v_pk_mul_f32 v[162:163], v[58:59], v[160:161] op_sel_hi:[1,0]
	v_pk_mul_f32 v[160:161], v[56:57], v[160:161] op_sel_hi:[1,0]
	global_store_dwordx4 v[152:153], v[148:151], off
	global_store_dwordx4 v[152:153], v[160:163], off offset:16
	v_mul_f32_e32 v145, v149, v149
	v_mul_f32_e32 v149, v151, v151
	v_mul_f32_e32 v151, v161, v161
	v_fmac_f32_e32 v145, v148, v148
	v_fmac_f32_e32 v149, v150, v150
	v_mul_f32_e32 v152, v163, v163
	v_fmac_f32_e32 v151, v160, v160
	v_add_f32_e32 v145, v145, v149
	v_fmac_f32_e32 v152, v162, v162
	v_add_f32_e32 v145, v151, v145
	v_add_f32_e32 v145, v152, v145
	v_mov_b32_e32 v148, v145
	s_nop 1
	v_permlane16_swap_b32_e32 v145, v148
	v_add_f32_e32 v145, v145, v148
	v_mov_b32_e32 v148, v145
	s_nop 1
	v_permlane32_swap_b32_e32 v145, v148
	s_and_saveexec_b64 s[10:11], s[6:7]
	s_cbranch_execz .LBB0_536
	v_lshl_add_u64 v[146:147], v[146:147], 2, s[26:27]
	v_add_f32_e32 v145, v145, v148
	global_atomic_add_f32 v[146:147], v145, off
.LBB0_536:
	s_or_b64 exec, exec, s[10:11]
	v_add_u32_e32 v146, 0x90, v144
	v_ashrrev_i32_e32 v147, 31, v146
	v_lshl_add_u64 v[148:149], v[146:147], 2, s[24:25]
	v_fmamk_f32 v145, v245, 0x3a000000, v197
	v_mul_f32_e32 v148, 0x4f800000, v145
	v_cmp_gt_f32_e32 vcc, s36, v145
	s_nop 1
	v_cndmask_b32_e32 v145, v145, v148, vcc
	v_sqrt_f32_e32 v150, v145
	v_lshlrev_b64 v[148:149], 8, v[146:147]
	v_add_u32_e32 v151, -1, v150
	v_add_u32_e32 v152, 1, v150
	v_fma_f32 v153, -v151, v150, v145
	v_fma_f32 v159, -v152, v150, v145
	v_cmp_ge_f32_e64 s[10:11], 0, v153
	s_nop 1
	v_cndmask_b32_e64 v150, v150, v151, s[10:11]
	v_cmp_lt_f32_e64 s[10:11], 0, v159
	s_nop 1
	v_cndmask_b32_e64 v150, v150, v152, s[10:11]
	v_mul_f32_e32 v151, 0x37800000, v150
	v_cndmask_b32_e32 v150, v150, v151, vcc
	v_cmp_class_f32_e32 vcc, v145, v198
	v_lshl_add_u64 v[152:153], v[136:137], 0, v[148:149]
	s_nop 0
	v_cndmask_b32_e32 v145, v150, v145, vcc
	v_div_scale_f32 v150, s[10:11], v145, v145, 1.0
	v_rcp_f32_e32 v151, v150
	v_div_scale_f32 v148, vcc, 1.0, v145, 1.0
	v_fma_f32 v149, -v150, v151, 1.0
	v_fmac_f32_e32 v151, v149, v151
	v_mul_f32_e32 v149, v148, v151
	v_fma_f32 v159, -v150, v149, v148
	v_fmac_f32_e32 v149, v159, v151
	v_fma_f32 v148, -v150, v149, v148
	v_div_fmas_f32 v148, v148, v151, v149
	v_div_fixup_f32 v160, v148, v145, 1.0
	v_pk_mul_f32 v[150:151], v[46:47], v[160:161] op_sel_hi:[1,0]
	v_pk_mul_f32 v[148:149], v[44:45], v[160:161] op_sel_hi:[1,0]
	v_pk_mul_f32 v[162:163], v[42:43], v[160:161] op_sel_hi:[1,0]
	v_pk_mul_f32 v[160:161], v[40:41], v[160:161] op_sel_hi:[1,0]
	global_store_dwordx4 v[152:153], v[148:151], off
	global_store_dwordx4 v[152:153], v[160:163], off offset:16
	v_mul_f32_e32 v145, v149, v149
	v_mul_f32_e32 v149, v151, v151
	v_mul_f32_e32 v151, v161, v161
	v_fmac_f32_e32 v145, v148, v148
	v_fmac_f32_e32 v149, v150, v150
	v_mul_f32_e32 v152, v163, v163
	v_fmac_f32_e32 v151, v160, v160
	v_add_f32_e32 v145, v145, v149
	v_fmac_f32_e32 v152, v162, v162
	v_add_f32_e32 v145, v151, v145
	v_add_f32_e32 v145, v152, v145
	v_mov_b32_e32 v148, v145
	s_nop 1
	v_permlane16_swap_b32_e32 v145, v148
	v_add_f32_e32 v145, v145, v148
	v_mov_b32_e32 v148, v145
	s_nop 1
	v_permlane32_swap_b32_e32 v145, v148
	s_and_saveexec_b64 s[10:11], s[6:7]
	s_cbranch_execz .LBB0_538
	v_lshl_add_u64 v[146:147], v[146:147], 2, s[26:27]
	v_add_f32_e32 v145, v145, v148
	global_atomic_add_f32 v[146:147], v145, off
.LBB0_538:
	s_or_b64 exec, exec, s[10:11]
	v_add_u32_e32 v146, 0xa0, v144
	v_ashrrev_i32_e32 v147, 31, v146
	v_lshl_add_u64 v[148:149], v[146:147], 2, s[24:25]
	v_fmamk_f32 v145, v246, 0x3a000000, v197
	v_mul_f32_e32 v148, 0x4f800000, v145
	v_cmp_gt_f32_e32 vcc, s36, v145
	s_nop 1
	v_cndmask_b32_e32 v145, v145, v148, vcc
	v_sqrt_f32_e32 v150, v145
	v_lshlrev_b64 v[148:149], 8, v[146:147]
	v_add_u32_e32 v151, -1, v150
	v_add_u32_e32 v152, 1, v150
	v_fma_f32 v153, -v151, v150, v145
	v_fma_f32 v159, -v152, v150, v145
	v_cmp_ge_f32_e64 s[10:11], 0, v153
	s_nop 1
	v_cndmask_b32_e64 v150, v150, v151, s[10:11]
	v_cmp_lt_f32_e64 s[10:11], 0, v159
	s_nop 1
	v_cndmask_b32_e64 v150, v150, v152, s[10:11]
	v_mul_f32_e32 v151, 0x37800000, v150
	v_cndmask_b32_e32 v150, v150, v151, vcc
	v_cmp_class_f32_e32 vcc, v145, v198
	v_lshl_add_u64 v[152:153], v[136:137], 0, v[148:149]
	s_nop 0
	v_cndmask_b32_e32 v145, v150, v145, vcc
	v_div_scale_f32 v150, s[10:11], v145, v145, 1.0
	v_rcp_f32_e32 v151, v150
	v_div_scale_f32 v148, vcc, 1.0, v145, 1.0
	v_fma_f32 v149, -v150, v151, 1.0
	v_fmac_f32_e32 v151, v149, v151
	v_mul_f32_e32 v149, v148, v151
	v_fma_f32 v159, -v150, v149, v148
	v_fmac_f32_e32 v149, v159, v151
	v_fma_f32 v148, -v150, v149, v148
	v_div_fmas_f32 v148, v148, v151, v149
	v_div_fixup_f32 v160, v148, v145, 1.0
	v_pk_mul_f32 v[150:151], v[30:31], v[160:161] op_sel_hi:[1,0]
	v_pk_mul_f32 v[148:149], v[28:29], v[160:161] op_sel_hi:[1,0]
	v_pk_mul_f32 v[162:163], v[26:27], v[160:161] op_sel_hi:[1,0]
	v_pk_mul_f32 v[160:161], v[24:25], v[160:161] op_sel_hi:[1,0]
	global_store_dwordx4 v[152:153], v[148:151], off
	global_store_dwordx4 v[152:153], v[160:163], off offset:16
	v_mul_f32_e32 v145, v149, v149
	v_mul_f32_e32 v149, v151, v151
	v_mul_f32_e32 v151, v161, v161
	v_fmac_f32_e32 v145, v148, v148
	v_fmac_f32_e32 v149, v150, v150
	v_mul_f32_e32 v152, v163, v163
	v_fmac_f32_e32 v151, v160, v160
	v_add_f32_e32 v145, v145, v149
	v_fmac_f32_e32 v152, v162, v162
	v_add_f32_e32 v145, v151, v145
	v_add_f32_e32 v145, v152, v145
	v_mov_b32_e32 v148, v145
	s_nop 1
	v_permlane16_swap_b32_e32 v145, v148
	v_add_f32_e32 v145, v145, v148
	v_mov_b32_e32 v148, v145
	s_nop 1
	v_permlane32_swap_b32_e32 v145, v148
	s_and_saveexec_b64 s[10:11], s[6:7]
	s_cbranch_execz .LBB0_540
	v_lshl_add_u64 v[146:147], v[146:147], 2, s[26:27]
	v_add_f32_e32 v145, v145, v148
	global_atomic_add_f32 v[146:147], v145, off
.LBB0_540:
	s_or_b64 exec, exec, s[10:11]
	v_add_u32_e32 v144, 0xb0, v144
	v_ashrrev_i32_e32 v145, 31, v144
	v_lshl_add_u64 v[146:147], v[144:145], 2, s[24:25]
	v_fmamk_f32 v146, v247, 0x3a000000, v197
	v_mul_f32_e32 v147, 0x4f800000, v146
	v_cmp_gt_f32_e32 vcc, s36, v146
	s_nop 1
	v_cndmask_b32_e32 v148, v146, v147, vcc
	v_sqrt_f32_e32 v149, v148
	v_lshlrev_b64 v[146:147], 8, v[144:145]
	v_lshl_add_u64 v[160:161], v[136:137], 0, v[146:147]
	v_add_u32_e32 v150, -1, v149
	v_add_u32_e32 v151, 1, v149
	v_fma_f32 v152, -v150, v149, v148
	v_fma_f32 v153, -v151, v149, v148
	v_cmp_ge_f32_e64 s[10:11], 0, v152
	s_nop 1
	v_cndmask_b32_e64 v149, v149, v150, s[10:11]
	v_cmp_lt_f32_e64 s[10:11], 0, v153
	s_nop 1
	v_cndmask_b32_e64 v149, v149, v151, s[10:11]
	v_mul_f32_e32 v150, 0x37800000, v149
	v_cndmask_b32_e32 v149, v149, v150, vcc
	v_cmp_class_f32_e32 vcc, v148, v198
	s_nop 1
	v_cndmask_b32_e32 v148, v149, v148, vcc
	v_div_scale_f32 v149, s[10:11], v148, v148, 1.0
	v_rcp_f32_e32 v150, v149
	v_div_scale_f32 v146, vcc, 1.0, v148, 1.0
	v_fma_f32 v147, -v149, v150, 1.0
	v_fmac_f32_e32 v150, v147, v150
	v_mul_f32_e32 v147, v146, v150
	v_fma_f32 v151, -v149, v147, v146
	v_fmac_f32_e32 v147, v151, v150
	v_fma_f32 v146, -v149, v147, v146
	v_div_fmas_f32 v146, v146, v150, v147
	v_div_fixup_f32 v150, v146, v148, 1.0
	v_pk_mul_f32 v[148:149], v[14:15], v[150:151] op_sel_hi:[1,0]
	v_pk_mul_f32 v[146:147], v[12:13], v[150:151] op_sel_hi:[1,0]
	v_pk_mul_f32 v[152:153], v[10:11], v[150:151] op_sel_hi:[1,0]
	v_pk_mul_f32 v[150:151], v[8:9], v[150:151] op_sel_hi:[1,0]
	global_store_dwordx4 v[160:161], v[146:149], off
	global_store_dwordx4 v[160:161], v[150:153], off offset:16
	s_nop 0
	v_mul_f32_e32 v147, v147, v147
	v_mul_f32_e32 v149, v149, v149
	v_mul_f32_e32 v151, v151, v151
	v_fmac_f32_e32 v147, v146, v146
	v_fmac_f32_e32 v149, v148, v148
	v_mul_f32_e32 v153, v153, v153
	v_fmac_f32_e32 v151, v150, v150
	v_add_f32_e32 v146, v147, v149
	v_fmac_f32_e32 v153, v152, v152
	v_add_f32_e32 v146, v151, v146
	v_add_f32_e32 v146, v153, v146
	v_mov_b32_e32 v147, v146
	s_nop 1
	v_permlane16_swap_b32_e32 v146, v147
	v_add_f32_e32 v146, v146, v147
	v_mov_b32_e32 v147, v146
	s_nop 1
	v_permlane32_swap_b32_e32 v146, v147
	s_and_saveexec_b64 s[10:11], s[6:7]
	s_cbranch_execz .LBB0_542
	v_lshl_add_u64 v[144:145], v[144:145], 2, s[26:27]
	v_add_f32_e32 v146, v146, v147
	global_atomic_add_f32 v[144:145], v146, off

.LBB0_673:
	s_lshl_b32 s23, s52, 8
	s_add_i32 s23, s23, s49
	v_or_b32_e32 v144, s23, v152
	v_ashrrev_i32_e32 v145, 31, v144
	v_lshl_add_u64 v[150:151], v[144:145], 2, s[18:19]
	global_load_dword v240, v[150:151], off
	global_load_dword v241, v[150:151], off offset:64
	global_load_dword v242, v[150:151], off offset:128
	global_load_dword v243, v[150:151], off offset:192
	v_lshl_or_b32 v140, s4, 8, v154
	v_mul_hi_i32 v141, v140, s69
	v_or_b32_e32 v142, 0x80, v140
	v_lshrrev_b32_e32 v143, 31, v141
	v_ashrrev_i32_e32 v141, 5, v141
	v_mul_hi_i32 v145, v142, s69
	s_ashr_i32 s4, s23, 8
	v_add_u32_e32 v156, v141, v143
	v_lshrrev_b32_e32 v143, 31, v145
	v_ashrrev_i32_e32 v145, 5, v145
	s_and_b32 s4, s4, -16
	v_add_u32_e32 v145, v145, v143
	v_add_u32_e32 v146, s4, v156
	v_add_u32_e32 v148, s4, v145
	v_ashrrev_i32_e32 v147, 31, v146
	v_ashrrev_i32_e32 v149, 31, v148
	v_bitop3_b32 v160, s23, v199, v152 bitop3:0xc8
	v_lshlrev_b64 v[146:147], 12, v[146:147]
	v_lshlrev_b64 v[148:149], 12, v[148:149]
	v_mov_b64_e32 v[138:139], s[16:17]
	v_or_b32_e32 v158, v146, v160
	v_or_b32_e32 v160, v148, v160
	v_mad_u64_u32 v[140:141], s[10:11], v156, s73, v[140:141]
	v_mad_u64_u32 v[142:143], s[10:11], v145, s73, v[142:143]
	v_mad_u64_u32 v[158:159], s[10:11], v158, s35, v[138:139]
	v_ashrrev_i32_e32 v141, 31, v140
	v_ashrrev_i32_e32 v143, 31, v142
	v_lshlrev_b64 v[140:141], 1, v[140:141]
	v_lshlrev_b64 v[142:143], 1, v[142:143]
	v_mad_i32_i24 v159, v147, s35, v159
	v_lshl_add_u64 v[158:159], v[158:159], 0, v[140:141]
	s_addk_i32 s23, 0x80
	s_ashr_i32 s4, s23, 8
	s_and_b32 s4, s4, -16
	s_waitcnt vmcnt(0)
	v_fmamk_f32 v157, v240, 0x3b000000, v197
	v_mul_f32_e32 v161, 0x4f800000, v157
	v_cmp_gt_f32_e32 vcc, s36, v157
	s_nop 1
	v_cndmask_b32_e32 v157, v157, v161, vcc
	v_sqrt_f32_e32 v162, v157
	v_mad_u64_u32 v[160:161], s[10:11], v160, s35, v[138:139]
	v_mad_i32_i24 v161, v149, s35, v161
	v_add_u32_e32 v163, -1, v162
	v_add_u32_e32 v164, 1, v162
	v_fma_f32 v165, -v163, v162, v157
	v_fma_f32 v166, -v164, v162, v157
	v_cmp_ge_f32_e64 s[10:11], 0, v165
	v_lshl_add_u64 v[160:161], v[160:161], 0, v[142:143]
	s_nop 0
	v_cndmask_b32_e64 v162, v162, v163, s[10:11]
	v_cmp_lt_f32_e64 s[10:11], 0, v166
	s_nop 1
	v_cndmask_b32_e64 v162, v162, v164, s[10:11]
	v_mul_f32_e32 v163, 0x37800000, v162
	v_cndmask_b32_e32 v162, v162, v163, vcc
	v_cmp_class_f32_e32 vcc, v157, v198
	s_nop 1
	v_cndmask_b32_e32 v157, v162, v157, vcc
	v_div_scale_f32 v162, s[10:11], v157, v157, 1.0
	v_rcp_f32_e32 v163, v162
	v_div_scale_f32 v164, vcc, 1.0, v157, 1.0
	v_fma_f32 v165, -v162, v163, 1.0
	v_fmac_f32_e32 v163, v165, v163
	v_mul_f32_e32 v165, v164, v163
	v_fma_f32 v166, -v162, v165, v164
	v_fmac_f32_e32 v165, v166, v163
	v_fma_f32 v162, -v162, v165, v164
	v_div_fmas_f32 v162, v162, v163, v165
	v_div_fixup_f32 v162, v162, v157, 1.0
	v_pk_mul_f32 v[126:127], v[126:127], v[162:163] op_sel_hi:[1,0]
	v_pk_mul_f32 v[124:125], v[124:125], v[162:163] op_sel_hi:[1,0]
	v_pk_mul_f32 v[122:123], v[122:123], v[162:163] op_sel_hi:[1,0]
	v_pk_mul_f32 v[120:121], v[120:121], v[162:163] op_sel_hi:[1,0]
	v_pk_mul_f32 v[118:119], v[118:119], v[162:163] op_sel_hi:[1,0]
	v_pk_mul_f32 v[116:117], v[116:117], v[162:163] op_sel_hi:[1,0]
	v_pk_mul_f32 v[164:165], v[114:115], v[162:163] op_sel_hi:[1,0]
	v_pk_mul_f32 v[162:163], v[112:113], v[162:163] op_sel_hi:[1,0]
	v_cvt_pk_bf16_f32 v112, v124, v125
	v_cvt_pk_bf16_f32 v113, v126, v127
	v_cvt_pk_bf16_f32 v114, v120, v121
	v_cvt_pk_bf16_f32 v115, v122, v123
	global_store_dwordx4 v[158:159], v[112:115], off
	s_nop 1
	v_cvt_pk_bf16_f32 v112, v116, v117
	v_cvt_pk_bf16_f32 v113, v118, v119
	v_cvt_pk_bf16_f32 v114, v162, v163
	v_cvt_pk_bf16_f32 v115, v164, v165
	global_store_dwordx4 v[160:161], v[112:115], off
	s_nop 0
	v_bitop3_b32 v115, v144, s74, 16 bitop3:0xc8
	v_or_b32_e32 v112, v146, v115
	v_or_b32_e32 v115, v148, v115
	v_mad_u64_u32 v[112:113], s[10:11], v112, s35, v[138:139]
	v_mad_i32_i24 v113, v147, s35, v113
	v_lshl_add_u64 v[112:113], v[112:113], 0, v[140:141]
	v_fmamk_f32 v114, v241, 0x3b000000, v197
	v_mul_f32_e32 v116, 0x4f800000, v114
	v_cmp_gt_f32_e32 vcc, s36, v114
	s_nop 1
	v_cndmask_b32_e32 v116, v114, v116, vcc
	v_sqrt_f32_e32 v117, v116
	v_mad_u64_u32 v[114:115], s[10:11], v115, s35, v[138:139]
	v_mad_i32_i24 v115, v149, s35, v115
	v_add_u32_e32 v118, -1, v117
	v_add_u32_e32 v119, 1, v117
	v_fma_f32 v120, -v118, v117, v116
	v_fma_f32 v121, -v119, v117, v116
	v_cmp_ge_f32_e64 s[10:11], 0, v120
	v_lshl_add_u64 v[114:115], v[114:115], 0, v[142:143]
	s_nop 0
	v_cndmask_b32_e64 v117, v117, v118, s[10:11]
	v_cmp_lt_f32_e64 s[10:11], 0, v121
	s_nop 1
	v_cndmask_b32_e64 v117, v117, v119, s[10:11]
	v_mul_f32_e32 v118, 0x37800000, v117
	v_cndmask_b32_e32 v117, v117, v118, vcc
	v_cmp_class_f32_e32 vcc, v116, v198
	s_nop 1
	v_cndmask_b32_e32 v116, v117, v116, vcc
	v_div_scale_f32 v117, s[10:11], v116, v116, 1.0
	v_rcp_f32_e32 v118, v117
	v_div_scale_f32 v119, vcc, 1.0, v116, 1.0
	v_fma_f32 v120, -v117, v118, 1.0
	v_fmac_f32_e32 v118, v120, v118
	v_mul_f32_e32 v120, v119, v118
	v_fma_f32 v121, -v117, v120, v119
	v_fmac_f32_e32 v120, v121, v118
	v_fma_f32 v117, -v117, v120, v119
	v_div_fmas_f32 v117, v117, v118, v120
	v_div_fixup_f32 v116, v117, v116, 1.0
	v_pk_mul_f32 v[110:111], v[110:111], v[116:117] op_sel_hi:[1,0]
	v_pk_mul_f32 v[108:109], v[108:109], v[116:117] op_sel_hi:[1,0]
	v_pk_mul_f32 v[106:107], v[106:107], v[116:117] op_sel_hi:[1,0]
	v_pk_mul_f32 v[104:105], v[104:105], v[116:117] op_sel_hi:[1,0]
	v_pk_mul_f32 v[102:103], v[102:103], v[116:117] op_sel_hi:[1,0]
	v_pk_mul_f32 v[100:101], v[100:101], v[116:117] op_sel_hi:[1,0]
	v_pk_mul_f32 v[118:119], v[98:99], v[116:117] op_sel_hi:[1,0]
	v_pk_mul_f32 v[116:117], v[96:97], v[116:117] op_sel_hi:[1,0]
	v_cvt_pk_bf16_f32 v96, v108, v109
	v_cvt_pk_bf16_f32 v97, v110, v111
	v_cvt_pk_bf16_f32 v98, v104, v105
	v_cvt_pk_bf16_f32 v99, v106, v107
	global_store_dwordx4 v[112:113], v[96:99], off
	s_nop 1
	v_cvt_pk_bf16_f32 v96, v100, v101
	v_cvt_pk_bf16_f32 v97, v102, v103
	v_cvt_pk_bf16_f32 v98, v116, v117
	v_cvt_pk_bf16_f32 v99, v118, v119
	global_store_dwordx4 v[114:115], v[96:99], off
	s_nop 0
	v_bitop3_b32 v99, v144, s75, 32 bitop3:0xc8
	v_or_b32_e32 v96, v146, v99
	v_or_b32_e32 v99, v148, v99
	v_mad_u64_u32 v[96:97], s[10:11], v96, s35, v[138:139]
	v_mad_i32_i24 v97, v147, s35, v97
	v_lshl_add_u64 v[96:97], v[96:97], 0, v[140:141]
	v_fmamk_f32 v98, v242, 0x3b000000, v197
	v_mul_f32_e32 v100, 0x4f800000, v98
	v_cmp_gt_f32_e32 vcc, s36, v98
	s_nop 1
	v_cndmask_b32_e32 v100, v98, v100, vcc
	v_sqrt_f32_e32 v101, v100
	v_mad_u64_u32 v[98:99], s[10:11], v99, s35, v[138:139]
	v_mad_i32_i24 v99, v149, s35, v99
	v_add_u32_e32 v102, -1, v101
	v_add_u32_e32 v103, 1, v101
	v_fma_f32 v104, -v102, v101, v100
	v_fma_f32 v105, -v103, v101, v100
	v_cmp_ge_f32_e64 s[10:11], 0, v104
	v_lshl_add_u64 v[98:99], v[98:99], 0, v[142:143]
	s_nop 0
	v_cndmask_b32_e64 v101, v101, v102, s[10:11]
	v_cmp_lt_f32_e64 s[10:11], 0, v105
	s_nop 1
	v_cndmask_b32_e64 v101, v101, v103, s[10:11]
	v_mul_f32_e32 v102, 0x37800000, v101
	v_cndmask_b32_e32 v101, v101, v102, vcc
	v_cmp_class_f32_e32 vcc, v100, v198
	s_nop 1
	v_cndmask_b32_e32 v100, v101, v100, vcc
	v_div_scale_f32 v101, s[10:11], v100, v100, 1.0
	v_rcp_f32_e32 v102, v101
	v_div_scale_f32 v103, vcc, 1.0, v100, 1.0
	v_fma_f32 v104, -v101, v102, 1.0
	v_fmac_f32_e32 v102, v104, v102
	v_mul_f32_e32 v104, v103, v102
	v_fma_f32 v105, -v101, v104, v103
	v_fmac_f32_e32 v104, v105, v102
	v_fma_f32 v101, -v101, v104, v103
	v_div_fmas_f32 v101, v101, v102, v104
	v_div_fixup_f32 v100, v101, v100, 1.0
	v_pk_mul_f32 v[94:95], v[94:95], v[100:101] op_sel_hi:[1,0]
	v_pk_mul_f32 v[92:93], v[92:93], v[100:101] op_sel_hi:[1,0]
	v_pk_mul_f32 v[90:91], v[90:91], v[100:101] op_sel_hi:[1,0]
	v_pk_mul_f32 v[88:89], v[88:89], v[100:101] op_sel_hi:[1,0]
	v_pk_mul_f32 v[86:87], v[86:87], v[100:101] op_sel_hi:[1,0]
	v_pk_mul_f32 v[84:85], v[84:85], v[100:101] op_sel_hi:[1,0]
	v_pk_mul_f32 v[102:103], v[82:83], v[100:101] op_sel_hi:[1,0]
	v_pk_mul_f32 v[100:101], v[80:81], v[100:101] op_sel_hi:[1,0]
	v_cvt_pk_bf16_f32 v80, v92, v93
	v_cvt_pk_bf16_f32 v81, v94, v95
	v_cvt_pk_bf16_f32 v82, v88, v89
	v_cvt_pk_bf16_f32 v83, v90, v91
	global_store_dwordx4 v[96:97], v[80:83], off
	s_nop 1
	v_cvt_pk_bf16_f32 v80, v84, v85
	v_cvt_pk_bf16_f32 v81, v86, v87
	v_cvt_pk_bf16_f32 v82, v100, v101
	v_cvt_pk_bf16_f32 v83, v102, v103
	global_store_dwordx4 v[98:99], v[80:83], off
	v_bitop3_b32 v87, v144, s77, 48 bitop3:0xc8
	v_or_b32_e32 v80, s23, v152
	v_ashrrev_i32_e32 v81, 31, v80
	v_lshl_add_u64 v[82:83], v[80:81], 2, s[18:19]
	v_or_b32_e32 v81, v146, v87
	v_mad_u64_u32 v[84:85], s[10:11], v81, s35, v[138:139]
	v_or_b32_e32 v81, v148, v87
	v_mad_i32_i24 v85, v147, s35, v85
	v_lshl_add_u64 v[84:85], v[84:85], 0, v[140:141]
	v_fmamk_f32 v86, v243, 0x3b000000, v197
	v_mul_f32_e32 v87, 0x4f800000, v86
	v_cmp_gt_f32_e32 vcc, s36, v86
	s_nop 1
	v_cndmask_b32_e32 v88, v86, v87, vcc
	v_sqrt_f32_e32 v89, v88
	v_mad_u64_u32 v[86:87], s[10:11], v81, s35, v[138:139]
	v_mad_i32_i24 v87, v149, s35, v87
	v_add_u32_e32 v81, -1, v89
	v_add_u32_e32 v90, 1, v89
	v_fma_f32 v91, -v81, v89, v88
	v_fma_f32 v92, -v90, v89, v88
	v_cmp_ge_f32_e64 s[10:11], 0, v91
	v_lshl_add_u64 v[86:87], v[86:87], 0, v[142:143]
	s_nop 0
	v_cndmask_b32_e64 v81, v89, v81, s[10:11]
	v_cmp_lt_f32_e64 s[10:11], 0, v92
	s_nop 1
	v_cndmask_b32_e64 v81, v81, v90, s[10:11]
	v_mul_f32_e32 v89, 0x37800000, v81
	v_cndmask_b32_e32 v81, v81, v89, vcc
	v_cmp_class_f32_e32 vcc, v88, v198
	s_nop 1
	v_cndmask_b32_e32 v81, v81, v88, vcc
	v_div_scale_f32 v88, s[10:11], v81, v81, 1.0
	v_rcp_f32_e32 v89, v88
	v_div_scale_f32 v90, vcc, 1.0, v81, 1.0
	v_fma_f32 v91, -v88, v89, 1.0
	v_fmac_f32_e32 v89, v91, v89
	v_mul_f32_e32 v91, v90, v89
	v_fma_f32 v92, -v88, v91, v90
	v_fmac_f32_e32 v91, v92, v89
	v_fma_f32 v88, -v88, v91, v90
	v_div_fmas_f32 v88, v88, v89, v91
	v_div_fixup_f32 v88, v88, v81, 1.0
	v_pk_mul_f32 v[78:79], v[78:79], v[88:89] op_sel_hi:[1,0]
	v_pk_mul_f32 v[76:77], v[76:77], v[88:89] op_sel_hi:[1,0]
	v_pk_mul_f32 v[74:75], v[74:75], v[88:89] op_sel_hi:[1,0]
	v_pk_mul_f32 v[72:73], v[72:73], v[88:89] op_sel_hi:[1,0]
	v_pk_mul_f32 v[70:71], v[70:71], v[88:89] op_sel_hi:[1,0]
	v_pk_mul_f32 v[68:69], v[68:69], v[88:89] op_sel_hi:[1,0]
	v_pk_mul_f32 v[90:91], v[66:67], v[88:89] op_sel_hi:[1,0]
	v_pk_mul_f32 v[88:89], v[64:65], v[88:89] op_sel_hi:[1,0]
	v_cvt_pk_bf16_f32 v64, v76, v77
	v_cvt_pk_bf16_f32 v65, v78, v79
	v_cvt_pk_bf16_f32 v66, v72, v73
	v_cvt_pk_bf16_f32 v67, v74, v75
	global_store_dwordx4 v[84:85], v[64:67], off
	s_nop 1
	v_cvt_pk_bf16_f32 v64, v68, v69
	v_cvt_pk_bf16_f32 v65, v70, v71
	v_cvt_pk_bf16_f32 v66, v88, v89
	v_cvt_pk_bf16_f32 v67, v90, v91
	global_store_dwordx4 v[86:87], v[64:67], off
	global_load_dword v244, v[82:83], off
	global_load_dword v245, v[82:83], off offset:64
	global_load_dword v246, v[82:83], off offset:128
	global_load_dword v247, v[82:83], off offset:192
	v_add_u32_e32 v68, s4, v145
	v_add_u32_e32 v64, s4, v156
	v_ashrrev_i32_e32 v65, 31, v64
	v_ashrrev_i32_e32 v69, 31, v68
	v_bitop3_b32 v70, s23, v199, v152 bitop3:0xc8
	v_lshlrev_b64 v[66:67], 12, v[64:65]
	v_lshlrev_b64 v[64:65], 12, v[68:69]
	v_or_b32_e32 v68, v66, v70
	v_or_b32_e32 v70, v64, v70
	v_mad_u64_u32 v[68:69], s[10:11], v68, s35, v[138:139]
	v_mad_u64_u32 v[70:71], s[10:11], v70, s35, v[138:139]
	v_mad_i32_i24 v69, v67, s35, v69
	v_mad_i32_i24 v71, v65, s35, v71
	v_lshl_add_u64 v[68:69], v[68:69], 0, v[140:141]
	v_lshl_add_u64 v[70:71], v[70:71], 0, v[142:143]
	s_waitcnt vmcnt(0)
	v_fmamk_f32 v72, v244, 0x3b000000, v197
	v_mul_f32_e32 v73, 0x4f800000, v72
	v_cmp_gt_f32_e32 vcc, s36, v72
	s_nop 1
	v_cndmask_b32_e32 v72, v72, v73, vcc
	v_sqrt_f32_e32 v73, v72
	s_nop 0
	v_add_u32_e32 v74, -1, v73
	v_add_u32_e32 v75, 1, v73
	v_fma_f32 v76, -v74, v73, v72
	v_fma_f32 v77, -v75, v73, v72
	v_cmp_ge_f32_e64 s[10:11], 0, v76
	s_nop 1
	v_cndmask_b32_e64 v73, v73, v74, s[10:11]
	v_cmp_lt_f32_e64 s[10:11], 0, v77
	s_nop 1
	v_cndmask_b32_e64 v73, v73, v75, s[10:11]
	v_mul_f32_e32 v74, 0x37800000, v73
	v_cndmask_b32_e32 v73, v73, v74, vcc
	v_cmp_class_f32_e32 vcc, v72, v198
	s_nop 1
	v_cndmask_b32_e32 v72, v73, v72, vcc
	v_div_scale_f32 v73, s[10:11], v72, v72, 1.0
	v_rcp_f32_e32 v74, v73
	v_div_scale_f32 v75, vcc, 1.0, v72, 1.0
	v_fma_f32 v76, -v73, v74, 1.0
	v_fmac_f32_e32 v74, v76, v74
	v_mul_f32_e32 v76, v75, v74
	v_fma_f32 v77, -v73, v76, v75
	v_fmac_f32_e32 v76, v77, v74
	v_fma_f32 v73, -v73, v76, v75
	v_div_fmas_f32 v73, v73, v74, v76
	v_div_fixup_f32 v72, v73, v72, 1.0
	v_pk_mul_f32 v[62:63], v[62:63], v[72:73] op_sel_hi:[1,0]
	v_pk_mul_f32 v[60:61], v[60:61], v[72:73] op_sel_hi:[1,0]
	v_pk_mul_f32 v[58:59], v[58:59], v[72:73] op_sel_hi:[1,0]
	v_pk_mul_f32 v[56:57], v[56:57], v[72:73] op_sel_hi:[1,0]
	v_pk_mul_f32 v[54:55], v[54:55], v[72:73] op_sel_hi:[1,0]
	v_pk_mul_f32 v[52:53], v[52:53], v[72:73] op_sel_hi:[1,0]
	v_pk_mul_f32 v[74:75], v[50:51], v[72:73] op_sel_hi:[1,0]
	v_pk_mul_f32 v[72:73], v[48:49], v[72:73] op_sel_hi:[1,0]
	v_cvt_pk_bf16_f32 v48, v60, v61
	v_cvt_pk_bf16_f32 v49, v62, v63
	v_cvt_pk_bf16_f32 v50, v56, v57
	v_cvt_pk_bf16_f32 v51, v58, v59
	global_store_dwordx4 v[68:69], v[48:51], off
	s_nop 1
	v_cvt_pk_bf16_f32 v48, v52, v53
	v_cvt_pk_bf16_f32 v49, v54, v55
	v_cvt_pk_bf16_f32 v50, v72, v73
	v_cvt_pk_bf16_f32 v51, v74, v75
	global_store_dwordx4 v[70:71], v[48:51], off
	v_fmamk_f32 v52, v245, 0x3b000000, v197
	v_mul_f32_e32 v53, 0x4f800000, v52
	v_cmp_gt_f32_e32 vcc, s36, v52
	v_bitop3_b32 v48, v80, s74, 16 bitop3:0xc8
	v_or_b32_e32 v49, v66, v48
	v_cndmask_b32_e32 v52, v52, v53, vcc
	v_sqrt_f32_e32 v53, v52
	v_or_b32_e32 v50, v64, v48
	v_mad_u64_u32 v[48:49], s[10:11], v49, s35, v[138:139]
	v_add_u32_e32 v54, -1, v53
	v_mad_u64_u32 v[50:51], s[10:11], v50, s35, v[138:139]
	v_add_u32_e32 v55, 1, v53
	v_fma_f32 v56, -v54, v53, v52
	v_fma_f32 v57, -v55, v53, v52
	v_cmp_ge_f32_e64 s[10:11], 0, v56
	v_mad_i32_i24 v49, v67, s35, v49
	v_mad_i32_i24 v51, v65, s35, v51
	v_cndmask_b32_e64 v53, v53, v54, s[10:11]
	v_cmp_lt_f32_e64 s[10:11], 0, v57
	v_lshl_add_u64 v[48:49], v[48:49], 0, v[140:141]
	v_lshl_add_u64 v[50:51], v[50:51], 0, v[142:143]
	v_cndmask_b32_e64 v53, v53, v55, s[10:11]
	v_mul_f32_e32 v54, 0x37800000, v53
	v_cndmask_b32_e32 v53, v53, v54, vcc
	v_cmp_class_f32_e32 vcc, v52, v198
	s_nop 1
	v_cndmask_b32_e32 v52, v53, v52, vcc
	v_div_scale_f32 v53, s[10:11], v52, v52, 1.0
	v_rcp_f32_e32 v54, v53
	v_div_scale_f32 v55, vcc, 1.0, v52, 1.0
	v_fma_f32 v56, -v53, v54, 1.0
	v_fmac_f32_e32 v54, v56, v54
	v_mul_f32_e32 v56, v55, v54
	v_fma_f32 v57, -v53, v56, v55
	v_fmac_f32_e32 v56, v57, v54
	v_fma_f32 v53, -v53, v56, v55
	v_div_fmas_f32 v53, v53, v54, v56
	v_div_fixup_f32 v52, v53, v52, 1.0
	v_pk_mul_f32 v[46:47], v[46:47], v[52:53] op_sel_hi:[1,0]
	v_pk_mul_f32 v[44:45], v[44:45], v[52:53] op_sel_hi:[1,0]
	v_pk_mul_f32 v[42:43], v[42:43], v[52:53] op_sel_hi:[1,0]
	v_pk_mul_f32 v[40:41], v[40:41], v[52:53] op_sel_hi:[1,0]
	v_pk_mul_f32 v[38:39], v[38:39], v[52:53] op_sel_hi:[1,0]
	v_pk_mul_f32 v[36:37], v[36:37], v[52:53] op_sel_hi:[1,0]
	v_pk_mul_f32 v[54:55], v[34:35], v[52:53] op_sel_hi:[1,0]
	v_pk_mul_f32 v[52:53], v[32:33], v[52:53] op_sel_hi:[1,0]
	v_cvt_pk_bf16_f32 v32, v44, v45
	v_cvt_pk_bf16_f32 v33, v46, v47
	v_cvt_pk_bf16_f32 v34, v40, v41
	v_cvt_pk_bf16_f32 v35, v42, v43
	global_store_dwordx4 v[48:49], v[32:35], off
	s_nop 1
	v_cvt_pk_bf16_f32 v32, v36, v37
	v_cvt_pk_bf16_f32 v33, v38, v39
	v_cvt_pk_bf16_f32 v34, v52, v53
	v_cvt_pk_bf16_f32 v35, v54, v55
	global_store_dwordx4 v[50:51], v[32:35], off
	v_fmamk_f32 v36, v246, 0x3b000000, v197
	v_mul_f32_e32 v37, 0x4f800000, v36
	v_cmp_gt_f32_e32 vcc, s36, v36
	v_bitop3_b32 v32, v80, s75, 32 bitop3:0xc8
	v_or_b32_e32 v33, v66, v32
	v_cndmask_b32_e32 v36, v36, v37, vcc
	v_sqrt_f32_e32 v37, v36
	v_or_b32_e32 v34, v64, v32
	v_mad_u64_u32 v[32:33], s[10:11], v33, s35, v[138:139]
	v_add_u32_e32 v38, -1, v37
	v_mad_u64_u32 v[34:35], s[10:11], v34, s35, v[138:139]
	v_add_u32_e32 v39, 1, v37
	v_fma_f32 v40, -v38, v37, v36
	v_fma_f32 v41, -v39, v37, v36
	v_cmp_ge_f32_e64 s[10:11], 0, v40
	v_mad_i32_i24 v33, v67, s35, v33
	v_mad_i32_i24 v35, v65, s35, v35
	v_cndmask_b32_e64 v37, v37, v38, s[10:11]
	v_cmp_lt_f32_e64 s[10:11], 0, v41
	v_lshl_add_u64 v[32:33], v[32:33], 0, v[140:141]
	v_lshl_add_u64 v[34:35], v[34:35], 0, v[142:143]
	v_cndmask_b32_e64 v37, v37, v39, s[10:11]
	v_mul_f32_e32 v38, 0x37800000, v37
	v_cndmask_b32_e32 v37, v37, v38, vcc
	v_cmp_class_f32_e32 vcc, v36, v198
	s_nop 1
	v_cndmask_b32_e32 v36, v37, v36, vcc
	v_div_scale_f32 v37, s[10:11], v36, v36, 1.0
	v_rcp_f32_e32 v38, v37
	v_div_scale_f32 v39, vcc, 1.0, v36, 1.0
	v_fma_f32 v40, -v37, v38, 1.0
	v_fmac_f32_e32 v38, v40, v38
	v_mul_f32_e32 v40, v39, v38
	v_fma_f32 v41, -v37, v40, v39
	v_fmac_f32_e32 v40, v41, v38
	v_fma_f32 v37, -v37, v40, v39
	v_div_fmas_f32 v37, v37, v38, v40
	v_div_fixup_f32 v36, v37, v36, 1.0
	v_pk_mul_f32 v[30:31], v[30:31], v[36:37] op_sel_hi:[1,0]
	v_pk_mul_f32 v[28:29], v[28:29], v[36:37] op_sel_hi:[1,0]
	v_pk_mul_f32 v[26:27], v[26:27], v[36:37] op_sel_hi:[1,0]
	v_pk_mul_f32 v[24:25], v[24:25], v[36:37] op_sel_hi:[1,0]
	v_pk_mul_f32 v[22:23], v[22:23], v[36:37] op_sel_hi:[1,0]
	v_pk_mul_f32 v[20:21], v[20:21], v[36:37] op_sel_hi:[1,0]
	v_pk_mul_f32 v[38:39], v[18:19], v[36:37] op_sel_hi:[1,0]
	v_pk_mul_f32 v[36:37], v[16:17], v[36:37] op_sel_hi:[1,0]
	v_cvt_pk_bf16_f32 v16, v28, v29
	v_cvt_pk_bf16_f32 v17, v30, v31
	v_cvt_pk_bf16_f32 v18, v24, v25
	v_cvt_pk_bf16_f32 v19, v26, v27
	global_store_dwordx4 v[32:33], v[16:19], off
	s_nop 1
	v_cvt_pk_bf16_f32 v16, v20, v21
	v_cvt_pk_bf16_f32 v17, v22, v23
	v_cvt_pk_bf16_f32 v18, v36, v37
	v_cvt_pk_bf16_f32 v19, v38, v39
	global_store_dwordx4 v[34:35], v[16:19], off
	v_fmamk_f32 v20, v247, 0x3b000000, v197
	v_mul_f32_e32 v21, 0x4f800000, v20
	v_cmp_gt_f32_e32 vcc, s36, v20
	v_bitop3_b32 v16, v80, s77, 48 bitop3:0xc8
	v_or_b32_e32 v17, v66, v16
	v_cndmask_b32_e32 v20, v20, v21, vcc
	v_sqrt_f32_e32 v21, v20
	v_or_b32_e32 v18, v64, v16
	v_mad_u64_u32 v[16:17], s[10:11], v17, s35, v[138:139]
	v_add_u32_e32 v22, -1, v21
	v_mad_u64_u32 v[18:19], s[10:11], v18, s35, v[138:139]
	v_add_u32_e32 v23, 1, v21
	v_fma_f32 v24, -v22, v21, v20
	v_fma_f32 v25, -v23, v21, v20
	v_cmp_ge_f32_e64 s[10:11], 0, v24
	v_mad_i32_i24 v17, v67, s35, v17
	v_mad_i32_i24 v19, v65, s35, v19
	v_cndmask_b32_e64 v21, v21, v22, s[10:11]
	v_cmp_lt_f32_e64 s[10:11], 0, v25
	v_lshl_add_u64 v[16:17], v[16:17], 0, v[140:141]
	v_lshl_add_u64 v[18:19], v[18:19], 0, v[142:143]
	v_cndmask_b32_e64 v21, v21, v23, s[10:11]
	v_mul_f32_e32 v22, 0x37800000, v21
	v_cndmask_b32_e32 v21, v21, v22, vcc
	v_cmp_class_f32_e32 vcc, v20, v198
	s_nop 1
	v_cndmask_b32_e32 v20, v21, v20, vcc
	v_div_scale_f32 v21, s[10:11], v20, v20, 1.0
	v_rcp_f32_e32 v22, v21
	v_div_scale_f32 v23, vcc, 1.0, v20, 1.0
	v_fma_f32 v24, -v21, v22, 1.0
	v_fmac_f32_e32 v22, v24, v22
	v_mul_f32_e32 v24, v23, v22
	v_fma_f32 v25, -v21, v24, v23
	v_fmac_f32_e32 v24, v25, v22
	v_fma_f32 v21, -v21, v24, v23
	v_div_fmas_f32 v21, v21, v22, v24
	v_div_fixup_f32 v20, v21, v20, 1.0
	s_andn2_b64 vcc, exec, s[8:9]
	v_pk_mul_f32 v[14:15], v[14:15], v[20:21] op_sel_hi:[1,0]
	v_pk_mul_f32 v[12:13], v[12:13], v[20:21] op_sel_hi:[1,0]
	v_pk_mul_f32 v[10:11], v[10:11], v[20:21] op_sel_hi:[1,0]
	v_pk_mul_f32 v[8:9], v[8:9], v[20:21] op_sel_hi:[1,0]
	v_pk_mul_f32 v[6:7], v[6:7], v[20:21] op_sel_hi:[1,0]
	v_pk_mul_f32 v[4:5], v[4:5], v[20:21] op_sel_hi:[1,0]
	v_pk_mul_f32 v[22:23], v[2:3], v[20:21] op_sel_hi:[1,0]
	v_pk_mul_f32 v[20:21], v[0:1], v[20:21] op_sel_hi:[1,0]
	v_cvt_pk_bf16_f32 v0, v12, v13
	v_cvt_pk_bf16_f32 v1, v14, v15
	v_cvt_pk_bf16_f32 v2, v8, v9
	v_cvt_pk_bf16_f32 v3, v10, v11
	s_mov_b64 s[8:9], -1
	global_store_dwordx4 v[16:17], v[0:3], off
	s_nop 1
	v_cvt_pk_bf16_f32 v0, v4, v5
	v_cvt_pk_bf16_f32 v1, v6, v7
	v_cvt_pk_bf16_f32 v2, v20, v21
	v_cvt_pk_bf16_f32 v3, v22, v23
	global_store_dwordx4 v[18:19], v[0:3], off
	s_cbranch_vccnz .LBB0_666
	s_andn2_b64 vcc, exec, s[12:13]
	s_cbranch_vccnz .LBB0_665
	s_barrier
	s_branch .LBB0_665

.LBB0_735:
	s_or_b64 exec, exec, s[10:11]
	s_ashr_i32 s4, s39, 31
	v_lshrrev_b32_e32 v81, 3, v194
	v_or_b32_e32 v78, s39, v81
	v_mov_b32_e32 v79, s4
	v_and_b32_e32 v82, 56, v192
	v_lshlrev_b64 v[64:65], 12, v[78:79]
	v_add_u32_e32 v80, s48, v176
	v_lshl_add_u64 v[64:65], s[88:89], 0, v[64:65]
	v_lshlrev_b32_e32 v176, 1, v82
	s_waitcnt lgkmcnt(0)
	v_lshl_add_u64 v[64:65], v[64:65], 0, v[176:177]
	v_lshl_add_u32 v156, v78, 12, v176
	global_load_dwordx4 v[70:73], v[64:65], off nt
	v_add_u32_e32 v157, 0x8000, v156
	global_load_dwordx4 v[128:131], v157, s[88:89] nt
	v_add_u32_e32 v157, 0x10000, v156
	global_load_dwordx4 v[132:135], v157, s[88:89] nt
	v_add_u32_e32 v157, 0x18000, v156
	global_load_dwordx4 v[136:139], v157, s[88:89] nt
	global_load_dwordx4 v[140:143], v156, s[88:89] offset:128 nt
	v_add_u32_e32 v157, 0x8000, v156
	global_load_dwordx4 v[144:147], v157, s[88:89] offset:128 nt
	v_add_u32_e32 v157, 0x10000, v156
	global_load_dwordx4 v[148:151], v157, s[88:89] offset:128 nt
	v_add_u32_e32 v157, 0x18000, v156
	global_load_dwordx4 v[152:155], v157, s[88:89] offset:128 nt
	ds_read_b128 v[66:69], v80
	ds_read_b128 v[74:77], v80 offset:32
	s_lshl_b32 s4, s42, 13
	s_add_i32 s4, s4, 0
	v_lshlrev_b32_e32 v78, 10, v191
	s_waitcnt lgkmcnt(1)
	v_rcp_f32_e32 v83, v66
	v_rcp_f32_e32 v84, v67
	v_rcp_f32_e32 v85, v68
	v_rcp_f32_e32 v86, v69
	s_waitcnt lgkmcnt(0)
	v_rcp_f32_e32 v87, v74
	ds_read_b128 v[66:69], v80 offset:64
	v_rcp_f32_e32 v88, v75
	v_rcp_f32_e32 v89, v76
	v_rcp_f32_e32 v90, v77
	ds_read_b128 v[74:77], v80 offset:96
	v_lshlrev_b32_e32 v80, 2, v190
	v_add3_u32 v80, s4, v78, v80
	v_mul_f32_e32 v32, v32, v83
	v_mul_f32_e32 v48, v48, v83
	ds_write2_b32 v80, v32, v48 offset1:32
	v_mul_f32_e32 v32, v33, v84
	v_mul_f32_e32 v33, v49, v84
	ds_write2_b32 v80, v32, v33 offset0:64 offset1:96
	v_mul_f32_e32 v32, v34, v85
	v_mul_f32_e32 v33, v50, v85
	ds_write2_b32 v80, v32, v33 offset0:128 offset1:160
	v_mul_f32_e32 v32, v35, v86
	v_mul_f32_e32 v33, v51, v86
	s_waitcnt lgkmcnt(4)
	v_rcp_f32_e32 v66, v66
	ds_write2_b32 v80, v32, v33 offset0:192 offset1:224
	v_mul_f32_e32 v32, v36, v87
	v_mul_f32_e32 v33, v52, v87
	v_add_u32_e32 v92, 0x800, v80
	v_rcp_f32_e32 v67, v67
	ds_write2_b32 v92, v32, v33 offset1:32
	v_mul_f32_e32 v32, v37, v88
	v_mul_f32_e32 v33, v53, v88
	v_rcp_f32_e32 v68, v68
	ds_write2_b32 v92, v32, v33 offset0:64 offset1:96
	v_mul_f32_e32 v32, v38, v89
	v_mul_f32_e32 v33, v54, v89
	v_rcp_f32_e32 v69, v69
	ds_write2_b32 v92, v32, v33 offset0:128 offset1:160
	v_mul_f32_e32 v32, v39, v90
	v_mul_f32_e32 v33, v55, v90
	s_waitcnt lgkmcnt(7)
	v_rcp_f32_e32 v74, v74
	ds_write2_b32 v92, v32, v33 offset0:192 offset1:224
	v_mul_f32_e32 v32, v40, v66
	v_mul_f32_e32 v33, v56, v66
	v_add_u32_e32 v54, 0x1000, v80
	v_rcp_f32_e32 v75, v75
	ds_write2_b32 v54, v32, v33 offset1:32
	v_mul_f32_e32 v32, v41, v67
	v_mul_f32_e32 v33, v57, v67
	v_rcp_f32_e32 v76, v76
	ds_write2_b32 v54, v32, v33 offset0:64 offset1:96
	v_mul_f32_e32 v32, v42, v68
	v_mul_f32_e32 v33, v58, v68
	ds_write2_b32 v54, v32, v33 offset0:128 offset1:160
	v_mul_f32_e32 v32, v43, v69
	v_mul_f32_e32 v33, v59, v69
	ds_write2_b32 v54, v32, v33 offset0:192 offset1:224
	v_mul_f32_e32 v32, v44, v74
	v_mul_f32_e32 v33, v60, v74
	v_add_u32_e32 v55, 0x1800, v80
	v_lshl_add_u32 v82, v82, 2, s4
	ds_write2_b32 v55, v32, v33 offset1:32
	v_mul_f32_e32 v32, v45, v75
	v_mul_f32_e32 v33, v61, v75
	v_lshl_add_u32 v91, v81, 8, v82
	ds_write2_b32 v55, v32, v33 offset0:64 offset1:96
	v_mul_f32_e32 v32, v46, v76
	v_mul_f32_e32 v33, v62, v76
	v_rcp_f32_e32 v77, v77
	ds_write2_b32 v55, v32, v33 offset0:128 offset1:160
	ds_read_b128 v[32:35], v91
	v_or_b32_e32 v44, 8, v81
	v_mul_f32_e32 v36, v47, v77
	v_mul_f32_e32 v37, v63, v77
	s_waitcnt vmcnt(7)
	v_lshlrev_b32_e32 v40, 16, v70
	ds_write2_b32 v55, v36, v37 offset0:192 offset1:224
	ds_read_b128 v[36:39], v91 offset:16
	s_waitcnt lgkmcnt(2)
	v_mul_f32_e32 v32, v32, v40
	v_and_b32_e32 v40, 0xffff0000, v70
	v_mul_f32_e32 v33, v33, v40
	v_cvt_pk_bf16_f32 v40, v32, v33
	v_lshlrev_b32_e32 v32, 16, v71
	v_and_b32_e32 v33, 0xffff0000, v71
	v_mul_f32_e32 v32, v34, v32
	v_mul_f32_e32 v33, v35, v33
	v_cvt_pk_bf16_f32 v41, v32, v33
	v_lshlrev_b32_e32 v32, 16, v72
	v_and_b32_e32 v33, 0xffff0000, v72
	s_waitcnt lgkmcnt(0)
	v_mul_f32_e32 v32, v36, v32
	v_mul_f32_e32 v33, v37, v33
	v_cvt_pk_bf16_f32 v42, v32, v33
	v_lshlrev_b32_e32 v32, 16, v73
	v_and_b32_e32 v33, 0xffff0000, v73
	v_mul_f32_e32 v32, v38, v32
	v_mul_f32_e32 v33, v39, v33
	v_or_b32_e32 v78, s39, v44
	v_cvt_pk_bf16_f32 v43, v32, v33
	v_lshlrev_b64 v[32:33], 12, v[78:79]
	v_lshl_add_u64 v[32:33], s[88:89], 0, v[32:33]
	v_lshl_add_u64 v[34:35], v[32:33], 0, v[176:177]
	v_lshl_add_u32 v56, v44, 8, v82
	ds_read_b128 v[44:47], v56
	ds_read_b128 v[48:51], v56 offset:16
	v_or_b32_e32 v52, 16, v81
	v_or_b32_e32 v78, s39, v52
	v_lshlrev_b64 v[32:33], 12, v[78:79]
	v_lshl_add_u64 v[32:33], s[88:89], 0, v[32:33]
	global_store_dwordx4 v[64:65], v[40:43], off
	v_lshl_add_u64 v[32:33], v[32:33], 0, v[176:177]
	v_lshl_add_u32 v58, v52, 8, v82
	v_or_b32_e32 v57, 24, v81
	v_or_b32_e32 v78, s39, v57
	v_lshl_add_u32 v57, v57, 8, v82
	v_mul_f32_e32 v0, v0, v83
	v_mul_f32_e32 v16, v16, v83
	v_mul_f32_e32 v1, v1, v84
	v_mul_f32_e32 v17, v17, v84
	v_mul_f32_e32 v2, v2, v85
	v_mul_f32_e32 v18, v18, v85
	v_mul_f32_e32 v3, v3, v86
	v_mul_f32_e32 v19, v19, v86
	v_mul_f32_e32 v4, v4, v87
	v_mul_f32_e32 v20, v20, v87
	v_mul_f32_e32 v5, v5, v88
	v_mul_f32_e32 v21, v21, v88
	v_mul_f32_e32 v6, v6, v89
	v_mul_f32_e32 v22, v22, v89
	v_mul_f32_e32 v7, v7, v90
	v_mul_f32_e32 v23, v23, v90
	v_mul_f32_e32 v8, v8, v66
	v_mul_f32_e32 v24, v24, v66
	v_mul_f32_e32 v9, v9, v67
	v_mul_f32_e32 v25, v25, v67
	v_mul_f32_e32 v10, v10, v68
	v_mul_f32_e32 v26, v26, v68
	v_mul_f32_e32 v11, v11, v69
	v_mul_f32_e32 v27, v27, v69
	v_mul_f32_e32 v12, v12, v74
	v_mul_f32_e32 v28, v28, v74
	v_mul_f32_e32 v13, v13, v75
	v_mul_f32_e32 v29, v29, v75
	v_mul_f32_e32 v14, v14, v76
	v_mul_f32_e32 v30, v30, v76
	v_mul_f32_e32 v15, v15, v77
	v_mul_f32_e32 v31, v31, v77
	s_add_i32 s41, s41, 1
	s_cmp_eq_u32 s41, 4
	s_waitcnt vmcnt(7)
	v_mov_b64_e32 v[36:37], v[128:129]
	v_mov_b64_e32 v[38:39], v[130:131]
	v_lshlrev_b32_e32 v40, 16, v36
	v_and_b32_e32 v36, 0xffff0000, v36
	v_lshlrev_b32_e32 v41, 16, v37
	v_lshlrev_b32_e32 v42, 16, v38
	v_and_b32_e32 v38, 0xffff0000, v38
	v_lshlrev_b32_e32 v43, 16, v39
	v_and_b32_e32 v39, 0xffff0000, v39
	v_and_b32_e32 v37, 0xffff0000, v37
	s_waitcnt lgkmcnt(1)
	v_mul_f32_e32 v40, v44, v40
	v_mul_f32_e32 v36, v45, v36
	v_mul_f32_e32 v41, v46, v41
	s_waitcnt lgkmcnt(0)
	v_mul_f32_e32 v42, v48, v42
	v_mul_f32_e32 v44, v49, v38
	v_mul_f32_e32 v43, v50, v43
	v_mul_f32_e32 v45, v51, v39
	v_mul_f32_e32 v37, v47, v37
	v_cvt_pk_bf16_f32 v38, v40, v36
	v_cvt_pk_bf16_f32 v39, v41, v37
	v_cvt_pk_bf16_f32 v40, v42, v44
	v_cvt_pk_bf16_f32 v41, v43, v45
	ds_read_b128 v[46:49], v58
	ds_read_b128 v[50:53], v58 offset:16
	v_lshlrev_b64 v[36:37], 12, v[78:79]
	v_lshl_add_u64 v[36:37], s[88:89], 0, v[36:37]
	global_store_dwordx4 v[34:35], v[38:41], off
	v_lshl_add_u64 v[36:37], v[36:37], 0, v[176:177]
	s_waitcnt vmcnt(7)
	v_mov_b64_e32 v[42:43], v[132:133]
	v_mov_b64_e32 v[44:45], v[134:135]
	v_lshlrev_b32_e32 v38, 16, v42
	v_and_b32_e32 v39, 0xffff0000, v42
	v_lshlrev_b32_e32 v40, 16, v43
	v_and_b32_e32 v41, 0xffff0000, v43
	v_lshlrev_b32_e32 v42, 16, v44
	v_and_b32_e32 v43, 0xffff0000, v44
	v_lshlrev_b32_e32 v44, 16, v45
	v_and_b32_e32 v45, 0xffff0000, v45
	s_waitcnt lgkmcnt(1)
	v_mul_f32_e32 v38, v46, v38
	v_mul_f32_e32 v39, v47, v39
	v_mul_f32_e32 v40, v48, v40
	v_mul_f32_e32 v41, v49, v41
	s_waitcnt lgkmcnt(0)
	v_mul_f32_e32 v42, v50, v42
	v_mul_f32_e32 v43, v51, v43
	v_mul_f32_e32 v44, v52, v44
	v_mul_f32_e32 v45, v53, v45
	v_cvt_pk_bf16_f32 v38, v38, v39
	v_cvt_pk_bf16_f32 v39, v40, v41
	v_cvt_pk_bf16_f32 v40, v42, v43
	v_cvt_pk_bf16_f32 v41, v44, v45
	ds_read_b128 v[46:49], v57
	ds_read_b128 v[50:53], v57 offset:16
	global_store_dwordx4 v[32:33], v[38:41], off
	s_waitcnt vmcnt(7)
	v_mov_b64_e32 v[42:43], v[136:137]
	v_mov_b64_e32 v[44:45], v[138:139]
	s_nop 0
	v_lshlrev_b32_e32 v38, 16, v42
	v_and_b32_e32 v39, 0xffff0000, v42
	v_lshlrev_b32_e32 v40, 16, v43
	v_and_b32_e32 v41, 0xffff0000, v43
	v_lshlrev_b32_e32 v42, 16, v44
	v_and_b32_e32 v43, 0xffff0000, v44
	v_lshlrev_b32_e32 v44, 16, v45
	v_and_b32_e32 v45, 0xffff0000, v45
	s_waitcnt lgkmcnt(1)
	v_mul_f32_e32 v38, v46, v38
	v_mul_f32_e32 v39, v47, v39
	v_mul_f32_e32 v40, v48, v40
	v_mul_f32_e32 v41, v49, v41
	s_waitcnt lgkmcnt(0)
	v_mul_f32_e32 v42, v50, v42
	v_mul_f32_e32 v43, v51, v43
	v_mul_f32_e32 v44, v52, v44
	v_mul_f32_e32 v45, v53, v45
	v_cvt_pk_bf16_f32 v38, v38, v39
	v_cvt_pk_bf16_f32 v39, v40, v41
	v_cvt_pk_bf16_f32 v40, v42, v43
	v_cvt_pk_bf16_f32 v41, v44, v45
	ds_write2_b32 v80, v0, v16 offset1:32
	ds_write2_b32 v80, v1, v17 offset0:64 offset1:96
	ds_write2_b32 v80, v2, v18 offset0:128 offset1:160
	ds_write2_b32 v80, v3, v19 offset0:192 offset1:224
	ds_write2_b32 v92, v4, v20 offset1:32
	ds_write2_b32 v92, v5, v21 offset0:64 offset1:96
	ds_write2_b32 v92, v6, v22 offset0:128 offset1:160
	ds_write2_b32 v92, v7, v23 offset0:192 offset1:224
	ds_write2_b32 v54, v8, v24 offset1:32
	ds_write2_b32 v54, v9, v25 offset0:64 offset1:96
	ds_write2_b32 v54, v10, v26 offset0:128 offset1:160
	ds_write2_b32 v54, v11, v27 offset0:192 offset1:224
	ds_write2_b32 v55, v12, v28 offset1:32
	ds_write2_b32 v55, v13, v29 offset0:64 offset1:96
	ds_write2_b32 v55, v14, v30 offset0:128 offset1:160
	ds_write2_b32 v55, v15, v31 offset0:192 offset1:224
	global_store_dwordx4 v[36:37], v[38:41], off
	ds_read_b128 v[0:3], v91
	ds_read_b128 v[4:7], v91 offset:16
	s_waitcnt vmcnt(7)
	v_mov_b64_e32 v[42:43], v[140:141]
	v_mov_b64_e32 v[44:45], v[142:143]
	v_lshlrev_b32_e32 v8, 16, v42
	v_and_b32_e32 v9, 0xffff0000, v42
	v_lshlrev_b32_e32 v10, 16, v43
	v_and_b32_e32 v11, 0xffff0000, v43
	v_lshlrev_b32_e32 v12, 16, v44
	v_and_b32_e32 v13, 0xffff0000, v44
	v_lshlrev_b32_e32 v14, 16, v45
	v_and_b32_e32 v15, 0xffff0000, v45
	s_waitcnt lgkmcnt(1)
	v_mul_f32_e32 v0, v0, v8
	v_mul_f32_e32 v1, v1, v9
	v_mul_f32_e32 v2, v2, v10
	v_mul_f32_e32 v3, v3, v11
	s_waitcnt lgkmcnt(0)
	v_mul_f32_e32 v4, v4, v12
	v_mul_f32_e32 v5, v5, v13
	v_mul_f32_e32 v6, v6, v14
	v_mul_f32_e32 v7, v7, v15
	v_cvt_pk_bf16_f32 v0, v0, v1
	v_cvt_pk_bf16_f32 v1, v2, v3
	v_cvt_pk_bf16_f32 v2, v4, v5
	v_cvt_pk_bf16_f32 v3, v6, v7
	ds_read_b128 v[8:11], v56
	ds_read_b128 v[12:15], v56 offset:16
	global_store_dwordx4 v[64:65], v[0:3], off offset:128
	s_waitcnt vmcnt(7)
	v_mov_b64_e32 v[4:5], v[144:145]
	v_mov_b64_e32 v[6:7], v[146:147]
	s_nop 0
	v_lshlrev_b32_e32 v0, 16, v4
	v_and_b32_e32 v1, 0xffff0000, v4
	v_lshlrev_b32_e32 v2, 16, v5
	v_and_b32_e32 v3, 0xffff0000, v5
	v_lshlrev_b32_e32 v4, 16, v6
	v_and_b32_e32 v5, 0xffff0000, v6
	v_lshlrev_b32_e32 v6, 16, v7
	v_and_b32_e32 v7, 0xffff0000, v7
	s_waitcnt lgkmcnt(1)
	v_mul_f32_e32 v0, v8, v0
	v_mul_f32_e32 v1, v9, v1
	v_mul_f32_e32 v2, v10, v2
	v_mul_f32_e32 v3, v11, v3
	s_waitcnt lgkmcnt(0)
	v_mul_f32_e32 v4, v12, v4
	v_mul_f32_e32 v5, v13, v5
	v_mul_f32_e32 v6, v14, v6
	v_mul_f32_e32 v7, v15, v7
	v_cvt_pk_bf16_f32 v0, v0, v1
	v_cvt_pk_bf16_f32 v1, v2, v3
	v_cvt_pk_bf16_f32 v2, v4, v5
	v_cvt_pk_bf16_f32 v3, v6, v7
	ds_read_b128 v[8:11], v58
	ds_read_b128 v[12:15], v58 offset:16
	global_store_dwordx4 v[34:35], v[0:3], off offset:128
	s_waitcnt vmcnt(7)
	v_mov_b64_e32 v[4:5], v[148:149]
	v_mov_b64_e32 v[6:7], v[150:151]
	s_nop 0
	v_lshlrev_b32_e32 v0, 16, v4
	v_and_b32_e32 v1, 0xffff0000, v4
	v_lshlrev_b32_e32 v2, 16, v5
	v_and_b32_e32 v3, 0xffff0000, v5
	v_lshlrev_b32_e32 v4, 16, v6
	v_and_b32_e32 v5, 0xffff0000, v6
	v_lshlrev_b32_e32 v6, 16, v7
	v_and_b32_e32 v7, 0xffff0000, v7
	s_waitcnt lgkmcnt(1)
	v_mul_f32_e32 v0, v8, v0
	v_mul_f32_e32 v1, v9, v1
	v_mul_f32_e32 v2, v10, v2
	v_mul_f32_e32 v3, v11, v3
	s_waitcnt lgkmcnt(0)
	v_mul_f32_e32 v4, v12, v4
	v_mul_f32_e32 v5, v13, v5
	v_mul_f32_e32 v6, v14, v6
	v_mul_f32_e32 v7, v15, v7
	v_cvt_pk_bf16_f32 v0, v0, v1
	v_cvt_pk_bf16_f32 v1, v2, v3
	v_cvt_pk_bf16_f32 v2, v4, v5
	v_cvt_pk_bf16_f32 v3, v6, v7
	ds_read_b128 v[8:11], v57
	ds_read_b128 v[12:15], v57 offset:16
	global_store_dwordx4 v[32:33], v[0:3], off offset:128
	s_waitcnt vmcnt(7)
	v_mov_b64_e32 v[4:5], v[152:153]
	v_mov_b64_e32 v[6:7], v[154:155]
	s_nop 0
	v_lshlrev_b32_e32 v0, 16, v4
	v_and_b32_e32 v1, 0xffff0000, v4
	v_lshlrev_b32_e32 v2, 16, v5
	v_and_b32_e32 v3, 0xffff0000, v5
	v_lshlrev_b32_e32 v4, 16, v6
	v_and_b32_e32 v5, 0xffff0000, v6
	v_lshlrev_b32_e32 v6, 16, v7
	v_and_b32_e32 v7, 0xffff0000, v7
	s_waitcnt lgkmcnt(1)
	v_mul_f32_e32 v0, v8, v0
	v_mul_f32_e32 v1, v9, v1
	v_mul_f32_e32 v2, v10, v2
	v_mul_f32_e32 v3, v11, v3
	s_waitcnt lgkmcnt(0)
	v_mul_f32_e32 v4, v12, v4
	v_mul_f32_e32 v5, v13, v5
	v_mul_f32_e32 v6, v14, v6
	v_mul_f32_e32 v7, v15, v7
	v_cvt_pk_bf16_f32 v0, v0, v1
	v_cvt_pk_bf16_f32 v1, v2, v3
	v_cvt_pk_bf16_f32 v2, v4, v5
	v_cvt_pk_bf16_f32 v3, v6, v7
	global_store_dwordx4 v[36:37], v[0:3], off offset:128
	s_waitcnt lgkmcnt(0)
	s_barrier
	s_cbranch_scc1 .LBB0_733

.LBB0_858:
	v_lshl_add_u32 v140, s49, 8, v148
	v_lshl_or_b32 v138, s4, 8, v150
	v_ashrrev_i32_e32 v141, 31, v140
	v_ashrrev_i32_e32 v139, 31, v138
	v_lshlrev_b64 v[142:143], 11, v[140:141]
	v_lshl_add_u64 v[142:143], v[142:143], 0, v[138:139]
	v_lshl_add_u64 v[146:147], v[142:143], 1, s[16:17]
	v_lshlrev_b32_e32 v252, 1, v142
	global_load_dwordx4 v[152:155], v252, s[16:17] nt
	global_load_dwordx4 v[158:161], v252, s[16:17] offset:256 nt
	v_add_u32_e32 v253, 0x10000, v252
	global_load_dwordx4 v[162:165], v253, s[16:17] nt
	global_load_dwordx4 v[166:169], v253, s[16:17] offset:256 nt
	v_add_u32_e32 v253, 0x20000, v252
	global_load_dwordx4 v[170:173], v253, s[16:17] nt
	global_load_dwordx4 v[180:183], v253, s[16:17] offset:256 nt
	v_add_u32_e32 v253, 0x30000, v252
	global_load_dwordx4 v[184:187], v253, s[16:17] nt
	global_load_dwordx4 v[188:191], v253, s[16:17] offset:256 nt
	v_add_u32_e32 v253, 0x80000, v252
	global_load_dwordx4 v[200:203], v253, s[16:17] nt
	global_load_dwordx4 v[204:207], v253, s[16:17] offset:256 nt
	v_add_u32_e32 v253, 0x90000, v252
	global_load_dwordx4 v[208:211], v253, s[16:17] nt
	global_load_dwordx4 v[212:215], v253, s[16:17] offset:256 nt
	v_add_u32_e32 v253, 0xa0000, v252
	global_load_dwordx4 v[216:219], v253, s[16:17] nt
	global_load_dwordx4 v[240:243], v253, s[16:17] offset:256 nt
	v_add_u32_e32 v253, 0xb0000, v252
	global_load_dwordx4 v[244:247], v253, s[16:17] nt
	global_load_dwordx4 v[248:251], v253, s[16:17] offset:256 nt
	s_andn2_b64 vcc, exec, s[28:29]
	s_waitcnt vmcnt(0)
	v_lshlrev_b32_e32 v144, 16, v152
	v_and_b32_e32 v145, 0xffff0000, v152
	v_lshlrev_b32_e32 v152, 16, v153
	v_and_b32_e32 v153, 0xffff0000, v153
	v_pk_add_f32 v[124:125], v[124:125], v[144:145]
	v_lshlrev_b32_e32 v144, 16, v154
	v_and_b32_e32 v145, 0xffff0000, v154
	v_pk_add_f32 v[126:127], v[126:127], v[152:153]
	v_lshlrev_b32_e32 v152, 16, v155
	v_and_b32_e32 v153, 0xffff0000, v155
	v_pk_add_f32 v[120:121], v[120:121], v[144:145]
	v_cndmask_b32_e64 v144, 0, 1, s[28:29]
	v_pk_add_f32 v[122:123], v[122:123], v[152:153]
	v_cmp_ne_u32_e64 s[12:13], 1, v144
	v_lshl_add_u64 v[144:145], v[142:143], 2, s[18:19]
	s_cbranch_vccnz .LBB0_860
	global_store_dwordx4 v[144:145], v[124:127], off
	global_store_dwordx4 v[144:145], v[120:123], off offset:16

.LBB0_862:
	v_mov_b64_e32 v[120:121], v[158:159]
	v_mov_b64_e32 v[122:123], v[160:161]
	s_and_b64 vcc, exec, s[12:13]
	v_lshlrev_b32_e32 v124, 16, v120
	v_and_b32_e32 v125, 0xffff0000, v120
	v_lshlrev_b32_e32 v120, 16, v121
	v_and_b32_e32 v121, 0xffff0000, v121
	v_pk_add_f32 v[118:119], v[118:119], v[120:121]
	v_lshlrev_b32_e32 v120, 16, v122
	v_and_b32_e32 v121, 0xffff0000, v122
	v_lshlrev_b32_e32 v122, 16, v123
	v_and_b32_e32 v123, 0xffff0000, v123
	v_pk_add_f32 v[116:117], v[116:117], v[124:125]
	v_pk_add_f32 v[114:115], v[114:115], v[122:123]
	v_pk_add_f32 v[112:113], v[112:113], v[120:121]
	s_cbranch_vccnz .LBB0_864
	global_store_dwordx4 v[144:145], v[116:119], off offset:512
	global_store_dwordx4 v[144:145], v[112:115], off offset:528

.LBB0_868:
	v_or_b32_e32 v112, 16, v140
	v_ashrrev_i32_e32 v113, 31, v112
	v_lshlrev_b64 v[114:115], 11, v[112:113]
	v_lshl_add_u64 v[114:115], v[114:115], 0, v[138:139]
	v_lshl_add_u64 v[118:119], v[114:115], 1, s[16:17]
	v_mov_b64_e32 v[120:121], v[162:163]
	v_mov_b64_e32 v[122:123], v[164:165]
	s_and_b64 vcc, exec, s[12:13]
	v_lshlrev_b32_e32 v116, 16, v120
	v_and_b32_e32 v117, 0xffff0000, v120
	v_lshlrev_b32_e32 v120, 16, v121
	v_and_b32_e32 v121, 0xffff0000, v121
	v_pk_add_f32 v[110:111], v[110:111], v[120:121]
	v_pk_add_f32 v[108:109], v[108:109], v[116:117]
	v_lshlrev_b32_e32 v116, 16, v122
	v_and_b32_e32 v117, 0xffff0000, v122
	v_lshlrev_b32_e32 v120, 16, v123
	v_and_b32_e32 v121, 0xffff0000, v123
	v_pk_add_f32 v[106:107], v[106:107], v[120:121]
	v_pk_add_f32 v[104:105], v[104:105], v[116:117]
	v_lshl_add_u64 v[116:117], v[114:115], 2, s[18:19]
	s_cbranch_vccnz .LBB0_870
	global_store_dwordx4 v[116:117], v[108:111], off
	global_store_dwordx4 v[116:117], v[104:107], off offset:16

.LBB0_872:
	v_mov_b64_e32 v[104:105], v[166:167]
	v_mov_b64_e32 v[106:107], v[168:169]
	s_and_b64 vcc, exec, s[12:13]
	v_lshlrev_b32_e32 v108, 16, v104
	v_and_b32_e32 v109, 0xffff0000, v104
	v_lshlrev_b32_e32 v104, 16, v105
	v_and_b32_e32 v105, 0xffff0000, v105
	v_pk_add_f32 v[102:103], v[102:103], v[104:105]
	v_lshlrev_b32_e32 v104, 16, v106
	v_and_b32_e32 v105, 0xffff0000, v106
	v_lshlrev_b32_e32 v106, 16, v107
	v_and_b32_e32 v107, 0xffff0000, v107
	v_pk_add_f32 v[100:101], v[100:101], v[108:109]
	v_pk_add_f32 v[98:99], v[98:99], v[106:107]
	v_pk_add_f32 v[96:97], v[96:97], v[104:105]
	s_cbranch_vccnz .LBB0_874
	global_store_dwordx4 v[116:117], v[100:103], off offset:512
	global_store_dwordx4 v[116:117], v[96:99], off offset:528

.LBB0_878:
	v_or_b32_e32 v96, 32, v140
	v_ashrrev_i32_e32 v97, 31, v96
	v_lshlrev_b64 v[98:99], 11, v[96:97]
	v_lshl_add_u64 v[98:99], v[98:99], 0, v[138:139]
	v_lshl_add_u64 v[102:103], v[98:99], 1, s[16:17]
	v_mov_b64_e32 v[104:105], v[170:171]
	v_mov_b64_e32 v[106:107], v[172:173]
	s_and_b64 vcc, exec, s[12:13]
	v_lshlrev_b32_e32 v100, 16, v104
	v_and_b32_e32 v101, 0xffff0000, v104
	v_lshlrev_b32_e32 v104, 16, v105
	v_and_b32_e32 v105, 0xffff0000, v105
	v_pk_add_f32 v[94:95], v[94:95], v[104:105]
	v_pk_add_f32 v[92:93], v[92:93], v[100:101]
	v_lshlrev_b32_e32 v100, 16, v106
	v_and_b32_e32 v101, 0xffff0000, v106
	v_lshlrev_b32_e32 v104, 16, v107
	v_and_b32_e32 v105, 0xffff0000, v107
	v_pk_add_f32 v[90:91], v[90:91], v[104:105]
	v_pk_add_f32 v[88:89], v[88:89], v[100:101]
	v_lshl_add_u64 v[100:101], v[98:99], 2, s[18:19]
	s_cbranch_vccnz .LBB0_880
	global_store_dwordx4 v[100:101], v[92:95], off
	global_store_dwordx4 v[100:101], v[88:91], off offset:16

.LBB0_882:
	v_mov_b64_e32 v[88:89], v[180:181]
	v_mov_b64_e32 v[90:91], v[182:183]
	s_and_b64 vcc, exec, s[12:13]
	v_lshlrev_b32_e32 v92, 16, v88
	v_and_b32_e32 v93, 0xffff0000, v88
	v_lshlrev_b32_e32 v88, 16, v89
	v_and_b32_e32 v89, 0xffff0000, v89
	v_pk_add_f32 v[86:87], v[86:87], v[88:89]
	v_lshlrev_b32_e32 v88, 16, v90
	v_and_b32_e32 v89, 0xffff0000, v90
	v_lshlrev_b32_e32 v90, 16, v91
	v_and_b32_e32 v91, 0xffff0000, v91
	v_pk_add_f32 v[84:85], v[84:85], v[92:93]
	v_pk_add_f32 v[82:83], v[82:83], v[90:91]
	v_pk_add_f32 v[80:81], v[80:81], v[88:89]
	s_cbranch_vccnz .LBB0_884
	global_store_dwordx4 v[100:101], v[84:87], off offset:512
	global_store_dwordx4 v[100:101], v[80:83], off offset:528

.LBB0_888:
	v_or_b32_e32 v80, 48, v140
	v_ashrrev_i32_e32 v81, 31, v80
	v_lshlrev_b64 v[82:83], 11, v[80:81]
	v_lshl_add_u64 v[82:83], v[82:83], 0, v[138:139]
	v_lshl_add_u64 v[86:87], v[82:83], 1, s[16:17]
	v_mov_b64_e32 v[88:89], v[184:185]
	v_mov_b64_e32 v[90:91], v[186:187]
	s_and_b64 vcc, exec, s[12:13]
	v_lshlrev_b32_e32 v84, 16, v88
	v_and_b32_e32 v85, 0xffff0000, v88
	v_lshlrev_b32_e32 v88, 16, v89
	v_and_b32_e32 v89, 0xffff0000, v89
	v_pk_add_f32 v[78:79], v[78:79], v[88:89]
	v_pk_add_f32 v[76:77], v[76:77], v[84:85]
	v_lshlrev_b32_e32 v84, 16, v90
	v_and_b32_e32 v85, 0xffff0000, v90
	v_lshlrev_b32_e32 v88, 16, v91
	v_and_b32_e32 v89, 0xffff0000, v91
	v_pk_add_f32 v[74:75], v[74:75], v[88:89]
	v_pk_add_f32 v[72:73], v[72:73], v[84:85]
	v_lshl_add_u64 v[84:85], v[82:83], 2, s[18:19]
	s_cbranch_vccnz .LBB0_890
	global_store_dwordx4 v[84:85], v[76:79], off
	global_store_dwordx4 v[84:85], v[72:75], off offset:16

.LBB0_892:
	v_mov_b64_e32 v[72:73], v[188:189]
	v_mov_b64_e32 v[74:75], v[190:191]
	s_and_b64 vcc, exec, s[12:13]
	v_lshlrev_b32_e32 v76, 16, v72
	v_and_b32_e32 v77, 0xffff0000, v72
	v_lshlrev_b32_e32 v72, 16, v73
	v_and_b32_e32 v73, 0xffff0000, v73
	v_pk_add_f32 v[70:71], v[70:71], v[72:73]
	v_lshlrev_b32_e32 v72, 16, v74
	v_and_b32_e32 v73, 0xffff0000, v74
	v_lshlrev_b32_e32 v74, 16, v75
	v_and_b32_e32 v75, 0xffff0000, v75
	v_pk_add_f32 v[68:69], v[68:69], v[76:77]
	v_pk_add_f32 v[66:67], v[66:67], v[74:75]
	v_pk_add_f32 v[64:65], v[64:65], v[72:73]
	s_cbranch_vccnz .LBB0_894
	global_store_dwordx4 v[84:85], v[68:71], off offset:512
	global_store_dwordx4 v[84:85], v[64:67], off offset:528

.LBB0_898:
	v_add_u32_e32 v64, 0x80, v140
	v_ashrrev_i32_e32 v65, 31, v64
	v_lshlrev_b64 v[66:67], 11, v[64:65]
	v_lshl_add_u64 v[66:67], v[66:67], 0, v[138:139]
	v_lshl_add_u64 v[70:71], v[66:67], 1, s[16:17]
	v_mov_b64_e32 v[72:73], v[200:201]
	v_mov_b64_e32 v[74:75], v[202:203]
	s_and_b64 vcc, exec, s[12:13]
	v_lshlrev_b32_e32 v68, 16, v72
	v_and_b32_e32 v69, 0xffff0000, v72
	v_lshlrev_b32_e32 v72, 16, v73
	v_and_b32_e32 v73, 0xffff0000, v73
	v_pk_add_f32 v[62:63], v[62:63], v[72:73]
	v_pk_add_f32 v[60:61], v[60:61], v[68:69]
	v_lshlrev_b32_e32 v68, 16, v74
	v_and_b32_e32 v69, 0xffff0000, v74
	v_lshlrev_b32_e32 v72, 16, v75
	v_and_b32_e32 v73, 0xffff0000, v75
	v_pk_add_f32 v[58:59], v[58:59], v[72:73]
	v_pk_add_f32 v[56:57], v[56:57], v[68:69]
	v_lshl_add_u64 v[68:69], v[66:67], 2, s[18:19]
	s_cbranch_vccnz .LBB0_900
	global_store_dwordx4 v[68:69], v[60:63], off
	global_store_dwordx4 v[68:69], v[56:59], off offset:16

.LBB0_902:
	v_mov_b64_e32 v[56:57], v[204:205]
	v_mov_b64_e32 v[58:59], v[206:207]
	s_and_b64 vcc, exec, s[12:13]
	v_lshlrev_b32_e32 v60, 16, v56
	v_and_b32_e32 v61, 0xffff0000, v56
	v_lshlrev_b32_e32 v56, 16, v57
	v_and_b32_e32 v57, 0xffff0000, v57
	v_pk_add_f32 v[54:55], v[54:55], v[56:57]
	v_lshlrev_b32_e32 v56, 16, v58
	v_and_b32_e32 v57, 0xffff0000, v58
	v_lshlrev_b32_e32 v58, 16, v59
	v_and_b32_e32 v59, 0xffff0000, v59
	v_pk_add_f32 v[52:53], v[52:53], v[60:61]
	v_pk_add_f32 v[50:51], v[50:51], v[58:59]
	v_pk_add_f32 v[48:49], v[48:49], v[56:57]
	s_cbranch_vccnz .LBB0_904
	global_store_dwordx4 v[68:69], v[52:55], off offset:512
	global_store_dwordx4 v[68:69], v[48:51], off offset:528

.LBB0_908:
	v_add_u32_e32 v48, 0x90, v140
	v_ashrrev_i32_e32 v49, 31, v48
	v_lshlrev_b64 v[50:51], 11, v[48:49]
	v_lshl_add_u64 v[50:51], v[50:51], 0, v[138:139]
	v_lshl_add_u64 v[54:55], v[50:51], 1, s[16:17]
	v_mov_b64_e32 v[56:57], v[208:209]
	v_mov_b64_e32 v[58:59], v[210:211]
	s_and_b64 vcc, exec, s[12:13]
	v_lshlrev_b32_e32 v52, 16, v56
	v_and_b32_e32 v53, 0xffff0000, v56
	v_lshlrev_b32_e32 v56, 16, v57
	v_and_b32_e32 v57, 0xffff0000, v57
	v_pk_add_f32 v[46:47], v[46:47], v[56:57]
	v_pk_add_f32 v[44:45], v[44:45], v[52:53]
	v_lshlrev_b32_e32 v52, 16, v58
	v_and_b32_e32 v53, 0xffff0000, v58
	v_lshlrev_b32_e32 v56, 16, v59
	v_and_b32_e32 v57, 0xffff0000, v59
	v_pk_add_f32 v[42:43], v[42:43], v[56:57]
	v_pk_add_f32 v[40:41], v[40:41], v[52:53]
	v_lshl_add_u64 v[52:53], v[50:51], 2, s[18:19]
	s_cbranch_vccnz .LBB0_910
	global_store_dwordx4 v[52:53], v[44:47], off
	global_store_dwordx4 v[52:53], v[40:43], off offset:16

.LBB0_912:
	v_mov_b64_e32 v[40:41], v[212:213]
	v_mov_b64_e32 v[42:43], v[214:215]
	s_and_b64 vcc, exec, s[12:13]
	v_lshlrev_b32_e32 v44, 16, v40
	v_and_b32_e32 v45, 0xffff0000, v40
	v_lshlrev_b32_e32 v40, 16, v41
	v_and_b32_e32 v41, 0xffff0000, v41
	v_pk_add_f32 v[38:39], v[38:39], v[40:41]
	v_lshlrev_b32_e32 v40, 16, v42
	v_and_b32_e32 v41, 0xffff0000, v42
	v_lshlrev_b32_e32 v42, 16, v43
	v_and_b32_e32 v43, 0xffff0000, v43
	v_pk_add_f32 v[36:37], v[36:37], v[44:45]
	v_pk_add_f32 v[34:35], v[34:35], v[42:43]
	v_pk_add_f32 v[32:33], v[32:33], v[40:41]
	s_cbranch_vccnz .LBB0_914
	global_store_dwordx4 v[52:53], v[36:39], off offset:512
	global_store_dwordx4 v[52:53], v[32:35], off offset:528

.LBB0_918:
	v_add_u32_e32 v32, 0xa0, v140
	v_ashrrev_i32_e32 v33, 31, v32
	v_lshlrev_b64 v[34:35], 11, v[32:33]
	v_lshl_add_u64 v[34:35], v[34:35], 0, v[138:139]
	v_lshl_add_u64 v[38:39], v[34:35], 1, s[16:17]
	v_mov_b64_e32 v[40:41], v[216:217]
	v_mov_b64_e32 v[42:43], v[218:219]
	s_and_b64 vcc, exec, s[12:13]
	v_lshlrev_b32_e32 v36, 16, v40
	v_and_b32_e32 v37, 0xffff0000, v40
	v_lshlrev_b32_e32 v40, 16, v41
	v_and_b32_e32 v41, 0xffff0000, v41
	v_pk_add_f32 v[30:31], v[30:31], v[40:41]
	v_pk_add_f32 v[28:29], v[28:29], v[36:37]
	v_lshlrev_b32_e32 v36, 16, v42
	v_and_b32_e32 v37, 0xffff0000, v42
	v_lshlrev_b32_e32 v40, 16, v43
	v_and_b32_e32 v41, 0xffff0000, v43
	v_pk_add_f32 v[26:27], v[26:27], v[40:41]
	v_pk_add_f32 v[24:25], v[24:25], v[36:37]
	v_lshl_add_u64 v[36:37], v[34:35], 2, s[18:19]
	s_cbranch_vccnz .LBB0_920
	global_store_dwordx4 v[36:37], v[28:31], off
	global_store_dwordx4 v[36:37], v[24:27], off offset:16

.LBB0_922:
	v_mov_b64_e32 v[24:25], v[240:241]
	v_mov_b64_e32 v[26:27], v[242:243]
	s_and_b64 vcc, exec, s[12:13]
	v_lshlrev_b32_e32 v28, 16, v24
	v_and_b32_e32 v29, 0xffff0000, v24
	v_lshlrev_b32_e32 v24, 16, v25
	v_and_b32_e32 v25, 0xffff0000, v25
	v_pk_add_f32 v[22:23], v[22:23], v[24:25]
	v_lshlrev_b32_e32 v24, 16, v26
	v_and_b32_e32 v25, 0xffff0000, v26
	v_lshlrev_b32_e32 v26, 16, v27
	v_and_b32_e32 v27, 0xffff0000, v27
	v_pk_add_f32 v[20:21], v[20:21], v[28:29]
	v_pk_add_f32 v[18:19], v[18:19], v[26:27]
	v_pk_add_f32 v[16:17], v[16:17], v[24:25]
	s_cbranch_vccnz .LBB0_924
	global_store_dwordx4 v[36:37], v[20:23], off offset:512
	global_store_dwordx4 v[36:37], v[16:19], off offset:528

.LBB0_928:
	v_add_u32_e32 v16, 0xb0, v140
	v_ashrrev_i32_e32 v17, 31, v16
	v_lshlrev_b64 v[18:19], 11, v[16:17]
	v_lshl_add_u64 v[18:19], v[18:19], 0, v[138:139]
	v_lshl_add_u64 v[22:23], v[18:19], 1, s[16:17]
	v_mov_b64_e32 v[24:25], v[244:245]
	v_mov_b64_e32 v[26:27], v[246:247]
	s_and_b64 vcc, exec, s[12:13]
	v_lshlrev_b32_e32 v20, 16, v24
	v_and_b32_e32 v21, 0xffff0000, v24
	v_lshlrev_b32_e32 v24, 16, v25
	v_and_b32_e32 v25, 0xffff0000, v25
	v_pk_add_f32 v[14:15], v[14:15], v[24:25]
	v_pk_add_f32 v[12:13], v[12:13], v[20:21]
	v_lshlrev_b32_e32 v20, 16, v26
	v_and_b32_e32 v21, 0xffff0000, v26
	v_lshlrev_b32_e32 v24, 16, v27
	v_and_b32_e32 v25, 0xffff0000, v27
	v_pk_add_f32 v[10:11], v[10:11], v[24:25]
	v_pk_add_f32 v[8:9], v[8:9], v[20:21]
	v_lshl_add_u64 v[20:21], v[18:19], 2, s[18:19]
	s_cbranch_vccnz .LBB0_930
	global_store_dwordx4 v[20:21], v[12:15], off
	global_store_dwordx4 v[20:21], v[8:11], off offset:16

.LBB0_932:
	v_mov_b64_e32 v[8:9], v[248:249]
	v_mov_b64_e32 v[10:11], v[250:251]
	s_and_b64 vcc, exec, s[12:13]
	v_lshlrev_b32_e32 v12, 16, v8
	v_and_b32_e32 v13, 0xffff0000, v8
	v_lshlrev_b32_e32 v8, 16, v9
	v_and_b32_e32 v9, 0xffff0000, v9
	v_pk_add_f32 v[6:7], v[6:7], v[8:9]
	v_lshlrev_b32_e32 v8, 16, v10
	v_and_b32_e32 v9, 0xffff0000, v10
	v_lshlrev_b32_e32 v10, 16, v11
	v_and_b32_e32 v11, 0xffff0000, v11
	v_pk_add_f32 v[4:5], v[4:5], v[12:13]
	v_pk_add_f32 v[2:3], v[2:3], v[10:11]
	v_pk_add_f32 v[0:1], v[0:1], v[8:9]
	s_cbranch_vccnz .LBB0_934
	global_store_dwordx4 v[20:21], v[4:7], off offset:512
	global_store_dwordx4 v[20:21], v[0:3], off offset:528
